# v50 + LDS base constants folded into the fragment-address adds as literals, SGPR constant setup sunk below the reads (ph1/ph3 heads shortened)
# speedup vs baseline: 1.0065x; 1.0065x over previous
; #define PG8_STAGE(bufoff, gbase, voff) do { _Pragma("unroll") for (int _i = 0; _i < 2; ++_i) \
;         __builtin_amdgcn_global_load_lds((const unsigned*)((const char*)(gbase) + (voff)[_i]), (PG8_LAS unsigned*)(lds + (bufoff) + ldsw + _i * (8 * USTR)), 16, 0, 0); } while (0)
; #define PG8_LDA(dst, b, h) do { _Pragma("unroll") for (int m = 0; m < 4; ++m) _Pragma("unroll") for (int k = 0; k < 2; ++k) dst[m][k] = *(const PG8_LAS bf16x8*)(lds + PG8_SA(b, h) + aoff + m * (2 * USTR) + k * 64); } while (0)
; #define PG8_LDB(dst, b, h) do { _Pragma("unroll") for (int n = 0; n < 2; ++n) _Pragma("unroll") for (int k = 0; k < 2; ++k) dst[n][k] = *(const PG8_LAS bf16x8*)(lds + PG8_SB(b, h) + boff + n * (2 * USTR) + k * 64); } while (0)
; #define PG8_MMA(ai, bj, At, Bt) do { __builtin_amdgcn_s_setprio(1); _Pragma("unroll") for (int m = 0; m < 4; ++m) _Pragma("unroll") for (int n = 0; n < 2; ++n) _Pragma("unroll") for (int k = 0; k < 2; ++k) \
;         acc[ai][bj][m][n] = __builtin_amdgcn_mfma_f32_16x16x32_bf16(Bt[n][k], At[m][k], acc[ai][bj][m][n], 0, 0, 0); __builtin_amdgcn_s_setprio(0); } while (0)
; #define PG8_WAIT_V(n) asm volatile("s_waitcnt vmcnt(" #n ")" ::: "memory")
; #define PG8_WAIT_L(n) asm volatile("s_waitcnt lgkmcnt(" #n ")" ::: "memory")
; #define PG8_BAR __builtin_amdgcn_s_barrier()
; #define PG8_SCHED __builtin_amdgcn_sched_barrier(0)
; template <class Epi, class Sched, bool ALIGN_EPI, bool SP2>
; __device__ __forceinline__ void gemm_phase(PG8_LAS unsigned char* lds, const Gemm g, const Sched& S, const Epi& E, int wid) {
;     ...
;             if constexpr (SP2) {
;             PG8_LDB(B0, 0, 0); PG8_LDB(B1, 0, 1); PG8_SCHED; PG8_LDA(At, 0, 0); PG8_STAGE(PG8_SA(1, 1), a1 + hstepA, voffA);
;             PG8_WAIT_V(8); PG8_WAIT_L(0); PG8_BAR; PG8_MMA(0, 0, At, B0); PG8_MMA(0, 1, At, B1); PG8_BAR; PG8_SCHED;
;             PG8_LDA(At, 0, 1); PG8_STAGE(PG8_SB(0, 0), b2, voffB); PG8_STAGE(PG8_SB(0, 1), b2 + hstepB, voffB); PG8_STAGE(PG8_SA(0, 0), a2, voffA);
;             PG8_WAIT_V(8); PG8_WAIT_L(0); PG8_BAR; PG8_MMA(1, 0, At, B0); PG8_MMA(1, 1, At, B1); PG8_BAR; PG8_SCHED;
.Lhb_mixout:
	v_add_u32_e32 v60, 0x11000, v216
	v_add_u32_e32 v156, 0x15400, v216
	ds_read_b128 v[48:51], v60
	ds_read_b128 v[52:55], v60 offset:64
	ds_read_b128 v[56:59], v60 offset:2176
	ds_read_b128 v[60:63], v60 offset:2240
	ds_read_b128 v[144:147], v156
	ds_read_b128 v[148:151], v156 offset:64
	ds_read_b128 v[152:155], v156 offset:2176
	ds_read_b128 v[156:159], v156 offset:2240
	s_add_i32 s95, 0, 0x11000
	s_add_i32 s44, 0, 0x15400
	v_lshl_add_u64 v[198:199], s[38:39], 0, v[168:169]
	s_add_i32 m0, s0, 0xcc00
	ds_read_b128 v[172:175], v217
	ds_read_b128 v[176:179], v217 offset:64
	ds_read_b128 v[180:183], v217 offset:2176
	ds_read_b128 v[184:187], v217 offset:2240
	ds_read_b128 v[188:191], v217 offset:4352
	ds_read_b128 v[208:211], v217 offset:4416
	ds_read_b128 v[212:215], v217 offset:6528
	ds_read_b128 v[218:221], v217 offset:6592
	global_load_lds_dwordx4 v[198:199], off
	v_lshl_add_u64 v[198:199], s[38:39], 0, v[170:171]
	s_add_i32 m0, s0, 0xee00
	s_nop 0
	global_load_lds_dwordx4 v[198:199], off
	s_add_u32 s40, s38, 0xfff80080
	s_addc_u32 s41, s39, -1
	s_cmp_eq_u32 s89, 12
	s_cselect_b32 s75, s26, s41
	s_cselect_b32 s74, s27, s40
	s_cselect_b32 s41, s23, s79
	s_cselect_b32 s40, s69, s78
	s_waitcnt vmcnt(8)
	s_waitcnt lgkmcnt(0)
	s_barrier
	s_setprio 1
	s_waitcnt lgkmcnt(0)
	v_mfma_f32_16x16x32_bf16 v[140:143], v[48:51], v[172:175], 0
	v_mfma_f32_16x16x32_bf16 v[136:139], v[56:59], v[172:175], 0
	v_mfma_f32_16x16x32_bf16 v[124:127], v[48:51], v[180:183], 0
	v_mfma_f32_16x16x32_bf16 v[120:123], v[56:59], v[180:183], 0
	v_mfma_f32_16x16x32_bf16 v[108:111], v[48:51], v[188:191], 0
	v_mfma_f32_16x16x32_bf16 v[104:107], v[56:59], v[188:191], 0
	v_mfma_f32_16x16x32_bf16 v[92:95], v[48:51], v[212:215], 0
	v_mfma_f32_16x16x32_bf16 v[88:91], v[56:59], v[212:215], 0
	v_mfma_f32_16x16x32_bf16 v[140:143], v[52:55], v[176:179], v[140:143]
	v_mfma_f32_16x16x32_bf16 v[136:139], v[60:63], v[176:179], v[136:139]
	v_mfma_f32_16x16x32_bf16 v[124:127], v[52:55], v[184:187], v[124:127]
	v_mfma_f32_16x16x32_bf16 v[120:123], v[60:63], v[184:187], v[120:123]
	v_mfma_f32_16x16x32_bf16 v[108:111], v[52:55], v[208:211], v[108:111]
	v_mfma_f32_16x16x32_bf16 v[104:107], v[60:63], v[208:211], v[104:107]
	v_mfma_f32_16x16x32_bf16 v[92:95], v[52:55], v[218:221], v[92:95]
	v_mfma_f32_16x16x32_bf16 v[88:91], v[60:63], v[218:221], v[88:91]
	s_setprio 0
	s_setprio 1
	v_mfma_f32_16x16x32_bf16 v[132:135], v[144:147], v[172:175], 0
	v_mfma_f32_16x16x32_bf16 v[128:131], v[152:155], v[172:175], 0
	v_mfma_f32_16x16x32_bf16 v[116:119], v[144:147], v[180:183], 0
	v_mfma_f32_16x16x32_bf16 v[112:115], v[152:155], v[180:183], 0
	v_mfma_f32_16x16x32_bf16 v[100:103], v[144:147], v[188:191], 0
	v_mfma_f32_16x16x32_bf16 v[96:99], v[152:155], v[188:191], 0
	v_mfma_f32_16x16x32_bf16 v[84:87], v[144:147], v[212:215], 0
	v_mfma_f32_16x16x32_bf16 v[80:83], v[152:155], v[212:215], 0
	v_mfma_f32_16x16x32_bf16 v[132:135], v[148:151], v[176:179], v[132:135]
	v_mfma_f32_16x16x32_bf16 v[128:131], v[156:159], v[176:179], v[128:131]
	v_mfma_f32_16x16x32_bf16 v[116:119], v[148:151], v[184:187], v[116:119]
	v_mfma_f32_16x16x32_bf16 v[112:115], v[156:159], v[184:187], v[112:115]
	v_mfma_f32_16x16x32_bf16 v[100:103], v[148:151], v[208:211], v[100:103]
	v_mfma_f32_16x16x32_bf16 v[96:99], v[156:159], v[208:211], v[96:99]
	v_mfma_f32_16x16x32_bf16 v[84:87], v[148:151], v[218:221], v[84:87]
	v_mfma_f32_16x16x32_bf16 v[80:83], v[156:159], v[218:221], v[80:83]
	s_setprio 0
	s_barrier
	s_add_i32 s45, s95, s33
	v_lshl_add_u64 v[198:199], s[40:41], 0, v[192:193]
	s_mov_b32 m0, s45
	ds_read_b128 v[172:175], v217 offset:17408
	ds_read_b128 v[176:179], v217 offset:17472
	ds_read_b128 v[180:183], v217 offset:19584
	ds_read_b128 v[184:187], v217 offset:19648
	ds_read_b128 v[188:191], v217 offset:21760
	ds_read_b128 v[208:211], v217 offset:21824
	ds_read_b128 v[212:215], v217 offset:23936
	ds_read_b128 v[218:221], v217 offset:24000
	global_load_lds_dwordx4 v[198:199], off
	s_add_i32 m0, s45, 0x2200
	s_add_u32 vcc_lo, s40, 0x40000
	v_lshl_add_u64 v[200:201], s[40:41], 0, v[160:161]
	s_addc_u32 vcc_hi, s41, 0
	s_add_i32 s44, s44, s33
	global_load_lds_dwordx4 v[200:201], off
	v_lshl_add_u64 v[222:223], vcc, 0, v[192:193]
	s_mov_b32 m0, s44
	v_lshl_add_u64 v[224:225], s[74:75], 0, v[162:163]
	global_load_lds_dwordx4 v[222:223], off
	v_lshl_add_u64 v[222:223], vcc, 0, v[160:161]
	s_add_i32 m0, s44, 0x2200
	s_nop 0
	global_load_lds_dwordx4 v[222:223], off
	v_lshl_add_u64 v[222:223], s[74:75], 0, v[164:165]
	s_mov_b32 m0, s0
	s_nop 0
	global_load_lds_dwordx4 v[222:223], off
	s_mov_b32 m0, s5
	s_nop 0
	global_load_lds_dwordx4 v[224:225], off
	s_waitcnt vmcnt(8)
	s_waitcnt lgkmcnt(0)
	s_barrier
; #define PG8_STAGE(bufoff, gbase, voff) do { _Pragma("unroll") for (int _i = 0; _i < 2; ++_i) \
;         __builtin_amdgcn_global_load_lds((const unsigned*)((const char*)(gbase) + (voff)[_i]), (PG8_LAS unsigned*)(lds + (bufoff) + ldsw + _i * (8 * USTR)), 16, 0, 0); } while (0)
; #define PG8_LDA(dst, b, h) do { _Pragma("unroll") for (int m = 0; m < 4; ++m) _Pragma("unroll") for (int k = 0; k < 2; ++k) dst[m][k] = *(const PG8_LAS bf16x8*)(lds + PG8_SA(b, h) + aoff + m * (2 * USTR) + k * 64); } while (0)
; #define PG8_LDB(dst, b, h) do { _Pragma("unroll") for (int n = 0; n < 2; ++n) _Pragma("unroll") for (int k = 0; k < 2; ++k) dst[n][k] = *(const PG8_LAS bf16x8*)(lds + PG8_SB(b, h) + boff + n * (2 * USTR) + k * 64); } while (0)
; #define PG8_MMA(ai, bj, At, Bt) do { __builtin_amdgcn_s_setprio(1); _Pragma("unroll") for (int m = 0; m < 4; ++m) _Pragma("unroll") for (int n = 0; n < 2; ++n) _Pragma("unroll") for (int k = 0; k < 2; ++k) \
;         acc[ai][bj][m][n] = __builtin_amdgcn_mfma_f32_16x16x32_bf16(Bt[n][k], At[m][k], acc[ai][bj][m][n], 0, 0, 0); __builtin_amdgcn_s_setprio(0); } while (0)
; #define PG8_WAIT_V(n) asm volatile("s_waitcnt vmcnt(" #n ")" ::: "memory")
; #define PG8_WAIT_L(n) asm volatile("s_waitcnt lgkmcnt(" #n ")" ::: "memory")
; #define PG8_BAR __builtin_amdgcn_s_barrier()
; #define PG8_SCHED __builtin_amdgcn_sched_barrier(0)
; template <class Epi, class Sched, bool ALIGN_EPI, bool SP2>
; __device__ __forceinline__ void gemm_phase(PG8_LAS unsigned char* lds, const Gemm g, const Sched& S, const Epi& E, int wid) {
;     ...
;             PG8_WAIT_V(8); PG8_WAIT_L(0); PG8_BAR; PG8_MMA(1, 0, At, B0); PG8_MMA(1, 1, At, B1); PG8_BAR; PG8_SCHED;
;             PG8_LDB(B0, 1, 0); PG8_LDB(B1, 1, 1); PG8_SCHED; PG8_LDA(At, 1, 0); PG8_STAGE(PG8_SA(0, 1), a2 + hstepA, voffA);
;             PG8_WAIT_V(8); PG8_WAIT_L(0); PG8_BAR; PG8_MMA(0, 0, At, B0); PG8_MMA(0, 1, At, B1); PG8_BAR; PG8_SCHED;
	s_setprio 1
	s_waitcnt lgkmcnt(0)
	v_mfma_f32_16x16x32_bf16 v[76:79], v[48:51], v[172:175], 0
	v_mfma_f32_16x16x32_bf16 v[72:75], v[56:59], v[172:175], 0
	v_mfma_f32_16x16x32_bf16 v[44:47], v[48:51], v[180:183], 0
	v_mfma_f32_16x16x32_bf16 v[40:43], v[56:59], v[180:183], 0
	v_mfma_f32_16x16x32_bf16 v[24:27], v[48:51], v[188:191], 0
	v_mfma_f32_16x16x32_bf16 v[28:31], v[56:59], v[188:191], 0
	v_mfma_f32_16x16x32_bf16 v[4:7], v[48:51], v[212:215], 0
	v_mfma_f32_16x16x32_bf16 v[12:15], v[56:59], v[212:215], 0
	v_mfma_f32_16x16x32_bf16 v[76:79], v[52:55], v[176:179], v[76:79]
	v_mfma_f32_16x16x32_bf16 v[72:75], v[60:63], v[176:179], v[72:75]
	v_mfma_f32_16x16x32_bf16 v[44:47], v[52:55], v[184:187], v[44:47]
	v_mfma_f32_16x16x32_bf16 v[40:43], v[60:63], v[184:187], v[40:43]
	v_mfma_f32_16x16x32_bf16 v[24:27], v[52:55], v[208:211], v[24:27]
	v_mfma_f32_16x16x32_bf16 v[28:31], v[60:63], v[208:211], v[28:31]
	v_mfma_f32_16x16x32_bf16 v[4:7], v[52:55], v[218:221], v[4:7]
	v_mfma_f32_16x16x32_bf16 v[12:15], v[60:63], v[218:221], v[12:15]
	s_setprio 0
	s_setprio 1
	v_mfma_f32_16x16x32_bf16 v[36:39], v[144:147], v[180:183], 0
	v_mfma_f32_16x16x32_bf16 v[32:35], v[152:155], v[180:183], 0
	v_mfma_f32_16x16x32_bf16 v[20:23], v[144:147], v[188:191], 0
	v_mfma_f32_16x16x32_bf16 v[16:19], v[152:155], v[188:191], 0
	v_mfma_f32_16x16x32_bf16 v[8:11], v[144:147], v[212:215], 0
	v_mfma_f32_16x16x32_bf16 v[0:3], v[152:155], v[212:215], 0
	v_mfma_f32_16x16x32_bf16 v[48:51], v[144:147], v[172:175], 0
	v_mfma_f32_16x16x32_bf16 v[52:55], v[152:155], v[172:175], 0
	v_mfma_f32_16x16x32_bf16 v[36:39], v[148:151], v[184:187], v[36:39]
	v_mfma_f32_16x16x32_bf16 v[32:35], v[156:159], v[184:187], v[32:35]
	v_mfma_f32_16x16x32_bf16 v[20:23], v[148:151], v[208:211], v[20:23]
	v_mfma_f32_16x16x32_bf16 v[16:19], v[156:159], v[208:211], v[16:19]
	v_mfma_f32_16x16x32_bf16 v[8:11], v[148:151], v[218:221], v[8:11]
	v_mfma_f32_16x16x32_bf16 v[0:3], v[156:159], v[218:221], v[0:3]
	v_mfma_f32_16x16x32_bf16 v[48:51], v[148:151], v[176:179], v[48:51]
	v_mfma_f32_16x16x32_bf16 v[52:55], v[156:159], v[176:179], v[52:55]
	s_setprio 0
	s_barrier
	v_add_u32_e32 v68, 0x19800, v216
	v_add_u32_e32 v156, 0x1dc00, v216
	ds_read_b128 v[56:59], v68
	ds_read_b128 v[60:63], v68 offset:64
	ds_read_b128 v[64:67], v68 offset:2176
	ds_read_b128 v[68:71], v68 offset:2240
	ds_read_b128 v[144:147], v156
	ds_read_b128 v[148:151], v156 offset:64
	ds_read_b128 v[152:155], v156 offset:2176
	ds_read_b128 v[156:159], v156 offset:2240
	s_add_i32 s44, 0, 0x19800
	s_add_i32 s45, 0, 0x1dc00
	s_add_u32 s74, s74, 0x80000
	s_addc_u32 s75, s75, 0
	s_mov_b32 m0, s29
	v_lshl_add_u64 v[226:227], s[74:75], 0, v[164:165]
	ds_read_b128 v[172:175], v217 offset:34816
	ds_read_b128 v[176:179], v217 offset:34880
	ds_read_b128 v[180:183], v217 offset:36992
	ds_read_b128 v[184:187], v217 offset:37056
	ds_read_b128 v[188:191], v217 offset:39168
	ds_read_b128 v[208:211], v217 offset:39232
	ds_read_b128 v[212:215], v217 offset:41344
	ds_read_b128 v[218:221], v217 offset:41408
	global_load_lds_dwordx4 v[226:227], off
	v_lshl_add_u64 v[226:227], s[74:75], 0, v[162:163]
	s_mov_b32 m0, s56
	s_nop 0
	global_load_lds_dwordx4 v[226:227], off
	s_waitcnt vmcnt(8)
	s_waitcnt lgkmcnt(0)
	s_barrier
	s_setprio 1
	s_waitcnt lgkmcnt(0)
	v_mfma_f32_16x16x32_bf16 v[140:143], v[56:59], v[172:175], v[140:143]
	v_mfma_f32_16x16x32_bf16 v[136:139], v[64:67], v[172:175], v[136:139]
	v_mfma_f32_16x16x32_bf16 v[124:127], v[56:59], v[180:183], v[124:127]
	v_mfma_f32_16x16x32_bf16 v[120:123], v[64:67], v[180:183], v[120:123]
	v_mfma_f32_16x16x32_bf16 v[108:111], v[56:59], v[188:191], v[108:111]
	v_mfma_f32_16x16x32_bf16 v[104:107], v[64:67], v[188:191], v[104:107]
	v_mfma_f32_16x16x32_bf16 v[92:95], v[56:59], v[212:215], v[92:95]
	v_mfma_f32_16x16x32_bf16 v[88:91], v[64:67], v[212:215], v[88:91]
	v_mfma_f32_16x16x32_bf16 v[140:143], v[60:63], v[176:179], v[140:143]
	v_mfma_f32_16x16x32_bf16 v[136:139], v[68:71], v[176:179], v[136:139]
	v_mfma_f32_16x16x32_bf16 v[124:127], v[60:63], v[184:187], v[124:127]
	v_mfma_f32_16x16x32_bf16 v[120:123], v[68:71], v[184:187], v[120:123]
	v_mfma_f32_16x16x32_bf16 v[108:111], v[60:63], v[208:211], v[108:111]
	v_mfma_f32_16x16x32_bf16 v[104:107], v[68:71], v[208:211], v[104:107]
	v_mfma_f32_16x16x32_bf16 v[92:95], v[60:63], v[218:221], v[92:95]
	v_mfma_f32_16x16x32_bf16 v[88:91], v[68:71], v[218:221], v[88:91]
	s_setprio 0
	s_setprio 1
	v_mfma_f32_16x16x32_bf16 v[132:135], v[144:147], v[172:175], v[132:135]
	v_mfma_f32_16x16x32_bf16 v[128:131], v[152:155], v[172:175], v[128:131]
	v_mfma_f32_16x16x32_bf16 v[116:119], v[144:147], v[180:183], v[116:119]
	v_mfma_f32_16x16x32_bf16 v[112:115], v[152:155], v[180:183], v[112:115]
	v_mfma_f32_16x16x32_bf16 v[100:103], v[144:147], v[188:191], v[100:103]
	v_mfma_f32_16x16x32_bf16 v[96:99], v[152:155], v[188:191], v[96:99]
	v_mfma_f32_16x16x32_bf16 v[84:87], v[144:147], v[212:215], v[84:87]
	v_mfma_f32_16x16x32_bf16 v[80:83], v[152:155], v[212:215], v[80:83]
	v_mfma_f32_16x16x32_bf16 v[132:135], v[148:151], v[176:179], v[132:135]
	v_mfma_f32_16x16x32_bf16 v[128:131], v[156:159], v[176:179], v[128:131]
	v_mfma_f32_16x16x32_bf16 v[116:119], v[148:151], v[184:187], v[116:119]
	v_mfma_f32_16x16x32_bf16 v[112:115], v[156:159], v[184:187], v[112:115]
	v_mfma_f32_16x16x32_bf16 v[100:103], v[148:151], v[208:211], v[100:103]
	v_mfma_f32_16x16x32_bf16 v[96:99], v[156:159], v[208:211], v[96:99]
	v_mfma_f32_16x16x32_bf16 v[84:87], v[148:151], v[218:221], v[84:87]
	v_mfma_f32_16x16x32_bf16 v[80:83], v[156:159], v[218:221], v[80:83]
	s_setprio 0
	s_barrier
; #define PG8_STAGE(bufoff, gbase, voff) do { _Pragma("unroll") for (int _i = 0; _i < 2; ++_i) \
;         __builtin_amdgcn_global_load_lds((const unsigned*)((const char*)(gbase) + (voff)[_i]), (PG8_LAS unsigned*)(lds + (bufoff) + ldsw + _i * (8 * USTR)), 16, 0, 0); } while (0)
; #define PG8_LDA(dst, b, h) do { _Pragma("unroll") for (int m = 0; m < 4; ++m) _Pragma("unroll") for (int k = 0; k < 2; ++k) dst[m][k] = *(const PG8_LAS bf16x8*)(lds + PG8_SA(b, h) + aoff + m * (2 * USTR) + k * 64); } while (0)
; #define PG8_LDB(dst, b, h) do { _Pragma("unroll") for (int n = 0; n < 2; ++n) _Pragma("unroll") for (int k = 0; k < 2; ++k) dst[n][k] = *(const PG8_LAS bf16x8*)(lds + PG8_SB(b, h) + boff + n * (2 * USTR) + k * 64); } while (0)
; #define PG8_MMA(ai, bj, At, Bt) do { __builtin_amdgcn_s_setprio(1); _Pragma("unroll") for (int m = 0; m < 4; ++m) _Pragma("unroll") for (int n = 0; n < 2; ++n) _Pragma("unroll") for (int k = 0; k < 2; ++k) \
;         acc[ai][bj][m][n] = __builtin_amdgcn_mfma_f32_16x16x32_bf16(Bt[n][k], At[m][k], acc[ai][bj][m][n], 0, 0, 0); __builtin_amdgcn_s_setprio(0); } while (0)
; #define PG8_WAIT_V(n) asm volatile("s_waitcnt vmcnt(" #n ")" ::: "memory")
; #define PG8_WAIT_L(n) asm volatile("s_waitcnt lgkmcnt(" #n ")" ::: "memory")
; #define PG8_BAR __builtin_amdgcn_s_barrier()
; #define PG8_SCHED __builtin_amdgcn_sched_barrier(0)
; template <class Epi, class Sched, bool ALIGN_EPI, bool SP2>
; __device__ __forceinline__ void gemm_phase(PG8_LAS unsigned char* lds, const Gemm g, const Sched& S, const Epi& E, int wid) {
;     ...
;             PG8_LDB(B0, 0, 0); PG8_LDB(B1, 0, 1); PG8_SCHED; PG8_LDA(At, 0, 0); PG8_STAGE(PG8_SA(1, 1), a1 + hstepA, voffA);
;             PG8_WAIT_V(8); PG8_WAIT_L(0); PG8_BAR; PG8_MMA(0, 0, At, B0); PG8_MMA(0, 1, At, B1); PG8_BAR; PG8_SCHED;
;     ...
;             PG8_LDA(At, 1, 1); PG8_STAGE(PG8_SB(1, 0), b3, voffB); PG8_STAGE(PG8_SB(1, 1), b3 + hstepB, voffB); PG8_STAGE(PG8_SA(1, 0), a3, voffA);
;             PG8_WAIT_V(8); PG8_WAIT_L(0); PG8_BAR; PG8_MMA(1, 0, At, B0); PG8_MMA(1, 1, At, B1); PG8_BAR; PG8_SCHED;
	s_add_i32 s44, s44, s33
	v_lshl_add_u64 v[198:199], v[198:199], 0, s[6:7]
	s_mov_b32 m0, s44
	ds_read_b128 v[172:175], v217 offset:52224
	ds_read_b128 v[176:179], v217 offset:52288
	ds_read_b128 v[180:183], v217 offset:54400
	ds_read_b128 v[184:187], v217 offset:54464
	ds_read_b128 v[188:191], v217 offset:56576
	ds_read_b128 v[208:211], v217 offset:56640
	ds_read_b128 v[212:215], v217 offset:58752
	ds_read_b128 v[218:221], v217 offset:58816
	global_load_lds_dwordx4 v[198:199], off
	s_add_i32 m0, s44, 0x2200
	s_add_u32 s40, s40, 0x40080
	v_lshl_add_u64 v[198:199], v[200:201], 0, s[6:7]
	s_addc_u32 s41, s41, 0
	s_add_i32 s44, s45, s33
	global_load_lds_dwordx4 v[198:199], off
	v_lshl_add_u64 v[198:199], s[40:41], 0, v[192:193]
	s_mov_b32 m0, s44
	s_nop 0
	global_load_lds_dwordx4 v[198:199], off
	v_lshl_add_u64 v[198:199], s[40:41], 0, v[160:161]
	s_add_i32 m0, s44, 0x2200
	s_nop 0
	global_load_lds_dwordx4 v[198:199], off
	v_lshl_add_u64 v[198:199], v[222:223], 0, s[6:7]
	s_mov_b32 m0, s57
	s_nop 0
	global_load_lds_dwordx4 v[198:199], off
	v_lshl_add_u64 v[198:199], v[224:225], 0, s[6:7]
	s_mov_b32 m0, s76
	s_nop 0
	global_load_lds_dwordx4 v[198:199], off
	s_add_i32 s89, s89, 2
	s_add_u32 s38, s38, 0x100
	s_addc_u32 s39, s39, 0
	s_add_u32 s78, s78, 0x100
	s_addc_u32 s79, s79, 0
	s_waitcnt vmcnt(8)
	s_waitcnt lgkmcnt(0)
	s_barrier
	s_setprio 1
	s_waitcnt lgkmcnt(0)
	v_mfma_f32_16x16x32_bf16 v[76:79], v[56:59], v[172:175], v[76:79]
	v_mfma_f32_16x16x32_bf16 v[72:75], v[64:67], v[172:175], v[72:75]
	v_mfma_f32_16x16x32_bf16 v[44:47], v[56:59], v[180:183], v[44:47]
	v_mfma_f32_16x16x32_bf16 v[40:43], v[64:67], v[180:183], v[40:43]
	v_mfma_f32_16x16x32_bf16 v[24:27], v[56:59], v[188:191], v[24:27]
	v_mfma_f32_16x16x32_bf16 v[28:31], v[64:67], v[188:191], v[28:31]
	v_mfma_f32_16x16x32_bf16 v[4:7], v[56:59], v[212:215], v[4:7]
	v_mfma_f32_16x16x32_bf16 v[12:15], v[64:67], v[212:215], v[12:15]
	v_mfma_f32_16x16x32_bf16 v[76:79], v[60:63], v[176:179], v[76:79]
	v_mfma_f32_16x16x32_bf16 v[72:75], v[68:71], v[176:179], v[72:75]
	v_mfma_f32_16x16x32_bf16 v[44:47], v[60:63], v[184:187], v[44:47]
	v_mfma_f32_16x16x32_bf16 v[40:43], v[68:71], v[184:187], v[40:43]
	v_mfma_f32_16x16x32_bf16 v[24:27], v[60:63], v[208:211], v[24:27]
	v_mfma_f32_16x16x32_bf16 v[28:31], v[68:71], v[208:211], v[28:31]
	v_mfma_f32_16x16x32_bf16 v[4:7], v[60:63], v[218:221], v[4:7]
	v_mfma_f32_16x16x32_bf16 v[12:15], v[68:71], v[218:221], v[12:15]
	s_setprio 0
	s_setprio 1
	v_mfma_f32_16x16x32_bf16 v[48:51], v[144:147], v[172:175], v[48:51]
	v_mfma_f32_16x16x32_bf16 v[68:71], v[148:151], v[176:179], v[48:51]
	v_mfma_f32_16x16x32_bf16 v[48:51], v[152:155], v[172:175], v[52:55]
	v_mfma_f32_16x16x32_bf16 v[36:39], v[144:147], v[180:183], v[36:39]
	v_mfma_f32_16x16x32_bf16 v[32:35], v[152:155], v[180:183], v[32:35]
	v_mfma_f32_16x16x32_bf16 v[20:23], v[144:147], v[188:191], v[20:23]
	v_mfma_f32_16x16x32_bf16 v[16:19], v[152:155], v[188:191], v[16:19]
	v_mfma_f32_16x16x32_bf16 v[8:11], v[144:147], v[212:215], v[8:11]
	v_mfma_f32_16x16x32_bf16 v[0:3], v[152:155], v[212:215], v[0:3]
	v_mfma_f32_16x16x32_bf16 v[64:67], v[156:159], v[176:179], v[48:51]
	v_mfma_f32_16x16x32_bf16 v[36:39], v[148:151], v[184:187], v[36:39]
	v_mfma_f32_16x16x32_bf16 v[32:35], v[156:159], v[184:187], v[32:35]
	v_mfma_f32_16x16x32_bf16 v[20:23], v[148:151], v[208:211], v[20:23]
	v_mfma_f32_16x16x32_bf16 v[16:19], v[156:159], v[208:211], v[16:19]
	v_mfma_f32_16x16x32_bf16 v[8:11], v[148:151], v[218:221], v[8:11]
	v_mfma_f32_16x16x32_bf16 v[0:3], v[156:159], v[218:221], v[0:3]
	s_setprio 0
	s_barrier
	s_cmp_gt_u32 s89, 13
.LBB0_150:
	v_add_u32_e32 v60, 0x11000, v216
	v_add_u32_e32 v156, 0x15400, v216
	ds_read_b128 v[48:51], v60
	ds_read_b128 v[52:55], v60 offset:64
	ds_read_b128 v[56:59], v60 offset:2176
	ds_read_b128 v[60:63], v60 offset:2240
	ds_read_b128 v[144:147], v156
	ds_read_b128 v[148:151], v156 offset:64
	ds_read_b128 v[152:155], v156 offset:2176
	ds_read_b128 v[156:159], v156 offset:2240
	s_add_i32 s95, 0, 0x11000
	s_add_i32 s44, 0, 0x15400
	v_lshl_add_u64 v[198:199], s[38:39], 0, v[168:169]
	s_add_i32 m0, s0, 0xcc00
	ds_read_b128 v[172:175], v217
	ds_read_b128 v[176:179], v217 offset:64
	ds_read_b128 v[180:183], v217 offset:2176
	ds_read_b128 v[184:187], v217 offset:2240
	ds_read_b128 v[188:191], v217 offset:4352
	ds_read_b128 v[208:211], v217 offset:4416
	ds_read_b128 v[212:215], v217 offset:6528
	ds_read_b128 v[218:221], v217 offset:6592
	global_load_lds_dwordx4 v[198:199], off
	v_lshl_add_u64 v[198:199], s[38:39], 0, v[170:171]
	s_add_i32 m0, s0, 0xee00
	s_nop 0
	global_load_lds_dwordx4 v[198:199], off
	s_add_u32 s40, s38, 0xfff80080
	s_addc_u32 s41, s39, -1
	s_cmp_eq_u32 s89, 12
	s_cselect_b32 s75, s26, s41
	s_cselect_b32 s74, s27, s40
	s_cselect_b32 s41, s23, s79
	s_cselect_b32 s40, s69, s78
	s_waitcnt vmcnt(8)
	s_waitcnt lgkmcnt(0)
	s_barrier
; #define PG8_STAGE(bufoff, gbase, voff) do { _Pragma("unroll") for (int _i = 0; _i < 2; ++_i) \
;         __builtin_amdgcn_global_load_lds((const unsigned*)((const char*)(gbase) + (voff)[_i]), (PG8_LAS unsigned*)(lds + (bufoff) + ldsw + _i * (8 * USTR)), 16, 0, 0); } while (0)
; #define PG8_LDA(dst, b, h) do { _Pragma("unroll") for (int m = 0; m < 4; ++m) _Pragma("unroll") for (int k = 0; k < 2; ++k) dst[m][k] = *(const PG8_LAS bf16x8*)(lds + PG8_SA(b, h) + aoff + m * (2 * USTR) + k * 64); } while (0)
; #define PG8_MMA(ai, bj, At, Bt) do { __builtin_amdgcn_s_setprio(1); _Pragma("unroll") for (int m = 0; m < 4; ++m) _Pragma("unroll") for (int n = 0; n < 2; ++n) _Pragma("unroll") for (int k = 0; k < 2; ++k) \
;         acc[ai][bj][m][n] = __builtin_amdgcn_mfma_f32_16x16x32_bf16(Bt[n][k], At[m][k], acc[ai][bj][m][n], 0, 0, 0); __builtin_amdgcn_s_setprio(0); } while (0)
; #define PG8_WAIT_V(n) asm volatile("s_waitcnt vmcnt(" #n ")" ::: "memory")
; #define PG8_WAIT_L(n) asm volatile("s_waitcnt lgkmcnt(" #n ")" ::: "memory")
; #define PG8_BAR __builtin_amdgcn_s_barrier()
; #define PG8_SCHED __builtin_amdgcn_sched_barrier(0)
; template <class Epi, class Sched, bool ALIGN_EPI, bool SP2>
; __device__ __forceinline__ void gemm_phase(PG8_LAS unsigned char* lds, const Gemm g, const Sched& S, const Epi& E, int wid) {
;     ...
;             PG8_WAIT_V(8); PG8_WAIT_L(0); PG8_BAR; PG8_MMA(0, 0, At, B0); PG8_MMA(0, 1, At, B1); PG8_BAR; PG8_SCHED;
;             PG8_LDA(At, 0, 1); PG8_STAGE(PG8_SB(0, 0), b2, voffB); PG8_STAGE(PG8_SB(0, 1), b2 + hstepB, voffB); PG8_STAGE(PG8_SA(0, 0), a2, voffA);
;             PG8_WAIT_V(8); PG8_WAIT_L(0); PG8_BAR; PG8_MMA(1, 0, At, B0); PG8_MMA(1, 1, At, B1); PG8_BAR; PG8_SCHED;
	s_setprio 1
	s_waitcnt lgkmcnt(0)
	v_mfma_f32_16x16x32_bf16 v[140:143], v[48:51], v[172:175], v[140:143]
	v_mfma_f32_16x16x32_bf16 v[136:139], v[56:59], v[172:175], v[136:139]
	v_mfma_f32_16x16x32_bf16 v[124:127], v[48:51], v[180:183], v[124:127]
	v_mfma_f32_16x16x32_bf16 v[120:123], v[56:59], v[180:183], v[120:123]
	v_mfma_f32_16x16x32_bf16 v[108:111], v[48:51], v[188:191], v[108:111]
	v_mfma_f32_16x16x32_bf16 v[104:107], v[56:59], v[188:191], v[104:107]
	v_mfma_f32_16x16x32_bf16 v[92:95], v[48:51], v[212:215], v[92:95]
	v_mfma_f32_16x16x32_bf16 v[88:91], v[56:59], v[212:215], v[88:91]
	v_mfma_f32_16x16x32_bf16 v[140:143], v[52:55], v[176:179], v[140:143]
	v_mfma_f32_16x16x32_bf16 v[136:139], v[60:63], v[176:179], v[136:139]
	v_mfma_f32_16x16x32_bf16 v[124:127], v[52:55], v[184:187], v[124:127]
	v_mfma_f32_16x16x32_bf16 v[120:123], v[60:63], v[184:187], v[120:123]
	v_mfma_f32_16x16x32_bf16 v[108:111], v[52:55], v[208:211], v[108:111]
	v_mfma_f32_16x16x32_bf16 v[104:107], v[60:63], v[208:211], v[104:107]
	v_mfma_f32_16x16x32_bf16 v[92:95], v[52:55], v[218:221], v[92:95]
	v_mfma_f32_16x16x32_bf16 v[88:91], v[60:63], v[218:221], v[88:91]
	s_setprio 0
	s_setprio 1
	v_mfma_f32_16x16x32_bf16 v[132:135], v[144:147], v[172:175], v[132:135]
	v_mfma_f32_16x16x32_bf16 v[128:131], v[152:155], v[172:175], v[128:131]
	v_mfma_f32_16x16x32_bf16 v[116:119], v[144:147], v[180:183], v[116:119]
	v_mfma_f32_16x16x32_bf16 v[112:115], v[152:155], v[180:183], v[112:115]
	v_mfma_f32_16x16x32_bf16 v[100:103], v[144:147], v[188:191], v[100:103]
	v_mfma_f32_16x16x32_bf16 v[96:99], v[152:155], v[188:191], v[96:99]
	v_mfma_f32_16x16x32_bf16 v[84:87], v[144:147], v[212:215], v[84:87]
	v_mfma_f32_16x16x32_bf16 v[80:83], v[152:155], v[212:215], v[80:83]
	v_mfma_f32_16x16x32_bf16 v[132:135], v[148:151], v[176:179], v[132:135]
	v_mfma_f32_16x16x32_bf16 v[128:131], v[156:159], v[176:179], v[128:131]
	v_mfma_f32_16x16x32_bf16 v[116:119], v[148:151], v[184:187], v[116:119]
	v_mfma_f32_16x16x32_bf16 v[112:115], v[156:159], v[184:187], v[112:115]
	v_mfma_f32_16x16x32_bf16 v[100:103], v[148:151], v[208:211], v[100:103]
	v_mfma_f32_16x16x32_bf16 v[96:99], v[156:159], v[208:211], v[96:99]
	v_mfma_f32_16x16x32_bf16 v[84:87], v[148:151], v[218:221], v[84:87]
	v_mfma_f32_16x16x32_bf16 v[80:83], v[156:159], v[218:221], v[80:83]
	s_setprio 0
	s_barrier
	s_add_i32 s45, s95, s33
	v_lshl_add_u64 v[198:199], s[40:41], 0, v[192:193]
	s_mov_b32 m0, s45
	ds_read_b128 v[172:175], v217 offset:17408
	ds_read_b128 v[176:179], v217 offset:17472
	ds_read_b128 v[180:183], v217 offset:19584
	ds_read_b128 v[184:187], v217 offset:19648
	ds_read_b128 v[188:191], v217 offset:21760
	ds_read_b128 v[208:211], v217 offset:21824
	ds_read_b128 v[212:215], v217 offset:23936
	ds_read_b128 v[218:221], v217 offset:24000
	global_load_lds_dwordx4 v[198:199], off
	s_add_i32 m0, s45, 0x2200
	s_add_u32 vcc_lo, s40, 0x40000
	v_lshl_add_u64 v[200:201], s[40:41], 0, v[160:161]
	s_addc_u32 vcc_hi, s41, 0
	s_add_i32 s44, s44, s33
	global_load_lds_dwordx4 v[200:201], off
	v_lshl_add_u64 v[222:223], vcc, 0, v[192:193]
	s_mov_b32 m0, s44
	v_lshl_add_u64 v[224:225], s[74:75], 0, v[162:163]
	global_load_lds_dwordx4 v[222:223], off
	v_lshl_add_u64 v[222:223], vcc, 0, v[160:161]
	s_add_i32 m0, s44, 0x2200
	s_nop 0
	global_load_lds_dwordx4 v[222:223], off
	v_lshl_add_u64 v[222:223], s[74:75], 0, v[164:165]
	s_mov_b32 m0, s0
	s_nop 0
	global_load_lds_dwordx4 v[222:223], off
	s_mov_b32 m0, s5
	s_nop 0
	global_load_lds_dwordx4 v[224:225], off
	s_waitcnt vmcnt(8)
	s_waitcnt lgkmcnt(0)
	s_barrier
	s_setprio 1
	s_waitcnt lgkmcnt(0)
	v_mfma_f32_16x16x32_bf16 v[76:79], v[48:51], v[172:175], v[76:79]
	v_mfma_f32_16x16x32_bf16 v[72:75], v[56:59], v[172:175], v[72:75]
	v_mfma_f32_16x16x32_bf16 v[44:47], v[48:51], v[180:183], v[44:47]
	v_mfma_f32_16x16x32_bf16 v[40:43], v[56:59], v[180:183], v[40:43]
	v_mfma_f32_16x16x32_bf16 v[24:27], v[48:51], v[188:191], v[24:27]
	v_mfma_f32_16x16x32_bf16 v[28:31], v[56:59], v[188:191], v[28:31]
	v_mfma_f32_16x16x32_bf16 v[4:7], v[48:51], v[212:215], v[4:7]
	v_mfma_f32_16x16x32_bf16 v[12:15], v[56:59], v[212:215], v[12:15]
	v_mfma_f32_16x16x32_bf16 v[76:79], v[52:55], v[176:179], v[76:79]
	v_mfma_f32_16x16x32_bf16 v[72:75], v[60:63], v[176:179], v[72:75]
	v_mfma_f32_16x16x32_bf16 v[44:47], v[52:55], v[184:187], v[44:47]
	v_mfma_f32_16x16x32_bf16 v[40:43], v[60:63], v[184:187], v[40:43]
	v_mfma_f32_16x16x32_bf16 v[24:27], v[52:55], v[208:211], v[24:27]
	v_mfma_f32_16x16x32_bf16 v[28:31], v[60:63], v[208:211], v[28:31]
	v_mfma_f32_16x16x32_bf16 v[4:7], v[52:55], v[218:221], v[4:7]
	v_mfma_f32_16x16x32_bf16 v[12:15], v[60:63], v[218:221], v[12:15]
	s_setprio 0
	s_setprio 1
	v_mfma_f32_16x16x32_bf16 v[36:39], v[144:147], v[180:183], v[36:39]
	v_mfma_f32_16x16x32_bf16 v[32:35], v[152:155], v[180:183], v[32:35]
	v_mfma_f32_16x16x32_bf16 v[20:23], v[144:147], v[188:191], v[20:23]
	v_mfma_f32_16x16x32_bf16 v[16:19], v[152:155], v[188:191], v[16:19]
	v_mfma_f32_16x16x32_bf16 v[8:11], v[144:147], v[212:215], v[8:11]
	v_mfma_f32_16x16x32_bf16 v[0:3], v[152:155], v[212:215], v[0:3]
	v_mfma_f32_16x16x32_bf16 v[48:51], v[144:147], v[172:175], v[68:71]
	v_mfma_f32_16x16x32_bf16 v[52:55], v[152:155], v[172:175], v[64:67]
	v_mfma_f32_16x16x32_bf16 v[36:39], v[148:151], v[184:187], v[36:39]
	v_mfma_f32_16x16x32_bf16 v[32:35], v[156:159], v[184:187], v[32:35]
	v_mfma_f32_16x16x32_bf16 v[20:23], v[148:151], v[208:211], v[20:23]
	v_mfma_f32_16x16x32_bf16 v[16:19], v[156:159], v[208:211], v[16:19]
	v_mfma_f32_16x16x32_bf16 v[8:11], v[148:151], v[218:221], v[8:11]
	v_mfma_f32_16x16x32_bf16 v[0:3], v[156:159], v[218:221], v[0:3]
	v_mfma_f32_16x16x32_bf16 v[48:51], v[148:151], v[176:179], v[48:51]
	v_mfma_f32_16x16x32_bf16 v[52:55], v[156:159], v[176:179], v[52:55]
	s_setprio 0
	s_barrier
; #define PG8_STAGE(bufoff, gbase, voff) do { _Pragma("unroll") for (int _i = 0; _i < 2; ++_i) \
;         __builtin_amdgcn_global_load_lds((const unsigned*)((const char*)(gbase) + (voff)[_i]), (PG8_LAS unsigned*)(lds + (bufoff) + ldsw + _i * (8 * USTR)), 16, 0, 0); } while (0)
; #define PG8_LDA(dst, b, h) do { _Pragma("unroll") for (int m = 0; m < 4; ++m) _Pragma("unroll") for (int k = 0; k < 2; ++k) dst[m][k] = *(const PG8_LAS bf16x8*)(lds + PG8_SA(b, h) + aoff + m * (2 * USTR) + k * 64); } while (0)
; #define PG8_LDB(dst, b, h) do { _Pragma("unroll") for (int n = 0; n < 2; ++n) _Pragma("unroll") for (int k = 0; k < 2; ++k) dst[n][k] = *(const PG8_LAS bf16x8*)(lds + PG8_SB(b, h) + boff + n * (2 * USTR) + k * 64); } while (0)
; #define PG8_MMA(ai, bj, At, Bt) do { __builtin_amdgcn_s_setprio(1); _Pragma("unroll") for (int m = 0; m < 4; ++m) _Pragma("unroll") for (int n = 0; n < 2; ++n) _Pragma("unroll") for (int k = 0; k < 2; ++k) \
;         acc[ai][bj][m][n] = __builtin_amdgcn_mfma_f32_16x16x32_bf16(Bt[n][k], At[m][k], acc[ai][bj][m][n], 0, 0, 0); __builtin_amdgcn_s_setprio(0); } while (0)
; #define PG8_WAIT_V(n) asm volatile("s_waitcnt vmcnt(" #n ")" ::: "memory")
; #define PG8_WAIT_L(n) asm volatile("s_waitcnt lgkmcnt(" #n ")" ::: "memory")
; #define PG8_BAR __builtin_amdgcn_s_barrier()
; #define PG8_SCHED __builtin_amdgcn_sched_barrier(0)
; template <class Epi, class Sched, bool ALIGN_EPI, bool SP2>
; __device__ __forceinline__ void gemm_phase(PG8_LAS unsigned char* lds, const Gemm g, const Sched& S, const Epi& E, int wid) {
;     ...
;             PG8_LDB(B0, 1, 0); PG8_LDB(B1, 1, 1); PG8_SCHED; PG8_LDA(At, 1, 0); PG8_STAGE(PG8_SA(0, 1), a2 + hstepA, voffA);
;             PG8_WAIT_V(8); PG8_WAIT_L(0); PG8_BAR; PG8_MMA(0, 0, At, B0); PG8_MMA(0, 1, At, B1); PG8_BAR; PG8_SCHED;
	v_add_u32_e32 v68, 0x19800, v216
	v_add_u32_e32 v156, 0x1dc00, v216
	ds_read_b128 v[56:59], v68
	ds_read_b128 v[60:63], v68 offset:64
	ds_read_b128 v[64:67], v68 offset:2176
	ds_read_b128 v[68:71], v68 offset:2240
	ds_read_b128 v[144:147], v156
	ds_read_b128 v[148:151], v156 offset:64
	ds_read_b128 v[152:155], v156 offset:2176
	ds_read_b128 v[156:159], v156 offset:2240
	s_add_i32 s44, 0, 0x19800
	s_add_i32 s45, 0, 0x1dc00
	s_add_u32 s74, s74, 0x80000
	s_addc_u32 s75, s75, 0
	s_mov_b32 m0, s29
	v_lshl_add_u64 v[226:227], s[74:75], 0, v[164:165]
	ds_read_b128 v[172:175], v217 offset:34816
	ds_read_b128 v[176:179], v217 offset:34880
	ds_read_b128 v[180:183], v217 offset:36992
	ds_read_b128 v[184:187], v217 offset:37056
	ds_read_b128 v[188:191], v217 offset:39168
	ds_read_b128 v[208:211], v217 offset:39232
	ds_read_b128 v[212:215], v217 offset:41344
	ds_read_b128 v[218:221], v217 offset:41408
	global_load_lds_dwordx4 v[226:227], off
	v_lshl_add_u64 v[226:227], s[74:75], 0, v[162:163]
	s_mov_b32 m0, s56
	s_nop 0
	global_load_lds_dwordx4 v[226:227], off
	s_waitcnt vmcnt(8)
	s_waitcnt lgkmcnt(0)
	s_barrier
	s_setprio 1
	s_waitcnt lgkmcnt(0)
	v_mfma_f32_16x16x32_bf16 v[140:143], v[56:59], v[172:175], v[140:143]
	v_mfma_f32_16x16x32_bf16 v[136:139], v[64:67], v[172:175], v[136:139]
	v_mfma_f32_16x16x32_bf16 v[124:127], v[56:59], v[180:183], v[124:127]
	v_mfma_f32_16x16x32_bf16 v[120:123], v[64:67], v[180:183], v[120:123]
	v_mfma_f32_16x16x32_bf16 v[108:111], v[56:59], v[188:191], v[108:111]
	v_mfma_f32_16x16x32_bf16 v[104:107], v[64:67], v[188:191], v[104:107]
	v_mfma_f32_16x16x32_bf16 v[92:95], v[56:59], v[212:215], v[92:95]
	v_mfma_f32_16x16x32_bf16 v[88:91], v[64:67], v[212:215], v[88:91]
	v_mfma_f32_16x16x32_bf16 v[140:143], v[60:63], v[176:179], v[140:143]
	v_mfma_f32_16x16x32_bf16 v[136:139], v[68:71], v[176:179], v[136:139]
	v_mfma_f32_16x16x32_bf16 v[124:127], v[60:63], v[184:187], v[124:127]
	v_mfma_f32_16x16x32_bf16 v[120:123], v[68:71], v[184:187], v[120:123]
	v_mfma_f32_16x16x32_bf16 v[108:111], v[60:63], v[208:211], v[108:111]
	v_mfma_f32_16x16x32_bf16 v[104:107], v[68:71], v[208:211], v[104:107]
	v_mfma_f32_16x16x32_bf16 v[92:95], v[60:63], v[218:221], v[92:95]
	v_mfma_f32_16x16x32_bf16 v[88:91], v[68:71], v[218:221], v[88:91]
	s_setprio 0
	s_setprio 1
	v_mfma_f32_16x16x32_bf16 v[132:135], v[144:147], v[172:175], v[132:135]
	v_mfma_f32_16x16x32_bf16 v[128:131], v[152:155], v[172:175], v[128:131]
	v_mfma_f32_16x16x32_bf16 v[116:119], v[144:147], v[180:183], v[116:119]
	v_mfma_f32_16x16x32_bf16 v[112:115], v[152:155], v[180:183], v[112:115]
	v_mfma_f32_16x16x32_bf16 v[100:103], v[144:147], v[188:191], v[100:103]
	v_mfma_f32_16x16x32_bf16 v[96:99], v[152:155], v[188:191], v[96:99]
	v_mfma_f32_16x16x32_bf16 v[84:87], v[144:147], v[212:215], v[84:87]
	v_mfma_f32_16x16x32_bf16 v[80:83], v[152:155], v[212:215], v[80:83]
	v_mfma_f32_16x16x32_bf16 v[132:135], v[148:151], v[176:179], v[132:135]
	v_mfma_f32_16x16x32_bf16 v[128:131], v[156:159], v[176:179], v[128:131]
	v_mfma_f32_16x16x32_bf16 v[116:119], v[148:151], v[184:187], v[116:119]
	v_mfma_f32_16x16x32_bf16 v[112:115], v[156:159], v[184:187], v[112:115]
	v_mfma_f32_16x16x32_bf16 v[100:103], v[148:151], v[208:211], v[100:103]
	v_mfma_f32_16x16x32_bf16 v[96:99], v[156:159], v[208:211], v[96:99]
	v_mfma_f32_16x16x32_bf16 v[84:87], v[148:151], v[218:221], v[84:87]
	v_mfma_f32_16x16x32_bf16 v[80:83], v[156:159], v[218:221], v[80:83]
	s_setprio 0
	s_barrier
; #define PG8_STAGE(bufoff, gbase, voff) do { _Pragma("unroll") for (int _i = 0; _i < 2; ++_i) \
;         __builtin_amdgcn_global_load_lds((const unsigned*)((const char*)(gbase) + (voff)[_i]), (PG8_LAS unsigned*)(lds + (bufoff) + ldsw + _i * (8 * USTR)), 16, 0, 0); } while (0)
; #define PG8_LDA(dst, b, h) do { _Pragma("unroll") for (int m = 0; m < 4; ++m) _Pragma("unroll") for (int k = 0; k < 2; ++k) dst[m][k] = *(const PG8_LAS bf16x8*)(lds + PG8_SA(b, h) + aoff + m * (2 * USTR) + k * 64); } while (0)
; #define PG8_MMA(ai, bj, At, Bt) do { __builtin_amdgcn_s_setprio(1); _Pragma("unroll") for (int m = 0; m < 4; ++m) _Pragma("unroll") for (int n = 0; n < 2; ++n) _Pragma("unroll") for (int k = 0; k < 2; ++k) \
;         acc[ai][bj][m][n] = __builtin_amdgcn_mfma_f32_16x16x32_bf16(Bt[n][k], At[m][k], acc[ai][bj][m][n], 0, 0, 0); __builtin_amdgcn_s_setprio(0); } while (0)
; #define PG8_WAIT_V(n) asm volatile("s_waitcnt vmcnt(" #n ")" ::: "memory")
; #define PG8_WAIT_L(n) asm volatile("s_waitcnt lgkmcnt(" #n ")" ::: "memory")
; #define PG8_BAR __builtin_amdgcn_s_barrier()
; #define PG8_SCHED __builtin_amdgcn_sched_barrier(0)
; template <class Epi, class Sched, bool ALIGN_EPI, bool SP2>
; __device__ __forceinline__ void gemm_phase(PG8_LAS unsigned char* lds, const Gemm g, const Sched& S, const Epi& E, int wid) {
;     ...
;             PG8_LDA(At, 1, 1); PG8_STAGE(PG8_SB(1, 0), b3, voffB); PG8_STAGE(PG8_SB(1, 1), b3 + hstepB, voffB); PG8_STAGE(PG8_SA(1, 0), a3, voffA);
;             PG8_WAIT_V(8); PG8_WAIT_L(0); PG8_BAR; PG8_MMA(1, 0, At, B0); PG8_MMA(1, 1, At, B1); PG8_BAR; PG8_SCHED;
;     ...
;         if constexpr (ALIGN_EPI) { if (wr == 0) PG8_BAR; }
	s_add_i32 s44, s44, s33
	v_lshl_add_u64 v[198:199], v[198:199], 0, s[6:7]
	s_mov_b32 m0, s44
	ds_read_b128 v[172:175], v217 offset:52224
	ds_read_b128 v[176:179], v217 offset:52288
	ds_read_b128 v[180:183], v217 offset:54400
	ds_read_b128 v[184:187], v217 offset:54464
	ds_read_b128 v[188:191], v217 offset:56576
	ds_read_b128 v[208:211], v217 offset:56640
	ds_read_b128 v[212:215], v217 offset:58752
	ds_read_b128 v[218:221], v217 offset:58816
	global_load_lds_dwordx4 v[198:199], off
	s_add_i32 m0, s44, 0x2200
	s_add_u32 s40, s40, 0x40080
	v_lshl_add_u64 v[198:199], v[200:201], 0, s[6:7]
	s_addc_u32 s41, s41, 0
	s_add_i32 s44, s45, s33
	global_load_lds_dwordx4 v[198:199], off
	v_lshl_add_u64 v[198:199], s[40:41], 0, v[192:193]
	s_mov_b32 m0, s44
	s_nop 0
	global_load_lds_dwordx4 v[198:199], off
	v_lshl_add_u64 v[198:199], s[40:41], 0, v[160:161]
	s_add_i32 m0, s44, 0x2200
	s_nop 0
	global_load_lds_dwordx4 v[198:199], off
	v_lshl_add_u64 v[198:199], v[222:223], 0, s[6:7]
	s_mov_b32 m0, s57
	s_nop 0
	global_load_lds_dwordx4 v[198:199], off
	v_lshl_add_u64 v[198:199], v[224:225], 0, s[6:7]
	s_mov_b32 m0, s76
	s_nop 0
	global_load_lds_dwordx4 v[198:199], off
	s_add_i32 s89, s89, 2
	s_add_u32 s38, s38, 0x100
	s_addc_u32 s39, s39, 0
	s_add_u32 s78, s78, 0x100
	s_addc_u32 s79, s79, 0
	s_waitcnt vmcnt(8)
	s_waitcnt lgkmcnt(0)
	s_barrier
	s_setprio 1
	s_waitcnt lgkmcnt(0)
	v_mfma_f32_16x16x32_bf16 v[76:79], v[56:59], v[172:175], v[76:79]
	v_mfma_f32_16x16x32_bf16 v[72:75], v[64:67], v[172:175], v[72:75]
	v_mfma_f32_16x16x32_bf16 v[44:47], v[56:59], v[180:183], v[44:47]
	v_mfma_f32_16x16x32_bf16 v[40:43], v[64:67], v[180:183], v[40:43]
	v_mfma_f32_16x16x32_bf16 v[24:27], v[56:59], v[188:191], v[24:27]
	v_mfma_f32_16x16x32_bf16 v[28:31], v[64:67], v[188:191], v[28:31]
	v_mfma_f32_16x16x32_bf16 v[4:7], v[56:59], v[212:215], v[4:7]
	v_mfma_f32_16x16x32_bf16 v[12:15], v[64:67], v[212:215], v[12:15]
	v_mfma_f32_16x16x32_bf16 v[76:79], v[60:63], v[176:179], v[76:79]
	v_mfma_f32_16x16x32_bf16 v[72:75], v[68:71], v[176:179], v[72:75]
	v_mfma_f32_16x16x32_bf16 v[44:47], v[60:63], v[184:187], v[44:47]
	v_mfma_f32_16x16x32_bf16 v[40:43], v[68:71], v[184:187], v[40:43]
	v_mfma_f32_16x16x32_bf16 v[24:27], v[60:63], v[208:211], v[24:27]
	v_mfma_f32_16x16x32_bf16 v[28:31], v[68:71], v[208:211], v[28:31]
	v_mfma_f32_16x16x32_bf16 v[4:7], v[60:63], v[218:221], v[4:7]
	v_mfma_f32_16x16x32_bf16 v[12:15], v[68:71], v[218:221], v[12:15]
	s_setprio 0
	s_setprio 1
	v_mfma_f32_16x16x32_bf16 v[48:51], v[144:147], v[172:175], v[48:51]
	v_mfma_f32_16x16x32_bf16 v[68:71], v[148:151], v[176:179], v[48:51]
	v_mfma_f32_16x16x32_bf16 v[48:51], v[152:155], v[172:175], v[52:55]
	v_mfma_f32_16x16x32_bf16 v[36:39], v[144:147], v[180:183], v[36:39]
	v_mfma_f32_16x16x32_bf16 v[32:35], v[152:155], v[180:183], v[32:35]
	v_mfma_f32_16x16x32_bf16 v[20:23], v[144:147], v[188:191], v[20:23]
	v_mfma_f32_16x16x32_bf16 v[16:19], v[152:155], v[188:191], v[16:19]
	v_mfma_f32_16x16x32_bf16 v[8:11], v[144:147], v[212:215], v[8:11]
	v_mfma_f32_16x16x32_bf16 v[0:3], v[152:155], v[212:215], v[0:3]
	v_mfma_f32_16x16x32_bf16 v[64:67], v[156:159], v[176:179], v[48:51]
	v_mfma_f32_16x16x32_bf16 v[36:39], v[148:151], v[184:187], v[36:39]
	v_mfma_f32_16x16x32_bf16 v[32:35], v[156:159], v[184:187], v[32:35]
	v_mfma_f32_16x16x32_bf16 v[20:23], v[148:151], v[208:211], v[20:23]
	v_mfma_f32_16x16x32_bf16 v[16:19], v[156:159], v[208:211], v[16:19]
	v_mfma_f32_16x16x32_bf16 v[8:11], v[148:151], v[218:221], v[8:11]
	v_mfma_f32_16x16x32_bf16 v[0:3], v[156:159], v[218:221], v[0:3]
	s_setprio 0
	s_barrier
	s_cmp_gt_u32 s89, 13
	s_cbranch_scc0 .LBB0_150
	s_and_b64 vcc, exec, s[20:21]
	s_cbranch_vccz .LBB0_153
	s_barrier

; #define PG8_STAGE(bufoff, gbase, voff) do { _Pragma("unroll") for (int _i = 0; _i < 2; ++_i) \
;         __builtin_amdgcn_global_load_lds((const unsigned*)((const char*)(gbase) + (voff)[_i]), (PG8_LAS unsigned*)(lds + (bufoff) + ldsw + _i * (8 * USTR)), 16, 0, 0); } while (0)
; #define PG8_LDA(dst, b, h) do { _Pragma("unroll") for (int m = 0; m < 4; ++m) _Pragma("unroll") for (int k = 0; k < 2; ++k) dst[m][k] = *(const PG8_LAS bf16x8*)(lds + PG8_SA(b, h) + aoff + m * (2 * USTR) + k * 64); } while (0)
; #define PG8_LDB(dst, b, h) do { _Pragma("unroll") for (int n = 0; n < 2; ++n) _Pragma("unroll") for (int k = 0; k < 2; ++k) dst[n][k] = *(const PG8_LAS bf16x8*)(lds + PG8_SB(b, h) + boff + n * (2 * USTR) + k * 64); } while (0)
; #define PG8_MMA(ai, bj, At, Bt) do { __builtin_amdgcn_s_setprio(1); _Pragma("unroll") for (int m = 0; m < 4; ++m) _Pragma("unroll") for (int n = 0; n < 2; ++n) _Pragma("unroll") for (int k = 0; k < 2; ++k) \
;         acc[ai][bj][m][n] = __builtin_amdgcn_mfma_f32_16x16x32_bf16(Bt[n][k], At[m][k], acc[ai][bj][m][n], 0, 0, 0); __builtin_amdgcn_s_setprio(0); } while (0)
; #define PG8_WAIT_V(n) asm volatile("s_waitcnt vmcnt(" #n ")" ::: "memory")
; #define PG8_WAIT_L(n) asm volatile("s_waitcnt lgkmcnt(" #n ")" ::: "memory")
; #define PG8_BAR __builtin_amdgcn_s_barrier()
; #define PG8_SCHED __builtin_amdgcn_sched_barrier(0)
; template <class Epi, class Sched, bool ALIGN_EPI, bool SP2>
; __device__ __forceinline__ void gemm_phase(PG8_LAS unsigned char* lds, const Gemm g, const Sched& S, const Epi& E, int wid) {
;     ...
;             const char* a2 = last ? nA : cA + (size_t)(t + 2) * kstep; const char* b2 = last ? nB : cB + (size_t)(t + 2) * kstep;
;     ...
;             if constexpr (SP2) {
;             PG8_LDB(B0, 0, 0); PG8_LDB(B1, 0, 1); PG8_SCHED; PG8_LDA(At, 0, 0); PG8_STAGE(PG8_SA(1, 1), a1 + hstepA, voffA);
;             PG8_WAIT_V(8); PG8_WAIT_L(0); PG8_BAR; PG8_MMA(0, 0, At, B0); PG8_MMA(0, 1, At, B1); PG8_BAR; PG8_SCHED;
;             PG8_LDA(At, 0, 1); PG8_STAGE(PG8_SB(0, 0), b2, voffB); PG8_STAGE(PG8_SB(0, 1), b2 + hstepB, voffB); PG8_STAGE(PG8_SA(0, 0), a2, voffA);
;             PG8_WAIT_V(8); PG8_WAIT_L(0); PG8_BAR; PG8_MMA(1, 0, At, B0); PG8_MMA(1, 1, At, B1); PG8_BAR; PG8_SCHED;
.Lhb_down:
	v_add_u32_e32 v52, 0x11000, v197
	v_add_u32_e32 v156, 0x15400, v197
	ds_read_b128 v[40:43], v52
	ds_read_b128 v[44:47], v52 offset:64
	ds_read_b128 v[48:51], v52 offset:2176
	ds_read_b128 v[52:55], v52 offset:2240
	ds_read_b128 v[144:147], v156
	ds_read_b128 v[148:151], v156 offset:64
	ds_read_b128 v[152:155], v156 offset:2176
	ds_read_b128 v[156:159], v156 offset:2240
	s_add_i32 s69, 0, 0x11000
	s_add_i32 s76, 0, 0x15400
	v_lshl_add_u64 v[198:199], s[38:39], 0, v[212:213]
	s_add_i32 m0, s0, 0xcc00
	ds_read_b128 v[160:163], v241
	ds_read_b128 v[164:167], v241 offset:64
	ds_read_b128 v[168:171], v241 offset:2176
	ds_read_b128 v[172:175], v241 offset:2240
	ds_read_b128 v[176:179], v241 offset:4352
	ds_read_b128 v[180:183], v241 offset:4416
	ds_read_b128 v[184:187], v241 offset:6528
	ds_read_b128 v[188:191], v241 offset:6592
	global_load_lds_dwordx4 v[198:199], off
	v_lshl_add_u64 v[198:199], s[38:39], 0, v[214:215]
	s_add_i32 m0, s0, 0xee00
	s_nop 0
	global_load_lds_dwordx4 v[198:199], off
	s_add_u32 s40, s38, 0xfff50080
	s_addc_u32 s41, s39, -1
	s_cmp_eq_u32 s68, 40
	s_cselect_b32 s43, s23, s41
	s_cselect_b32 s42, s22, s40
	s_cselect_b32 s41, s45, s27
	s_cselect_b32 s40, s44, s26
	s_waitcnt vmcnt(8)
	s_waitcnt lgkmcnt(0)
	s_barrier
	s_setprio 1
	s_waitcnt lgkmcnt(0)
	v_mfma_f32_16x16x32_bf16 v[132:135], v[40:43], v[160:163], 0
	v_mfma_f32_16x16x32_bf16 v[128:131], v[48:51], v[160:163], 0
	v_mfma_f32_16x16x32_bf16 v[124:127], v[40:43], v[168:171], 0
	v_mfma_f32_16x16x32_bf16 v[120:123], v[48:51], v[168:171], 0
	v_mfma_f32_16x16x32_bf16 v[108:111], v[40:43], v[176:179], 0
	v_mfma_f32_16x16x32_bf16 v[104:107], v[48:51], v[176:179], 0
	v_mfma_f32_16x16x32_bf16 v[92:95], v[40:43], v[184:187], 0
	v_mfma_f32_16x16x32_bf16 v[88:91], v[48:51], v[184:187], 0
	v_mfma_f32_16x16x32_bf16 v[132:135], v[44:47], v[164:167], v[132:135]
	v_mfma_f32_16x16x32_bf16 v[128:131], v[52:55], v[164:167], v[128:131]
	v_mfma_f32_16x16x32_bf16 v[124:127], v[44:47], v[172:175], v[124:127]
	v_mfma_f32_16x16x32_bf16 v[120:123], v[52:55], v[172:175], v[120:123]
	v_mfma_f32_16x16x32_bf16 v[108:111], v[44:47], v[180:183], v[108:111]
	v_mfma_f32_16x16x32_bf16 v[104:107], v[52:55], v[180:183], v[104:107]
	v_mfma_f32_16x16x32_bf16 v[92:95], v[44:47], v[188:191], v[92:95]
	v_mfma_f32_16x16x32_bf16 v[88:91], v[52:55], v[188:191], v[88:91]
	s_setprio 0
	s_setprio 1
	v_mfma_f32_16x16x32_bf16 v[140:143], v[144:147], v[160:163], 0
	v_mfma_f32_16x16x32_bf16 v[136:139], v[152:155], v[160:163], 0
	v_mfma_f32_16x16x32_bf16 v[116:119], v[144:147], v[168:171], 0
	v_mfma_f32_16x16x32_bf16 v[112:115], v[152:155], v[168:171], 0
	v_mfma_f32_16x16x32_bf16 v[100:103], v[144:147], v[176:179], 0
	v_mfma_f32_16x16x32_bf16 v[96:99], v[152:155], v[176:179], 0
	v_mfma_f32_16x16x32_bf16 v[84:87], v[144:147], v[184:187], 0
	v_mfma_f32_16x16x32_bf16 v[80:83], v[152:155], v[184:187], 0
	v_mfma_f32_16x16x32_bf16 v[140:143], v[148:151], v[164:167], v[140:143]
	v_mfma_f32_16x16x32_bf16 v[136:139], v[156:159], v[164:167], v[136:139]
	v_mfma_f32_16x16x32_bf16 v[116:119], v[148:151], v[172:175], v[116:119]
	v_mfma_f32_16x16x32_bf16 v[112:115], v[156:159], v[172:175], v[112:115]
	v_mfma_f32_16x16x32_bf16 v[100:103], v[148:151], v[180:183], v[100:103]
	v_mfma_f32_16x16x32_bf16 v[96:99], v[156:159], v[180:183], v[96:99]
	v_mfma_f32_16x16x32_bf16 v[84:87], v[148:151], v[188:191], v[84:87]
	v_mfma_f32_16x16x32_bf16 v[80:83], v[156:159], v[188:191], v[80:83]
	s_setprio 0
	s_barrier
	s_add_i32 s69, s69, s33
	v_lshl_add_u64 v[198:199], s[40:41], 0, v[208:209]
	s_mov_b32 m0, s69
	ds_read_b128 v[160:163], v241 offset:17408
	ds_read_b128 v[164:167], v241 offset:17472
	ds_read_b128 v[168:171], v241 offset:19584
	ds_read_b128 v[172:175], v241 offset:19648
	ds_read_b128 v[176:179], v241 offset:21760
	ds_read_b128 v[180:183], v241 offset:21824
	ds_read_b128 v[184:187], v241 offset:23936
	ds_read_b128 v[188:191], v241 offset:24000
	global_load_lds_dwordx4 v[198:199], off
	s_add_i32 m0, s69, 0x2200
	s_add_u32 s74, s40, 0xb0000
	v_lshl_add_u64 v[200:201], s[40:41], 0, v[210:211]
	s_addc_u32 s75, s41, 0
	s_add_i32 s69, s76, s33
	global_load_lds_dwordx4 v[200:201], off
	v_lshl_add_u64 v[216:217], s[74:75], 0, v[208:209]
	s_mov_b32 m0, s69
	v_lshl_add_u64 v[218:219], s[42:43], 0, v[210:211]
	global_load_lds_dwordx4 v[216:217], off
	v_lshl_add_u64 v[216:217], s[74:75], 0, v[210:211]
	s_add_i32 m0, s69, 0x2200
	s_nop 0
	global_load_lds_dwordx4 v[216:217], off
	v_lshl_add_u64 v[216:217], s[42:43], 0, v[208:209]
	s_mov_b32 m0, s0
	s_nop 0
	global_load_lds_dwordx4 v[216:217], off
	s_mov_b32 m0, s5
	s_nop 0
	global_load_lds_dwordx4 v[218:219], off
	s_waitcnt vmcnt(8)
	s_waitcnt lgkmcnt(0)
	s_barrier
; #define PG8_STAGE(bufoff, gbase, voff) do { _Pragma("unroll") for (int _i = 0; _i < 2; ++_i) \
;         __builtin_amdgcn_global_load_lds((const unsigned*)((const char*)(gbase) + (voff)[_i]), (PG8_LAS unsigned*)(lds + (bufoff) + ldsw + _i * (8 * USTR)), 16, 0, 0); } while (0)
; #define PG8_LDA(dst, b, h) do { _Pragma("unroll") for (int m = 0; m < 4; ++m) _Pragma("unroll") for (int k = 0; k < 2; ++k) dst[m][k] = *(const PG8_LAS bf16x8*)(lds + PG8_SA(b, h) + aoff + m * (2 * USTR) + k * 64); } while (0)
; #define PG8_LDB(dst, b, h) do { _Pragma("unroll") for (int n = 0; n < 2; ++n) _Pragma("unroll") for (int k = 0; k < 2; ++k) dst[n][k] = *(const PG8_LAS bf16x8*)(lds + PG8_SB(b, h) + boff + n * (2 * USTR) + k * 64); } while (0)
; #define PG8_MMA(ai, bj, At, Bt) do { __builtin_amdgcn_s_setprio(1); _Pragma("unroll") for (int m = 0; m < 4; ++m) _Pragma("unroll") for (int n = 0; n < 2; ++n) _Pragma("unroll") for (int k = 0; k < 2; ++k) \
;         acc[ai][bj][m][n] = __builtin_amdgcn_mfma_f32_16x16x32_bf16(Bt[n][k], At[m][k], acc[ai][bj][m][n], 0, 0, 0); __builtin_amdgcn_s_setprio(0); } while (0)
; #define PG8_WAIT_V(n) asm volatile("s_waitcnt vmcnt(" #n ")" ::: "memory")
; #define PG8_WAIT_L(n) asm volatile("s_waitcnt lgkmcnt(" #n ")" ::: "memory")
; #define PG8_BAR __builtin_amdgcn_s_barrier()
; #define PG8_SCHED __builtin_amdgcn_sched_barrier(0)
; template <class Epi, class Sched, bool ALIGN_EPI, bool SP2>
; __device__ __forceinline__ void gemm_phase(PG8_LAS unsigned char* lds, const Gemm g, const Sched& S, const Epi& E, int wid) {
;     ...
;             PG8_WAIT_V(8); PG8_WAIT_L(0); PG8_BAR; PG8_MMA(1, 0, At, B0); PG8_MMA(1, 1, At, B1); PG8_BAR; PG8_SCHED;
;             PG8_LDB(B0, 1, 0); PG8_LDB(B1, 1, 1); PG8_SCHED; PG8_LDA(At, 1, 0); PG8_STAGE(PG8_SA(0, 1), a2 + hstepA, voffA);
;             PG8_WAIT_V(8); PG8_WAIT_L(0); PG8_BAR; PG8_MMA(0, 0, At, B0); PG8_MMA(0, 1, At, B1); PG8_BAR; PG8_SCHED;
	s_setprio 1
	s_waitcnt lgkmcnt(0)
	v_mfma_f32_16x16x32_bf16 v[76:79], v[40:43], v[160:163], 0
	v_mfma_f32_16x16x32_bf16 v[72:75], v[48:51], v[160:163], 0
	v_mfma_f32_16x16x32_bf16 v[60:63], v[40:43], v[168:171], 0
	v_mfma_f32_16x16x32_bf16 v[56:59], v[48:51], v[168:171], 0
	v_mfma_f32_16x16x32_bf16 v[24:27], v[40:43], v[176:179], 0
	v_mfma_f32_16x16x32_bf16 v[28:31], v[48:51], v[176:179], 0
	v_mfma_f32_16x16x32_bf16 v[8:11], v[40:43], v[184:187], 0
	v_mfma_f32_16x16x32_bf16 v[12:15], v[48:51], v[184:187], 0
	v_mfma_f32_16x16x32_bf16 v[76:79], v[44:47], v[164:167], v[76:79]
	v_mfma_f32_16x16x32_bf16 v[72:75], v[52:55], v[164:167], v[72:75]
	v_mfma_f32_16x16x32_bf16 v[60:63], v[44:47], v[172:175], v[60:63]
	v_mfma_f32_16x16x32_bf16 v[56:59], v[52:55], v[172:175], v[56:59]
	v_mfma_f32_16x16x32_bf16 v[24:27], v[44:47], v[180:183], v[24:27]
	v_mfma_f32_16x16x32_bf16 v[28:31], v[52:55], v[180:183], v[28:31]
	v_mfma_f32_16x16x32_bf16 v[8:11], v[44:47], v[188:191], v[8:11]
	v_mfma_f32_16x16x32_bf16 v[12:15], v[52:55], v[188:191], v[12:15]
	s_setprio 0
	s_setprio 1
	v_mfma_f32_16x16x32_bf16 v[36:39], v[144:147], v[168:171], 0
	v_mfma_f32_16x16x32_bf16 v[32:35], v[152:155], v[168:171], 0
	v_mfma_f32_16x16x32_bf16 v[20:23], v[144:147], v[176:179], 0
	v_mfma_f32_16x16x32_bf16 v[16:19], v[152:155], v[176:179], 0
	v_mfma_f32_16x16x32_bf16 v[4:7], v[144:147], v[184:187], 0
	v_mfma_f32_16x16x32_bf16 v[0:3], v[152:155], v[184:187], 0
	v_mfma_f32_16x16x32_bf16 v[40:43], v[144:147], v[160:163], 0
	v_mfma_f32_16x16x32_bf16 v[44:47], v[152:155], v[160:163], 0
	v_mfma_f32_16x16x32_bf16 v[36:39], v[148:151], v[172:175], v[36:39]
	v_mfma_f32_16x16x32_bf16 v[32:35], v[156:159], v[172:175], v[32:35]
	v_mfma_f32_16x16x32_bf16 v[20:23], v[148:151], v[180:183], v[20:23]
	v_mfma_f32_16x16x32_bf16 v[16:19], v[156:159], v[180:183], v[16:19]
	v_mfma_f32_16x16x32_bf16 v[4:7], v[148:151], v[188:191], v[4:7]
	v_mfma_f32_16x16x32_bf16 v[0:3], v[156:159], v[188:191], v[0:3]
	v_mfma_f32_16x16x32_bf16 v[40:43], v[148:151], v[164:167], v[40:43]
	v_mfma_f32_16x16x32_bf16 v[44:47], v[156:159], v[164:167], v[44:47]
	s_setprio 0
	s_barrier
	v_add_u32_e32 v68, 0x19800, v197
	v_add_u32_e32 v156, 0x1dc00, v197
	ds_read_b128 v[48:51], v68
	ds_read_b128 v[52:55], v68 offset:64
	ds_read_b128 v[64:67], v68 offset:2176
	ds_read_b128 v[68:71], v68 offset:2240
	ds_read_b128 v[144:147], v156
	ds_read_b128 v[148:151], v156 offset:64
	ds_read_b128 v[152:155], v156 offset:2176
	ds_read_b128 v[156:159], v156 offset:2240
	s_add_i32 s69, 0, 0x19800
	s_add_i32 s74, 0, 0x1dc00
	s_add_u32 s42, s42, 0xb0000
	s_addc_u32 s43, s43, 0
	s_mov_b32 m0, s29
	v_lshl_add_u64 v[220:221], s[42:43], 0, v[208:209]
	ds_read_b128 v[160:163], v241 offset:34816
	ds_read_b128 v[164:167], v241 offset:34880
	ds_read_b128 v[168:171], v241 offset:36992
	ds_read_b128 v[172:175], v241 offset:37056
	ds_read_b128 v[176:179], v241 offset:39168
	ds_read_b128 v[180:183], v241 offset:39232
	ds_read_b128 v[184:187], v241 offset:41344
	ds_read_b128 v[188:191], v241 offset:41408
	global_load_lds_dwordx4 v[220:221], off
	v_lshl_add_u64 v[220:221], s[42:43], 0, v[210:211]
	s_mov_b32 m0, s56
	s_nop 0
	global_load_lds_dwordx4 v[220:221], off
	s_waitcnt vmcnt(8)
	s_waitcnt lgkmcnt(0)
	s_barrier
	s_setprio 1
	s_waitcnt lgkmcnt(0)
	v_mfma_f32_16x16x32_bf16 v[132:135], v[48:51], v[160:163], v[132:135]
	v_mfma_f32_16x16x32_bf16 v[128:131], v[64:67], v[160:163], v[128:131]
	v_mfma_f32_16x16x32_bf16 v[124:127], v[48:51], v[168:171], v[124:127]
	v_mfma_f32_16x16x32_bf16 v[120:123], v[64:67], v[168:171], v[120:123]
	v_mfma_f32_16x16x32_bf16 v[108:111], v[48:51], v[176:179], v[108:111]
	v_mfma_f32_16x16x32_bf16 v[104:107], v[64:67], v[176:179], v[104:107]
	v_mfma_f32_16x16x32_bf16 v[92:95], v[48:51], v[184:187], v[92:95]
	v_mfma_f32_16x16x32_bf16 v[88:91], v[64:67], v[184:187], v[88:91]
	v_mfma_f32_16x16x32_bf16 v[132:135], v[52:55], v[164:167], v[132:135]
	v_mfma_f32_16x16x32_bf16 v[128:131], v[68:71], v[164:167], v[128:131]
	v_mfma_f32_16x16x32_bf16 v[124:127], v[52:55], v[172:175], v[124:127]
	v_mfma_f32_16x16x32_bf16 v[120:123], v[68:71], v[172:175], v[120:123]
	v_mfma_f32_16x16x32_bf16 v[108:111], v[52:55], v[180:183], v[108:111]
	v_mfma_f32_16x16x32_bf16 v[104:107], v[68:71], v[180:183], v[104:107]
	v_mfma_f32_16x16x32_bf16 v[92:95], v[52:55], v[188:191], v[92:95]
	v_mfma_f32_16x16x32_bf16 v[88:91], v[68:71], v[188:191], v[88:91]
	s_setprio 0
	s_setprio 1
	v_mfma_f32_16x16x32_bf16 v[140:143], v[144:147], v[160:163], v[140:143]
	v_mfma_f32_16x16x32_bf16 v[136:139], v[152:155], v[160:163], v[136:139]
	v_mfma_f32_16x16x32_bf16 v[116:119], v[144:147], v[168:171], v[116:119]
	v_mfma_f32_16x16x32_bf16 v[112:115], v[152:155], v[168:171], v[112:115]
	v_mfma_f32_16x16x32_bf16 v[100:103], v[144:147], v[176:179], v[100:103]
	v_mfma_f32_16x16x32_bf16 v[96:99], v[152:155], v[176:179], v[96:99]
	v_mfma_f32_16x16x32_bf16 v[84:87], v[144:147], v[184:187], v[84:87]
	v_mfma_f32_16x16x32_bf16 v[80:83], v[152:155], v[184:187], v[80:83]
	v_mfma_f32_16x16x32_bf16 v[140:143], v[148:151], v[164:167], v[140:143]
	v_mfma_f32_16x16x32_bf16 v[136:139], v[156:159], v[164:167], v[136:139]
	v_mfma_f32_16x16x32_bf16 v[116:119], v[148:151], v[172:175], v[116:119]
	v_mfma_f32_16x16x32_bf16 v[112:115], v[156:159], v[172:175], v[112:115]
	v_mfma_f32_16x16x32_bf16 v[100:103], v[148:151], v[180:183], v[100:103]
	v_mfma_f32_16x16x32_bf16 v[96:99], v[156:159], v[180:183], v[96:99]
	v_mfma_f32_16x16x32_bf16 v[84:87], v[148:151], v[188:191], v[84:87]
	v_mfma_f32_16x16x32_bf16 v[80:83], v[156:159], v[188:191], v[80:83]
	s_setprio 0
	s_barrier
; #define PG8_STAGE(bufoff, gbase, voff) do { _Pragma("unroll") for (int _i = 0; _i < 2; ++_i) \
;         __builtin_amdgcn_global_load_lds((const unsigned*)((const char*)(gbase) + (voff)[_i]), (PG8_LAS unsigned*)(lds + (bufoff) + ldsw + _i * (8 * USTR)), 16, 0, 0); } while (0)
; #define PG8_LDA(dst, b, h) do { _Pragma("unroll") for (int m = 0; m < 4; ++m) _Pragma("unroll") for (int k = 0; k < 2; ++k) dst[m][k] = *(const PG8_LAS bf16x8*)(lds + PG8_SA(b, h) + aoff + m * (2 * USTR) + k * 64); } while (0)
; #define PG8_LDB(dst, b, h) do { _Pragma("unroll") for (int n = 0; n < 2; ++n) _Pragma("unroll") for (int k = 0; k < 2; ++k) dst[n][k] = *(const PG8_LAS bf16x8*)(lds + PG8_SB(b, h) + boff + n * (2 * USTR) + k * 64); } while (0)
; #define PG8_MMA(ai, bj, At, Bt) do { __builtin_amdgcn_s_setprio(1); _Pragma("unroll") for (int m = 0; m < 4; ++m) _Pragma("unroll") for (int n = 0; n < 2; ++n) _Pragma("unroll") for (int k = 0; k < 2; ++k) \
;         acc[ai][bj][m][n] = __builtin_amdgcn_mfma_f32_16x16x32_bf16(Bt[n][k], At[m][k], acc[ai][bj][m][n], 0, 0, 0); __builtin_amdgcn_s_setprio(0); } while (0)
; #define PG8_WAIT_V(n) asm volatile("s_waitcnt vmcnt(" #n ")" ::: "memory")
; #define PG8_WAIT_L(n) asm volatile("s_waitcnt lgkmcnt(" #n ")" ::: "memory")
; #define PG8_BAR __builtin_amdgcn_s_barrier()
; #define PG8_SCHED __builtin_amdgcn_sched_barrier(0)
; template <class Epi, class Sched, bool ALIGN_EPI, bool SP2>
; __device__ __forceinline__ void gemm_phase(PG8_LAS unsigned char* lds, const Gemm g, const Sched& S, const Epi& E, int wid) {
;     ...
;             PG8_LDB(B0, 0, 0); PG8_LDB(B1, 0, 1); PG8_SCHED; PG8_LDA(At, 0, 0); PG8_STAGE(PG8_SA(1, 1), a1 + hstepA, voffA);
;             PG8_WAIT_V(8); PG8_WAIT_L(0); PG8_BAR; PG8_MMA(0, 0, At, B0); PG8_MMA(0, 1, At, B1); PG8_BAR; PG8_SCHED;
;     ...
;             PG8_LDA(At, 1, 1); PG8_STAGE(PG8_SB(1, 0), b3, voffB); PG8_STAGE(PG8_SB(1, 1), b3 + hstepB, voffB); PG8_STAGE(PG8_SA(1, 0), a3, voffA);
;             PG8_WAIT_V(8); PG8_WAIT_L(0); PG8_BAR; PG8_MMA(1, 0, At, B0); PG8_MMA(1, 1, At, B1); PG8_BAR; PG8_SCHED;
	s_add_i32 s42, s69, s33
	v_lshl_add_u64 v[198:199], v[198:199], 0, s[6:7]
	s_mov_b32 m0, s42
	ds_read_b128 v[160:163], v241 offset:52224
	ds_read_b128 v[164:167], v241 offset:52288
	ds_read_b128 v[168:171], v241 offset:54400
	ds_read_b128 v[172:175], v241 offset:54464
	ds_read_b128 v[176:179], v241 offset:56576
	ds_read_b128 v[180:183], v241 offset:56640
	ds_read_b128 v[184:187], v241 offset:58752
	ds_read_b128 v[188:191], v241 offset:58816
	global_load_lds_dwordx4 v[198:199], off
	s_add_i32 m0, s42, 0x2200
	s_add_u32 s40, s40, 0xb0080
	v_lshl_add_u64 v[198:199], v[200:201], 0, s[6:7]
	s_addc_u32 s41, s41, 0
	s_add_i32 s42, s74, s33
	global_load_lds_dwordx4 v[198:199], off
	v_lshl_add_u64 v[198:199], s[40:41], 0, v[208:209]
	s_mov_b32 m0, s42
	s_nop 0
	global_load_lds_dwordx4 v[198:199], off
	v_lshl_add_u64 v[198:199], s[40:41], 0, v[210:211]
	s_add_i32 m0, s42, 0x2200
	s_nop 0
	global_load_lds_dwordx4 v[198:199], off
	v_lshl_add_u64 v[198:199], v[216:217], 0, s[6:7]
	s_mov_b32 m0, s57
	s_nop 0
	global_load_lds_dwordx4 v[198:199], off
	v_lshl_add_u64 v[198:199], v[218:219], 0, s[6:7]
	s_mov_b32 m0, s70
	s_nop 0
	global_load_lds_dwordx4 v[198:199], off
	s_add_i32 s68, s68, 2
	s_add_u32 s38, s38, 0x100
	s_addc_u32 s39, s39, 0
	s_add_u32 s26, s26, 0x100
	s_addc_u32 s27, s27, 0
	s_waitcnt vmcnt(8)
	s_waitcnt lgkmcnt(0)
	s_barrier
	s_setprio 1
	s_waitcnt lgkmcnt(0)
	v_mfma_f32_16x16x32_bf16 v[76:79], v[48:51], v[160:163], v[76:79]
	v_mfma_f32_16x16x32_bf16 v[72:75], v[64:67], v[160:163], v[72:75]
	v_mfma_f32_16x16x32_bf16 v[60:63], v[48:51], v[168:171], v[60:63]
	v_mfma_f32_16x16x32_bf16 v[56:59], v[64:67], v[168:171], v[56:59]
	v_mfma_f32_16x16x32_bf16 v[24:27], v[48:51], v[176:179], v[24:27]
	v_mfma_f32_16x16x32_bf16 v[28:31], v[64:67], v[176:179], v[28:31]
	v_mfma_f32_16x16x32_bf16 v[8:11], v[48:51], v[184:187], v[8:11]
	v_mfma_f32_16x16x32_bf16 v[12:15], v[64:67], v[184:187], v[12:15]
	v_mfma_f32_16x16x32_bf16 v[76:79], v[52:55], v[164:167], v[76:79]
	v_mfma_f32_16x16x32_bf16 v[72:75], v[68:71], v[164:167], v[72:75]
	v_mfma_f32_16x16x32_bf16 v[60:63], v[52:55], v[172:175], v[60:63]
	v_mfma_f32_16x16x32_bf16 v[56:59], v[68:71], v[172:175], v[56:59]
	v_mfma_f32_16x16x32_bf16 v[24:27], v[52:55], v[180:183], v[24:27]
	v_mfma_f32_16x16x32_bf16 v[28:31], v[68:71], v[180:183], v[28:31]
	v_mfma_f32_16x16x32_bf16 v[8:11], v[52:55], v[188:191], v[8:11]
	v_mfma_f32_16x16x32_bf16 v[12:15], v[68:71], v[188:191], v[12:15]
	s_setprio 0
	s_setprio 1
	v_mfma_f32_16x16x32_bf16 v[40:43], v[144:147], v[160:163], v[40:43]
	v_mfma_f32_16x16x32_bf16 v[68:71], v[148:151], v[164:167], v[40:43]
	v_mfma_f32_16x16x32_bf16 v[40:43], v[152:155], v[160:163], v[44:47]
	v_mfma_f32_16x16x32_bf16 v[36:39], v[144:147], v[168:171], v[36:39]
	v_mfma_f32_16x16x32_bf16 v[32:35], v[152:155], v[168:171], v[32:35]
	v_mfma_f32_16x16x32_bf16 v[20:23], v[144:147], v[176:179], v[20:23]
	v_mfma_f32_16x16x32_bf16 v[16:19], v[152:155], v[176:179], v[16:19]
	v_mfma_f32_16x16x32_bf16 v[4:7], v[144:147], v[184:187], v[4:7]
	v_mfma_f32_16x16x32_bf16 v[0:3], v[152:155], v[184:187], v[0:3]
	v_mfma_f32_16x16x32_bf16 v[64:67], v[156:159], v[164:167], v[40:43]
	v_mfma_f32_16x16x32_bf16 v[36:39], v[148:151], v[172:175], v[36:39]
	v_mfma_f32_16x16x32_bf16 v[32:35], v[156:159], v[172:175], v[32:35]
	v_mfma_f32_16x16x32_bf16 v[20:23], v[148:151], v[180:183], v[20:23]
	v_mfma_f32_16x16x32_bf16 v[16:19], v[156:159], v[180:183], v[16:19]
	v_mfma_f32_16x16x32_bf16 v[4:7], v[148:151], v[188:191], v[4:7]
	v_mfma_f32_16x16x32_bf16 v[0:3], v[156:159], v[188:191], v[0:3]
	s_setprio 0
	s_barrier
	s_cmp_gt_u32 s68, 41
.LBB0_290:
	v_add_u32_e32 v52, 0x11000, v197
	v_add_u32_e32 v156, 0x15400, v197
	ds_read_b128 v[40:43], v52
	ds_read_b128 v[44:47], v52 offset:64
	ds_read_b128 v[48:51], v52 offset:2176
	ds_read_b128 v[52:55], v52 offset:2240
	ds_read_b128 v[144:147], v156
	ds_read_b128 v[148:151], v156 offset:64
	ds_read_b128 v[152:155], v156 offset:2176
	ds_read_b128 v[156:159], v156 offset:2240
	s_add_i32 s69, 0, 0x11000
	s_add_i32 s76, 0, 0x15400
	v_lshl_add_u64 v[198:199], s[38:39], 0, v[212:213]
	s_add_i32 m0, s0, 0xcc00
	ds_read_b128 v[160:163], v241
	ds_read_b128 v[164:167], v241 offset:64
	ds_read_b128 v[168:171], v241 offset:2176
	ds_read_b128 v[172:175], v241 offset:2240
	ds_read_b128 v[176:179], v241 offset:4352
	ds_read_b128 v[180:183], v241 offset:4416
	ds_read_b128 v[184:187], v241 offset:6528
	ds_read_b128 v[188:191], v241 offset:6592
	global_load_lds_dwordx4 v[198:199], off
	v_lshl_add_u64 v[198:199], s[38:39], 0, v[214:215]
	s_add_i32 m0, s0, 0xee00
	s_nop 0
	global_load_lds_dwordx4 v[198:199], off
	s_add_u32 s40, s38, 0xfff50080
	s_addc_u32 s41, s39, -1
	s_cmp_eq_u32 s68, 40
	s_cselect_b32 s43, s23, s41
	s_cselect_b32 s42, s22, s40
	s_cselect_b32 s41, s45, s27
	s_cselect_b32 s40, s44, s26
	s_waitcnt vmcnt(8)
	s_waitcnt lgkmcnt(0)
	s_barrier
; #define PG8_STAGE(bufoff, gbase, voff) do { _Pragma("unroll") for (int _i = 0; _i < 2; ++_i) \
;         __builtin_amdgcn_global_load_lds((const unsigned*)((const char*)(gbase) + (voff)[_i]), (PG8_LAS unsigned*)(lds + (bufoff) + ldsw + _i * (8 * USTR)), 16, 0, 0); } while (0)
; #define PG8_LDA(dst, b, h) do { _Pragma("unroll") for (int m = 0; m < 4; ++m) _Pragma("unroll") for (int k = 0; k < 2; ++k) dst[m][k] = *(const PG8_LAS bf16x8*)(lds + PG8_SA(b, h) + aoff + m * (2 * USTR) + k * 64); } while (0)
; #define PG8_MMA(ai, bj, At, Bt) do { __builtin_amdgcn_s_setprio(1); _Pragma("unroll") for (int m = 0; m < 4; ++m) _Pragma("unroll") for (int n = 0; n < 2; ++n) _Pragma("unroll") for (int k = 0; k < 2; ++k) \
;         acc[ai][bj][m][n] = __builtin_amdgcn_mfma_f32_16x16x32_bf16(Bt[n][k], At[m][k], acc[ai][bj][m][n], 0, 0, 0); __builtin_amdgcn_s_setprio(0); } while (0)
; #define PG8_WAIT_V(n) asm volatile("s_waitcnt vmcnt(" #n ")" ::: "memory")
; #define PG8_WAIT_L(n) asm volatile("s_waitcnt lgkmcnt(" #n ")" ::: "memory")
; #define PG8_BAR __builtin_amdgcn_s_barrier()
; #define PG8_SCHED __builtin_amdgcn_sched_barrier(0)
; template <class Epi, class Sched, bool ALIGN_EPI, bool SP2>
; __device__ __forceinline__ void gemm_phase(PG8_LAS unsigned char* lds, const Gemm g, const Sched& S, const Epi& E, int wid) {
;     ...
;             PG8_WAIT_V(8); PG8_WAIT_L(0); PG8_BAR; PG8_MMA(0, 0, At, B0); PG8_MMA(0, 1, At, B1); PG8_BAR; PG8_SCHED;
;             PG8_LDA(At, 0, 1); PG8_STAGE(PG8_SB(0, 0), b2, voffB); PG8_STAGE(PG8_SB(0, 1), b2 + hstepB, voffB); PG8_STAGE(PG8_SA(0, 0), a2, voffA);
;             PG8_WAIT_V(8); PG8_WAIT_L(0); PG8_BAR; PG8_MMA(1, 0, At, B0); PG8_MMA(1, 1, At, B1); PG8_BAR; PG8_SCHED;
	s_setprio 1
	s_waitcnt lgkmcnt(0)
	v_mfma_f32_16x16x32_bf16 v[132:135], v[40:43], v[160:163], v[132:135]
	v_mfma_f32_16x16x32_bf16 v[128:131], v[48:51], v[160:163], v[128:131]
	v_mfma_f32_16x16x32_bf16 v[124:127], v[40:43], v[168:171], v[124:127]
	v_mfma_f32_16x16x32_bf16 v[120:123], v[48:51], v[168:171], v[120:123]
	v_mfma_f32_16x16x32_bf16 v[108:111], v[40:43], v[176:179], v[108:111]
	v_mfma_f32_16x16x32_bf16 v[104:107], v[48:51], v[176:179], v[104:107]
	v_mfma_f32_16x16x32_bf16 v[92:95], v[40:43], v[184:187], v[92:95]
	v_mfma_f32_16x16x32_bf16 v[88:91], v[48:51], v[184:187], v[88:91]
	v_mfma_f32_16x16x32_bf16 v[132:135], v[44:47], v[164:167], v[132:135]
	v_mfma_f32_16x16x32_bf16 v[128:131], v[52:55], v[164:167], v[128:131]
	v_mfma_f32_16x16x32_bf16 v[124:127], v[44:47], v[172:175], v[124:127]
	v_mfma_f32_16x16x32_bf16 v[120:123], v[52:55], v[172:175], v[120:123]
	v_mfma_f32_16x16x32_bf16 v[108:111], v[44:47], v[180:183], v[108:111]
	v_mfma_f32_16x16x32_bf16 v[104:107], v[52:55], v[180:183], v[104:107]
	v_mfma_f32_16x16x32_bf16 v[92:95], v[44:47], v[188:191], v[92:95]
	v_mfma_f32_16x16x32_bf16 v[88:91], v[52:55], v[188:191], v[88:91]
	s_setprio 0
	s_setprio 1
	v_mfma_f32_16x16x32_bf16 v[140:143], v[144:147], v[160:163], v[140:143]
	v_mfma_f32_16x16x32_bf16 v[136:139], v[152:155], v[160:163], v[136:139]
	v_mfma_f32_16x16x32_bf16 v[116:119], v[144:147], v[168:171], v[116:119]
	v_mfma_f32_16x16x32_bf16 v[112:115], v[152:155], v[168:171], v[112:115]
	v_mfma_f32_16x16x32_bf16 v[100:103], v[144:147], v[176:179], v[100:103]
	v_mfma_f32_16x16x32_bf16 v[96:99], v[152:155], v[176:179], v[96:99]
	v_mfma_f32_16x16x32_bf16 v[84:87], v[144:147], v[184:187], v[84:87]
	v_mfma_f32_16x16x32_bf16 v[80:83], v[152:155], v[184:187], v[80:83]
	v_mfma_f32_16x16x32_bf16 v[140:143], v[148:151], v[164:167], v[140:143]
	v_mfma_f32_16x16x32_bf16 v[136:139], v[156:159], v[164:167], v[136:139]
	v_mfma_f32_16x16x32_bf16 v[116:119], v[148:151], v[172:175], v[116:119]
	v_mfma_f32_16x16x32_bf16 v[112:115], v[156:159], v[172:175], v[112:115]
	v_mfma_f32_16x16x32_bf16 v[100:103], v[148:151], v[180:183], v[100:103]
	v_mfma_f32_16x16x32_bf16 v[96:99], v[156:159], v[180:183], v[96:99]
	v_mfma_f32_16x16x32_bf16 v[84:87], v[148:151], v[188:191], v[84:87]
	v_mfma_f32_16x16x32_bf16 v[80:83], v[156:159], v[188:191], v[80:83]
	s_setprio 0
	s_barrier
	s_add_i32 s69, s69, s33
	v_lshl_add_u64 v[198:199], s[40:41], 0, v[208:209]
	s_mov_b32 m0, s69
	ds_read_b128 v[160:163], v241 offset:17408
	ds_read_b128 v[164:167], v241 offset:17472
	ds_read_b128 v[168:171], v241 offset:19584
	ds_read_b128 v[172:175], v241 offset:19648
	ds_read_b128 v[176:179], v241 offset:21760
	ds_read_b128 v[180:183], v241 offset:21824
	ds_read_b128 v[184:187], v241 offset:23936
	ds_read_b128 v[188:191], v241 offset:24000
	global_load_lds_dwordx4 v[198:199], off
	s_add_i32 m0, s69, 0x2200
	s_add_u32 s74, s40, 0xb0000
	v_lshl_add_u64 v[200:201], s[40:41], 0, v[210:211]
	s_addc_u32 s75, s41, 0
	s_add_i32 s69, s76, s33
	global_load_lds_dwordx4 v[200:201], off
	v_lshl_add_u64 v[216:217], s[74:75], 0, v[208:209]
	s_mov_b32 m0, s69
	v_lshl_add_u64 v[218:219], s[42:43], 0, v[210:211]
	global_load_lds_dwordx4 v[216:217], off
	v_lshl_add_u64 v[216:217], s[74:75], 0, v[210:211]
	s_add_i32 m0, s69, 0x2200
	s_nop 0
	global_load_lds_dwordx4 v[216:217], off
	v_lshl_add_u64 v[216:217], s[42:43], 0, v[208:209]
	s_mov_b32 m0, s0
	s_nop 0
	global_load_lds_dwordx4 v[216:217], off
	s_mov_b32 m0, s5
	s_nop 0
	global_load_lds_dwordx4 v[218:219], off
	s_waitcnt vmcnt(8)
	s_waitcnt lgkmcnt(0)
	s_barrier
	s_setprio 1
	s_waitcnt lgkmcnt(0)
	v_mfma_f32_16x16x32_bf16 v[76:79], v[40:43], v[160:163], v[76:79]
	v_mfma_f32_16x16x32_bf16 v[72:75], v[48:51], v[160:163], v[72:75]
	v_mfma_f32_16x16x32_bf16 v[60:63], v[40:43], v[168:171], v[60:63]
	v_mfma_f32_16x16x32_bf16 v[56:59], v[48:51], v[168:171], v[56:59]
	v_mfma_f32_16x16x32_bf16 v[24:27], v[40:43], v[176:179], v[24:27]
	v_mfma_f32_16x16x32_bf16 v[28:31], v[48:51], v[176:179], v[28:31]
	v_mfma_f32_16x16x32_bf16 v[8:11], v[40:43], v[184:187], v[8:11]
	v_mfma_f32_16x16x32_bf16 v[12:15], v[48:51], v[184:187], v[12:15]
	v_mfma_f32_16x16x32_bf16 v[76:79], v[44:47], v[164:167], v[76:79]
	v_mfma_f32_16x16x32_bf16 v[72:75], v[52:55], v[164:167], v[72:75]
	v_mfma_f32_16x16x32_bf16 v[60:63], v[44:47], v[172:175], v[60:63]
	v_mfma_f32_16x16x32_bf16 v[56:59], v[52:55], v[172:175], v[56:59]
	v_mfma_f32_16x16x32_bf16 v[24:27], v[44:47], v[180:183], v[24:27]
	v_mfma_f32_16x16x32_bf16 v[28:31], v[52:55], v[180:183], v[28:31]
	v_mfma_f32_16x16x32_bf16 v[8:11], v[44:47], v[188:191], v[8:11]
	v_mfma_f32_16x16x32_bf16 v[12:15], v[52:55], v[188:191], v[12:15]
	s_setprio 0
	s_setprio 1
	v_mfma_f32_16x16x32_bf16 v[36:39], v[144:147], v[168:171], v[36:39]
	v_mfma_f32_16x16x32_bf16 v[32:35], v[152:155], v[168:171], v[32:35]
	v_mfma_f32_16x16x32_bf16 v[20:23], v[144:147], v[176:179], v[20:23]
	v_mfma_f32_16x16x32_bf16 v[16:19], v[152:155], v[176:179], v[16:19]
	v_mfma_f32_16x16x32_bf16 v[4:7], v[144:147], v[184:187], v[4:7]
	v_mfma_f32_16x16x32_bf16 v[0:3], v[152:155], v[184:187], v[0:3]
	v_mfma_f32_16x16x32_bf16 v[40:43], v[144:147], v[160:163], v[68:71]
	v_mfma_f32_16x16x32_bf16 v[44:47], v[152:155], v[160:163], v[64:67]
	v_mfma_f32_16x16x32_bf16 v[36:39], v[148:151], v[172:175], v[36:39]
	v_mfma_f32_16x16x32_bf16 v[32:35], v[156:159], v[172:175], v[32:35]
	v_mfma_f32_16x16x32_bf16 v[20:23], v[148:151], v[180:183], v[20:23]
	v_mfma_f32_16x16x32_bf16 v[16:19], v[156:159], v[180:183], v[16:19]
	v_mfma_f32_16x16x32_bf16 v[4:7], v[148:151], v[188:191], v[4:7]
	v_mfma_f32_16x16x32_bf16 v[0:3], v[156:159], v[188:191], v[0:3]
	v_mfma_f32_16x16x32_bf16 v[40:43], v[148:151], v[164:167], v[40:43]
	v_mfma_f32_16x16x32_bf16 v[44:47], v[156:159], v[164:167], v[44:47]
	s_setprio 0
	s_barrier
; #define PG8_STAGE(bufoff, gbase, voff) do { _Pragma("unroll") for (int _i = 0; _i < 2; ++_i) \
;         __builtin_amdgcn_global_load_lds((const unsigned*)((const char*)(gbase) + (voff)[_i]), (PG8_LAS unsigned*)(lds + (bufoff) + ldsw + _i * (8 * USTR)), 16, 0, 0); } while (0)
; #define PG8_LDA(dst, b, h) do { _Pragma("unroll") for (int m = 0; m < 4; ++m) _Pragma("unroll") for (int k = 0; k < 2; ++k) dst[m][k] = *(const PG8_LAS bf16x8*)(lds + PG8_SA(b, h) + aoff + m * (2 * USTR) + k * 64); } while (0)
; #define PG8_LDB(dst, b, h) do { _Pragma("unroll") for (int n = 0; n < 2; ++n) _Pragma("unroll") for (int k = 0; k < 2; ++k) dst[n][k] = *(const PG8_LAS bf16x8*)(lds + PG8_SB(b, h) + boff + n * (2 * USTR) + k * 64); } while (0)
; #define PG8_MMA(ai, bj, At, Bt) do { __builtin_amdgcn_s_setprio(1); _Pragma("unroll") for (int m = 0; m < 4; ++m) _Pragma("unroll") for (int n = 0; n < 2; ++n) _Pragma("unroll") for (int k = 0; k < 2; ++k) \
;         acc[ai][bj][m][n] = __builtin_amdgcn_mfma_f32_16x16x32_bf16(Bt[n][k], At[m][k], acc[ai][bj][m][n], 0, 0, 0); __builtin_amdgcn_s_setprio(0); } while (0)
; #define PG8_WAIT_V(n) asm volatile("s_waitcnt vmcnt(" #n ")" ::: "memory")
; #define PG8_WAIT_L(n) asm volatile("s_waitcnt lgkmcnt(" #n ")" ::: "memory")
; #define PG8_BAR __builtin_amdgcn_s_barrier()
; #define PG8_SCHED __builtin_amdgcn_sched_barrier(0)
; template <class Epi, class Sched, bool ALIGN_EPI, bool SP2>
; __device__ __forceinline__ void gemm_phase(PG8_LAS unsigned char* lds, const Gemm g, const Sched& S, const Epi& E, int wid) {
;     ...
;             PG8_LDB(B0, 1, 0); PG8_LDB(B1, 1, 1); PG8_SCHED; PG8_LDA(At, 1, 0); PG8_STAGE(PG8_SA(0, 1), a2 + hstepA, voffA);
;             PG8_WAIT_V(8); PG8_WAIT_L(0); PG8_BAR; PG8_MMA(0, 0, At, B0); PG8_MMA(0, 1, At, B1); PG8_BAR; PG8_SCHED;
	v_add_u32_e32 v68, 0x19800, v197
	v_add_u32_e32 v156, 0x1dc00, v197
	ds_read_b128 v[48:51], v68
	ds_read_b128 v[52:55], v68 offset:64
	ds_read_b128 v[64:67], v68 offset:2176
	ds_read_b128 v[68:71], v68 offset:2240
	ds_read_b128 v[144:147], v156
	ds_read_b128 v[148:151], v156 offset:64
	ds_read_b128 v[152:155], v156 offset:2176
	ds_read_b128 v[156:159], v156 offset:2240
	s_add_i32 s69, 0, 0x19800
	s_add_i32 s74, 0, 0x1dc00
	s_add_u32 s42, s42, 0xb0000
	s_addc_u32 s43, s43, 0
	s_mov_b32 m0, s29
	v_lshl_add_u64 v[220:221], s[42:43], 0, v[208:209]
	ds_read_b128 v[160:163], v241 offset:34816
	ds_read_b128 v[164:167], v241 offset:34880
	ds_read_b128 v[168:171], v241 offset:36992
	ds_read_b128 v[172:175], v241 offset:37056
	ds_read_b128 v[176:179], v241 offset:39168
	ds_read_b128 v[180:183], v241 offset:39232
	ds_read_b128 v[184:187], v241 offset:41344
	ds_read_b128 v[188:191], v241 offset:41408
	global_load_lds_dwordx4 v[220:221], off
	v_lshl_add_u64 v[220:221], s[42:43], 0, v[210:211]
	s_mov_b32 m0, s56
	s_nop 0
	global_load_lds_dwordx4 v[220:221], off
	s_waitcnt vmcnt(8)
	s_waitcnt lgkmcnt(0)
	s_barrier
	s_setprio 1
	s_waitcnt lgkmcnt(0)
	v_mfma_f32_16x16x32_bf16 v[132:135], v[48:51], v[160:163], v[132:135]
	v_mfma_f32_16x16x32_bf16 v[128:131], v[64:67], v[160:163], v[128:131]
	v_mfma_f32_16x16x32_bf16 v[124:127], v[48:51], v[168:171], v[124:127]
	v_mfma_f32_16x16x32_bf16 v[120:123], v[64:67], v[168:171], v[120:123]
	v_mfma_f32_16x16x32_bf16 v[108:111], v[48:51], v[176:179], v[108:111]
	v_mfma_f32_16x16x32_bf16 v[104:107], v[64:67], v[176:179], v[104:107]
	v_mfma_f32_16x16x32_bf16 v[92:95], v[48:51], v[184:187], v[92:95]
	v_mfma_f32_16x16x32_bf16 v[88:91], v[64:67], v[184:187], v[88:91]
	v_mfma_f32_16x16x32_bf16 v[132:135], v[52:55], v[164:167], v[132:135]
	v_mfma_f32_16x16x32_bf16 v[128:131], v[68:71], v[164:167], v[128:131]
	v_mfma_f32_16x16x32_bf16 v[124:127], v[52:55], v[172:175], v[124:127]
	v_mfma_f32_16x16x32_bf16 v[120:123], v[68:71], v[172:175], v[120:123]
	v_mfma_f32_16x16x32_bf16 v[108:111], v[52:55], v[180:183], v[108:111]
	v_mfma_f32_16x16x32_bf16 v[104:107], v[68:71], v[180:183], v[104:107]
	v_mfma_f32_16x16x32_bf16 v[92:95], v[52:55], v[188:191], v[92:95]
	v_mfma_f32_16x16x32_bf16 v[88:91], v[68:71], v[188:191], v[88:91]
	s_setprio 0
	s_setprio 1
	v_mfma_f32_16x16x32_bf16 v[140:143], v[144:147], v[160:163], v[140:143]
	v_mfma_f32_16x16x32_bf16 v[136:139], v[152:155], v[160:163], v[136:139]
	v_mfma_f32_16x16x32_bf16 v[116:119], v[144:147], v[168:171], v[116:119]
	v_mfma_f32_16x16x32_bf16 v[112:115], v[152:155], v[168:171], v[112:115]
	v_mfma_f32_16x16x32_bf16 v[100:103], v[144:147], v[176:179], v[100:103]
	v_mfma_f32_16x16x32_bf16 v[96:99], v[152:155], v[176:179], v[96:99]
	v_mfma_f32_16x16x32_bf16 v[84:87], v[144:147], v[184:187], v[84:87]
	v_mfma_f32_16x16x32_bf16 v[80:83], v[152:155], v[184:187], v[80:83]
	v_mfma_f32_16x16x32_bf16 v[140:143], v[148:151], v[164:167], v[140:143]
	v_mfma_f32_16x16x32_bf16 v[136:139], v[156:159], v[164:167], v[136:139]
	v_mfma_f32_16x16x32_bf16 v[116:119], v[148:151], v[172:175], v[116:119]
	v_mfma_f32_16x16x32_bf16 v[112:115], v[156:159], v[172:175], v[112:115]
	v_mfma_f32_16x16x32_bf16 v[100:103], v[148:151], v[180:183], v[100:103]
	v_mfma_f32_16x16x32_bf16 v[96:99], v[156:159], v[180:183], v[96:99]
	v_mfma_f32_16x16x32_bf16 v[84:87], v[148:151], v[188:191], v[84:87]
	v_mfma_f32_16x16x32_bf16 v[80:83], v[156:159], v[188:191], v[80:83]
	s_setprio 0
	s_barrier
; #define PG8_STAGE(bufoff, gbase, voff) do { _Pragma("unroll") for (int _i = 0; _i < 2; ++_i) \
;         __builtin_amdgcn_global_load_lds((const unsigned*)((const char*)(gbase) + (voff)[_i]), (PG8_LAS unsigned*)(lds + (bufoff) + ldsw + _i * (8 * USTR)), 16, 0, 0); } while (0)
; #define PG8_LDA(dst, b, h) do { _Pragma("unroll") for (int m = 0; m < 4; ++m) _Pragma("unroll") for (int k = 0; k < 2; ++k) dst[m][k] = *(const PG8_LAS bf16x8*)(lds + PG8_SA(b, h) + aoff + m * (2 * USTR) + k * 64); } while (0)
; #define PG8_MMA(ai, bj, At, Bt) do { __builtin_amdgcn_s_setprio(1); _Pragma("unroll") for (int m = 0; m < 4; ++m) _Pragma("unroll") for (int n = 0; n < 2; ++n) _Pragma("unroll") for (int k = 0; k < 2; ++k) \
;         acc[ai][bj][m][n] = __builtin_amdgcn_mfma_f32_16x16x32_bf16(Bt[n][k], At[m][k], acc[ai][bj][m][n], 0, 0, 0); __builtin_amdgcn_s_setprio(0); } while (0)
; #define PG8_WAIT_V(n) asm volatile("s_waitcnt vmcnt(" #n ")" ::: "memory")
; #define PG8_WAIT_L(n) asm volatile("s_waitcnt lgkmcnt(" #n ")" ::: "memory")
; #define PG8_BAR __builtin_amdgcn_s_barrier()
; #define PG8_SCHED __builtin_amdgcn_sched_barrier(0)
; template <class Epi, class Sched, bool ALIGN_EPI, bool SP2>
; __device__ __forceinline__ void gemm_phase(PG8_LAS unsigned char* lds, const Gemm g, const Sched& S, const Epi& E, int wid) {
;     ...
;             PG8_LDA(At, 1, 1); PG8_STAGE(PG8_SB(1, 0), b3, voffB); PG8_STAGE(PG8_SB(1, 1), b3 + hstepB, voffB); PG8_STAGE(PG8_SA(1, 0), a3, voffA);
;             PG8_WAIT_V(8); PG8_WAIT_L(0); PG8_BAR; PG8_MMA(1, 0, At, B0); PG8_MMA(1, 1, At, B1); PG8_BAR; PG8_SCHED;
;     ...
;         if constexpr (ALIGN_EPI) { if (wr == 0) PG8_BAR; }
	s_add_i32 s42, s69, s33
	v_lshl_add_u64 v[198:199], v[198:199], 0, s[6:7]
	s_mov_b32 m0, s42
	ds_read_b128 v[160:163], v241 offset:52224
	ds_read_b128 v[164:167], v241 offset:52288
	ds_read_b128 v[168:171], v241 offset:54400
	ds_read_b128 v[172:175], v241 offset:54464
	ds_read_b128 v[176:179], v241 offset:56576
	ds_read_b128 v[180:183], v241 offset:56640
	ds_read_b128 v[184:187], v241 offset:58752
	ds_read_b128 v[188:191], v241 offset:58816
	global_load_lds_dwordx4 v[198:199], off
	s_add_i32 m0, s42, 0x2200
	s_add_u32 s40, s40, 0xb0080
	v_lshl_add_u64 v[198:199], v[200:201], 0, s[6:7]
	s_addc_u32 s41, s41, 0
	s_add_i32 s42, s74, s33
	global_load_lds_dwordx4 v[198:199], off
	v_lshl_add_u64 v[198:199], s[40:41], 0, v[208:209]
	s_mov_b32 m0, s42
	s_nop 0
	global_load_lds_dwordx4 v[198:199], off
	v_lshl_add_u64 v[198:199], s[40:41], 0, v[210:211]
	s_add_i32 m0, s42, 0x2200
	s_nop 0
	global_load_lds_dwordx4 v[198:199], off
	v_lshl_add_u64 v[198:199], v[216:217], 0, s[6:7]
	s_mov_b32 m0, s57
	s_nop 0
	global_load_lds_dwordx4 v[198:199], off
	v_lshl_add_u64 v[198:199], v[218:219], 0, s[6:7]
	s_mov_b32 m0, s70
	s_nop 0
	global_load_lds_dwordx4 v[198:199], off
	s_add_i32 s68, s68, 2
	s_add_u32 s38, s38, 0x100
	s_addc_u32 s39, s39, 0
	s_add_u32 s26, s26, 0x100
	s_addc_u32 s27, s27, 0
	s_waitcnt vmcnt(8)
	s_waitcnt lgkmcnt(0)
	s_barrier
	s_setprio 1
	s_waitcnt lgkmcnt(0)
	v_mfma_f32_16x16x32_bf16 v[76:79], v[48:51], v[160:163], v[76:79]
	v_mfma_f32_16x16x32_bf16 v[72:75], v[64:67], v[160:163], v[72:75]
	v_mfma_f32_16x16x32_bf16 v[60:63], v[48:51], v[168:171], v[60:63]
	v_mfma_f32_16x16x32_bf16 v[56:59], v[64:67], v[168:171], v[56:59]
	v_mfma_f32_16x16x32_bf16 v[24:27], v[48:51], v[176:179], v[24:27]
	v_mfma_f32_16x16x32_bf16 v[28:31], v[64:67], v[176:179], v[28:31]
	v_mfma_f32_16x16x32_bf16 v[8:11], v[48:51], v[184:187], v[8:11]
	v_mfma_f32_16x16x32_bf16 v[12:15], v[64:67], v[184:187], v[12:15]
	v_mfma_f32_16x16x32_bf16 v[76:79], v[52:55], v[164:167], v[76:79]
	v_mfma_f32_16x16x32_bf16 v[72:75], v[68:71], v[164:167], v[72:75]
	v_mfma_f32_16x16x32_bf16 v[60:63], v[52:55], v[172:175], v[60:63]
	v_mfma_f32_16x16x32_bf16 v[56:59], v[68:71], v[172:175], v[56:59]
	v_mfma_f32_16x16x32_bf16 v[24:27], v[52:55], v[180:183], v[24:27]
	v_mfma_f32_16x16x32_bf16 v[28:31], v[68:71], v[180:183], v[28:31]
	v_mfma_f32_16x16x32_bf16 v[8:11], v[52:55], v[188:191], v[8:11]
	v_mfma_f32_16x16x32_bf16 v[12:15], v[68:71], v[188:191], v[12:15]
	s_setprio 0
	s_setprio 1
	v_mfma_f32_16x16x32_bf16 v[40:43], v[144:147], v[160:163], v[40:43]
	v_mfma_f32_16x16x32_bf16 v[68:71], v[148:151], v[164:167], v[40:43]
	v_mfma_f32_16x16x32_bf16 v[40:43], v[152:155], v[160:163], v[44:47]
	v_mfma_f32_16x16x32_bf16 v[36:39], v[144:147], v[168:171], v[36:39]
	v_mfma_f32_16x16x32_bf16 v[32:35], v[152:155], v[168:171], v[32:35]
	v_mfma_f32_16x16x32_bf16 v[20:23], v[144:147], v[176:179], v[20:23]
	v_mfma_f32_16x16x32_bf16 v[16:19], v[152:155], v[176:179], v[16:19]
	v_mfma_f32_16x16x32_bf16 v[4:7], v[144:147], v[184:187], v[4:7]
	v_mfma_f32_16x16x32_bf16 v[0:3], v[152:155], v[184:187], v[0:3]
	v_mfma_f32_16x16x32_bf16 v[64:67], v[156:159], v[164:167], v[40:43]
	v_mfma_f32_16x16x32_bf16 v[36:39], v[148:151], v[172:175], v[36:39]
	v_mfma_f32_16x16x32_bf16 v[32:35], v[156:159], v[172:175], v[32:35]
	v_mfma_f32_16x16x32_bf16 v[20:23], v[148:151], v[180:183], v[20:23]
	v_mfma_f32_16x16x32_bf16 v[16:19], v[156:159], v[180:183], v[16:19]
	v_mfma_f32_16x16x32_bf16 v[4:7], v[148:151], v[188:191], v[4:7]
	v_mfma_f32_16x16x32_bf16 v[0:3], v[156:159], v[188:191], v[0:3]
	s_setprio 0
	s_barrier
	s_cmp_gt_u32 s68, 41
	s_cbranch_scc0 .LBB0_290
	s_and_b64 vcc, exec, s[20:21]
	s_cbranch_vccz .LBB0_293
	s_barrier

; #define PG8_STAGE(bufoff, gbase, voff) do { _Pragma("unroll") for (int _i = 0; _i < 2; ++_i) \
;         __builtin_amdgcn_global_load_lds((const unsigned*)((const char*)(gbase) + (voff)[_i]), (PG8_LAS unsigned*)(lds + (bufoff) + ldsw + _i * (8 * USTR)), 16, 0, 0); } while (0)
; #define PG8_LDA(dst, b, h) do { _Pragma("unroll") for (int m = 0; m < 4; ++m) _Pragma("unroll") for (int k = 0; k < 2; ++k) dst[m][k] = *(const PG8_LAS bf16x8*)(lds + PG8_SA(b, h) + aoff + m * (2 * USTR) + k * 64); } while (0)
; #define PG8_LDB(dst, b, h) do { _Pragma("unroll") for (int n = 0; n < 2; ++n) _Pragma("unroll") for (int k = 0; k < 2; ++k) dst[n][k] = *(const PG8_LAS bf16x8*)(lds + PG8_SB(b, h) + boff + n * (2 * USTR) + k * 64); } while (0)
; #define PG8_MMA(ai, bj, At, Bt) do { __builtin_amdgcn_s_setprio(1); _Pragma("unroll") for (int m = 0; m < 4; ++m) _Pragma("unroll") for (int n = 0; n < 2; ++n) _Pragma("unroll") for (int k = 0; k < 2; ++k) \
;         acc[ai][bj][m][n] = __builtin_amdgcn_mfma_f32_16x16x32_bf16(Bt[n][k], At[m][k], acc[ai][bj][m][n], 0, 0, 0); __builtin_amdgcn_s_setprio(0); } while (0)
; #define PG8_WAIT_V(n) asm volatile("s_waitcnt vmcnt(" #n ")" ::: "memory")
; #define PG8_WAIT_L(n) asm volatile("s_waitcnt lgkmcnt(" #n ")" ::: "memory")
; #define PG8_BAR __builtin_amdgcn_s_barrier()
; #define PG8_SCHED __builtin_amdgcn_sched_barrier(0)
; template <class Epi, class Sched, bool ALIGN_EPI, bool SP2>
; __device__ __forceinline__ void gemm_phase(PG8_LAS unsigned char* lds, const Gemm g, const Sched& S, const Epi& E, int wid) {
;     ...
;             PG8_LDB(B0, 0, 0); PG8_LDB(B1, 0, 1); PG8_SCHED; PG8_LDA(At, 0, 0); PG8_STAGE(PG8_SA(1, 1), a1 + hstepA, voffA);
;             PG8_WAIT_V(8); PG8_WAIT_L(0); PG8_BAR; PG8_MMA(0, 0, At, B0); PG8_MMA(0, 1, At, B1); PG8_BAR; PG8_SCHED;
;             PG8_LDA(At, 0, 1); PG8_STAGE(PG8_SB(0, 0), b2, voffB); PG8_STAGE(PG8_SB(0, 1), b2 + hstepB, voffB); PG8_STAGE(PG8_SA(0, 0), a2, voffA);
;             PG8_WAIT_V(8); PG8_WAIT_L(0); PG8_BAR; PG8_MMA(1, 0, At, B0); PG8_MMA(1, 1, At, B1); PG8_BAR; PG8_SCHED;
.Lhb_up:
	v_add_u32_e32 v94, 0x11000, v161
	ds_read_b128 v[86:89], v94
	ds_read_b128 v[90:93], v94 offset:64
	ds_read_b128 v[164:167], v94 offset:2176
	ds_read_b128 v[168:171], v94 offset:2240
	v_add_u32_e32 v94, 0x15400, v161
	ds_read_b128 v[172:175], v94
	ds_read_b128 v[176:179], v94 offset:64
	ds_read_b128 v[180:183], v94 offset:2176
	ds_read_b128 v[184:187], v94 offset:2240
	s_add_i32 s77, 0, 0x11000
	s_add_i32 s89, 0, 0x15400
	v_lshl_add_u64 v[94:95], s[38:39], 0, v[154:155]
	s_add_i32 m0, s0, 0xcc00
	ds_read_b128 v[188:191], v163
	ds_read_b128 v[208:211], v163 offset:64
	ds_read_b128 v[212:215], v163 offset:2176
	ds_read_b128 v[216:219], v163 offset:2240
	ds_read_b128 v[220:223], v163 offset:4352
	ds_read_b128 v[224:227], v163 offset:4416
	ds_read_b128 v[228:231], v163 offset:6528
	ds_read_b128 v[242:245], v163 offset:6592
	global_load_lds_dwordx4 v[94:95], off
	v_lshl_add_u64 v[94:95], s[38:39], 0, v[156:157]
	s_add_i32 m0, s0, 0xee00
	s_nop 0
	global_load_lds_dwordx4 v[94:95], off
	s_cmp_eq_u32 s76, 12
	s_cselect_b64 s[68:69], -1, 0
	s_add_u32 s70, s38, 0xfffc0080
	s_addc_u32 s71, s39, -1
	s_and_b64 s[68:69], s[68:69], exec
	s_cselect_b32 s71, s26, s71
	s_cselect_b32 s70, s27, s70
	s_cselect_b32 s69, s41, s75
	s_cselect_b32 s68, s73, s74
	s_waitcnt vmcnt(8)
	s_waitcnt lgkmcnt(0)
	s_barrier
	s_setprio 1
	s_waitcnt lgkmcnt(0)
	v_mfma_f32_16x16x32_bf16 v[140:143], v[86:89], v[188:191], 0
	v_mfma_f32_16x16x32_bf16 v[136:139], v[164:167], v[188:191], 0
	v_mfma_f32_16x16x32_bf16 v[124:127], v[86:89], v[212:215], 0
	v_mfma_f32_16x16x32_bf16 v[120:123], v[164:167], v[212:215], 0
	v_mfma_f32_16x16x32_bf16 v[108:111], v[86:89], v[220:223], 0
	v_mfma_f32_16x16x32_bf16 v[104:107], v[164:167], v[220:223], 0
	v_mfma_f32_16x16x32_bf16 v[76:79], v[86:89], v[228:231], 0
	v_mfma_f32_16x16x32_bf16 v[72:75], v[164:167], v[228:231], 0
	v_mfma_f32_16x16x32_bf16 v[140:143], v[90:93], v[208:211], v[140:143]
	v_mfma_f32_16x16x32_bf16 v[136:139], v[168:171], v[208:211], v[136:139]
	v_mfma_f32_16x16x32_bf16 v[124:127], v[90:93], v[216:219], v[124:127]
	v_mfma_f32_16x16x32_bf16 v[120:123], v[168:171], v[216:219], v[120:123]
	v_mfma_f32_16x16x32_bf16 v[108:111], v[90:93], v[224:227], v[108:111]
	v_mfma_f32_16x16x32_bf16 v[104:107], v[168:171], v[224:227], v[104:107]
	v_mfma_f32_16x16x32_bf16 v[76:79], v[90:93], v[242:245], v[76:79]
	v_mfma_f32_16x16x32_bf16 v[72:75], v[168:171], v[242:245], v[72:75]
	s_setprio 0
	s_setprio 1
	v_mfma_f32_16x16x32_bf16 v[132:135], v[172:175], v[188:191], 0
	v_mfma_f32_16x16x32_bf16 v[128:131], v[180:183], v[188:191], 0
	v_mfma_f32_16x16x32_bf16 v[116:119], v[172:175], v[212:215], 0
	v_mfma_f32_16x16x32_bf16 v[112:115], v[180:183], v[212:215], 0
	v_mfma_f32_16x16x32_bf16 v[100:103], v[172:175], v[220:223], 0
	v_mfma_f32_16x16x32_bf16 v[94:97], v[180:183], v[220:223], 0
	v_mfma_f32_16x16x32_bf16 v[68:71], v[172:175], v[228:231], 0
	v_mfma_f32_16x16x32_bf16 v[64:67], v[180:183], v[228:231], 0
	v_mfma_f32_16x16x32_bf16 v[132:135], v[176:179], v[208:211], v[132:135]
	v_mfma_f32_16x16x32_bf16 v[128:131], v[184:187], v[208:211], v[128:131]
	v_mfma_f32_16x16x32_bf16 v[116:119], v[176:179], v[216:219], v[116:119]
	v_mfma_f32_16x16x32_bf16 v[112:115], v[184:187], v[216:219], v[112:115]
	v_mfma_f32_16x16x32_bf16 v[100:103], v[176:179], v[224:227], v[100:103]
	v_mfma_f32_16x16x32_bf16 v[94:97], v[184:187], v[224:227], v[94:97]
	v_mfma_f32_16x16x32_bf16 v[68:71], v[176:179], v[242:245], v[68:71]
	v_mfma_f32_16x16x32_bf16 v[64:67], v[184:187], v[242:245], v[64:67]
	s_setprio 0
	s_barrier
	s_add_i32 s77, s77, s33
	v_lshl_add_u64 v[158:159], s[68:69], 0, v[192:193]
	s_mov_b32 m0, s77
	ds_read_b128 v[188:191], v163 offset:17408
	ds_read_b128 v[208:211], v163 offset:17472
	ds_read_b128 v[212:215], v163 offset:19584
	ds_read_b128 v[216:219], v163 offset:19648
	ds_read_b128 v[220:223], v163 offset:21760
	ds_read_b128 v[224:227], v163 offset:21824
	ds_read_b128 v[228:231], v163 offset:23936
	ds_read_b128 v[242:245], v163 offset:24000
	global_load_lds_dwordx4 v[158:159], off
	s_add_i32 m0, s77, 0x2200
	s_add_u32 s78, s68, 0x40000
	v_lshl_add_u64 v[198:199], s[68:69], 0, v[144:145]
	s_addc_u32 s79, s69, 0
	s_add_i32 s77, s89, s33
	global_load_lds_dwordx4 v[198:199], off
	v_lshl_add_u64 v[98:99], s[78:79], 0, v[192:193]
	s_mov_b32 m0, s77
	v_lshl_add_u64 v[200:201], s[70:71], 0, v[148:149]
	global_load_lds_dwordx4 v[98:99], off
	v_lshl_add_u64 v[98:99], s[78:79], 0, v[144:145]
	s_add_i32 m0, s77, 0x2200
	v_lshl_add_u64 v[232:233], s[70:71], 0, v[146:147]
	global_load_lds_dwordx4 v[98:99], off
	s_mov_b32 m0, s0
	s_nop 0
	global_load_lds_dwordx4 v[200:201], off
	s_mov_b32 m0, s5
	s_nop 0
	global_load_lds_dwordx4 v[232:233], off
	s_waitcnt vmcnt(8)
	s_waitcnt lgkmcnt(0)
	s_barrier
; #define PG8_STAGE(bufoff, gbase, voff) do { _Pragma("unroll") for (int _i = 0; _i < 2; ++_i) \
;         __builtin_amdgcn_global_load_lds((const unsigned*)((const char*)(gbase) + (voff)[_i]), (PG8_LAS unsigned*)(lds + (bufoff) + ldsw + _i * (8 * USTR)), 16, 0, 0); } while (0)
; #define PG8_LDA(dst, b, h) do { _Pragma("unroll") for (int m = 0; m < 4; ++m) _Pragma("unroll") for (int k = 0; k < 2; ++k) dst[m][k] = *(const PG8_LAS bf16x8*)(lds + PG8_SA(b, h) + aoff + m * (2 * USTR) + k * 64); } while (0)
; #define PG8_LDB(dst, b, h) do { _Pragma("unroll") for (int n = 0; n < 2; ++n) _Pragma("unroll") for (int k = 0; k < 2; ++k) dst[n][k] = *(const PG8_LAS bf16x8*)(lds + PG8_SB(b, h) + boff + n * (2 * USTR) + k * 64); } while (0)
; #define PG8_MMA(ai, bj, At, Bt) do { __builtin_amdgcn_s_setprio(1); _Pragma("unroll") for (int m = 0; m < 4; ++m) _Pragma("unroll") for (int n = 0; n < 2; ++n) _Pragma("unroll") for (int k = 0; k < 2; ++k) \
;         acc[ai][bj][m][n] = __builtin_amdgcn_mfma_f32_16x16x32_bf16(Bt[n][k], At[m][k], acc[ai][bj][m][n], 0, 0, 0); __builtin_amdgcn_s_setprio(0); } while (0)
; #define PG8_WAIT_V(n) asm volatile("s_waitcnt vmcnt(" #n ")" ::: "memory")
; #define PG8_WAIT_L(n) asm volatile("s_waitcnt lgkmcnt(" #n ")" ::: "memory")
; #define PG8_BAR __builtin_amdgcn_s_barrier()
; #define PG8_SCHED __builtin_amdgcn_sched_barrier(0)
; template <class Epi, class Sched, bool ALIGN_EPI, bool SP2>
; __device__ __forceinline__ void gemm_phase(PG8_LAS unsigned char* lds, const Gemm g, const Sched& S, const Epi& E, int wid) {
;     ...
;             PG8_WAIT_V(8); PG8_WAIT_L(0); PG8_BAR; PG8_MMA(1, 0, At, B0); PG8_MMA(1, 1, At, B1); PG8_BAR; PG8_SCHED;
;             PG8_LDB(B0, 1, 0); PG8_LDB(B1, 1, 1); PG8_SCHED; PG8_LDA(At, 1, 0); PG8_STAGE(PG8_SA(0, 1), a2 + hstepA, voffA);
;             PG8_WAIT_V(8); PG8_WAIT_L(0); PG8_BAR; PG8_MMA(0, 0, At, B0); PG8_MMA(0, 1, At, B1); PG8_BAR; PG8_SCHED;
	s_setprio 1
	s_waitcnt lgkmcnt(0)
	v_mfma_f32_16x16x32_bf16 v[60:63], v[86:89], v[188:191], 0
	v_mfma_f32_16x16x32_bf16 v[56:59], v[164:167], v[188:191], 0
	v_mfma_f32_16x16x32_bf16 v[44:47], v[86:89], v[212:215], 0
	v_mfma_f32_16x16x32_bf16 v[40:43], v[164:167], v[212:215], 0
	v_mfma_f32_16x16x32_bf16 v[28:31], v[86:89], v[220:223], 0
	v_mfma_f32_16x16x32_bf16 v[24:27], v[164:167], v[220:223], 0
	v_mfma_f32_16x16x32_bf16 v[12:15], v[86:89], v[228:231], 0
	v_mfma_f32_16x16x32_bf16 v[8:11], v[164:167], v[228:231], 0
	v_mfma_f32_16x16x32_bf16 v[60:63], v[90:93], v[208:211], v[60:63]
	v_mfma_f32_16x16x32_bf16 v[56:59], v[168:171], v[208:211], v[56:59]
	v_mfma_f32_16x16x32_bf16 v[44:47], v[90:93], v[216:219], v[44:47]
	v_mfma_f32_16x16x32_bf16 v[40:43], v[168:171], v[216:219], v[40:43]
	v_mfma_f32_16x16x32_bf16 v[28:31], v[90:93], v[224:227], v[28:31]
	v_mfma_f32_16x16x32_bf16 v[24:27], v[168:171], v[224:227], v[24:27]
	v_mfma_f32_16x16x32_bf16 v[12:15], v[90:93], v[242:245], v[12:15]
	v_mfma_f32_16x16x32_bf16 v[8:11], v[168:171], v[242:245], v[8:11]
	s_setprio 0
	s_setprio 1
	v_mfma_f32_16x16x32_bf16 v[52:55], v[172:175], v[188:191], 0
	v_mfma_f32_16x16x32_bf16 v[48:51], v[180:183], v[188:191], 0
	v_mfma_f32_16x16x32_bf16 v[36:39], v[172:175], v[212:215], 0
	v_mfma_f32_16x16x32_bf16 v[32:35], v[180:183], v[212:215], 0
	v_mfma_f32_16x16x32_bf16 v[20:23], v[172:175], v[220:223], 0
	v_mfma_f32_16x16x32_bf16 v[16:19], v[180:183], v[220:223], 0
	v_mfma_f32_16x16x32_bf16 v[4:7], v[172:175], v[228:231], 0
	v_mfma_f32_16x16x32_bf16 v[0:3], v[180:183], v[228:231], 0
	v_mfma_f32_16x16x32_bf16 v[52:55], v[176:179], v[208:211], v[52:55]
	v_mfma_f32_16x16x32_bf16 v[48:51], v[184:187], v[208:211], v[48:51]
	v_mfma_f32_16x16x32_bf16 v[36:39], v[176:179], v[216:219], v[36:39]
	v_mfma_f32_16x16x32_bf16 v[32:35], v[184:187], v[216:219], v[32:35]
	v_mfma_f32_16x16x32_bf16 v[20:23], v[176:179], v[224:227], v[20:23]
	v_mfma_f32_16x16x32_bf16 v[16:19], v[184:187], v[224:227], v[16:19]
	v_mfma_f32_16x16x32_bf16 v[4:7], v[176:179], v[242:245], v[4:7]
	v_mfma_f32_16x16x32_bf16 v[0:3], v[184:187], v[242:245], v[0:3]
	s_setprio 0
	s_barrier
	v_add_u32_e32 v98, 0x19800, v161
	ds_read_b128 v[86:89], v98
	ds_read_b128 v[90:93], v98 offset:64
	ds_read_b128 v[164:167], v98 offset:2176
	ds_read_b128 v[168:171], v98 offset:2240
	v_add_u32_e32 v98, 0x1dc00, v161
	ds_read_b128 v[172:175], v98
	ds_read_b128 v[176:179], v98 offset:64
	ds_read_b128 v[180:183], v98 offset:2176
	ds_read_b128 v[184:187], v98 offset:2240
	s_add_i32 s77, 0, 0x19800
	s_add_i32 s78, 0, 0x1dc00
	s_add_u32 s70, s70, 0x40000
	s_addc_u32 s71, s71, 0
	s_mov_b32 m0, s10
	v_lshl_add_u64 v[98:99], s[70:71], 0, v[148:149]
	ds_read_b128 v[188:191], v163 offset:34816
	ds_read_b128 v[208:211], v163 offset:34880
	ds_read_b128 v[212:215], v163 offset:36992
	ds_read_b128 v[216:219], v163 offset:37056
	ds_read_b128 v[220:223], v163 offset:39168
	ds_read_b128 v[224:227], v163 offset:39232
	ds_read_b128 v[228:231], v163 offset:41344
	ds_read_b128 v[242:245], v163 offset:41408
	global_load_lds_dwordx4 v[98:99], off
	v_lshl_add_u64 v[98:99], s[70:71], 0, v[146:147]
	s_mov_b32 m0, s29
	s_nop 0
	global_load_lds_dwordx4 v[98:99], off
	s_waitcnt vmcnt(8)
	s_waitcnt lgkmcnt(0)
	s_barrier
	s_setprio 1
	s_waitcnt lgkmcnt(0)
	v_mfma_f32_16x16x32_bf16 v[140:143], v[86:89], v[188:191], v[140:143]
	v_mfma_f32_16x16x32_bf16 v[136:139], v[164:167], v[188:191], v[136:139]
	v_mfma_f32_16x16x32_bf16 v[124:127], v[86:89], v[212:215], v[124:127]
	v_mfma_f32_16x16x32_bf16 v[120:123], v[164:167], v[212:215], v[120:123]
	v_mfma_f32_16x16x32_bf16 v[108:111], v[86:89], v[220:223], v[108:111]
	v_mfma_f32_16x16x32_bf16 v[104:107], v[164:167], v[220:223], v[104:107]
	v_mfma_f32_16x16x32_bf16 v[76:79], v[86:89], v[228:231], v[76:79]
	v_mfma_f32_16x16x32_bf16 v[72:75], v[164:167], v[228:231], v[72:75]
	v_mfma_f32_16x16x32_bf16 v[140:143], v[90:93], v[208:211], v[140:143]
	v_mfma_f32_16x16x32_bf16 v[136:139], v[168:171], v[208:211], v[136:139]
	v_mfma_f32_16x16x32_bf16 v[124:127], v[90:93], v[216:219], v[124:127]
	v_mfma_f32_16x16x32_bf16 v[120:123], v[168:171], v[216:219], v[120:123]
	v_mfma_f32_16x16x32_bf16 v[108:111], v[90:93], v[224:227], v[108:111]
	v_mfma_f32_16x16x32_bf16 v[104:107], v[168:171], v[224:227], v[104:107]
	v_mfma_f32_16x16x32_bf16 v[76:79], v[90:93], v[242:245], v[76:79]
	v_mfma_f32_16x16x32_bf16 v[72:75], v[168:171], v[242:245], v[72:75]
	s_setprio 0
	s_setprio 1
	v_mfma_f32_16x16x32_bf16 v[132:135], v[172:175], v[188:191], v[132:135]
	v_mfma_f32_16x16x32_bf16 v[128:131], v[180:183], v[188:191], v[128:131]
	v_mfma_f32_16x16x32_bf16 v[116:119], v[172:175], v[212:215], v[116:119]
	v_mfma_f32_16x16x32_bf16 v[112:115], v[180:183], v[212:215], v[112:115]
	v_mfma_f32_16x16x32_bf16 v[98:101], v[172:175], v[220:223], v[100:103]
	v_mfma_f32_16x16x32_bf16 v[94:97], v[180:183], v[220:223], v[94:97]
	v_mfma_f32_16x16x32_bf16 v[68:71], v[172:175], v[228:231], v[68:71]
	v_mfma_f32_16x16x32_bf16 v[64:67], v[180:183], v[228:231], v[64:67]
	v_mfma_f32_16x16x32_bf16 v[132:135], v[176:179], v[208:211], v[132:135]
	v_mfma_f32_16x16x32_bf16 v[128:131], v[184:187], v[208:211], v[128:131]
	v_mfma_f32_16x16x32_bf16 v[116:119], v[176:179], v[216:219], v[116:119]
	v_mfma_f32_16x16x32_bf16 v[112:115], v[184:187], v[216:219], v[112:115]
	v_mfma_f32_16x16x32_bf16 v[100:103], v[176:179], v[224:227], v[98:101]
	v_mfma_f32_16x16x32_bf16 v[96:99], v[184:187], v[224:227], v[94:97]
	v_mfma_f32_16x16x32_bf16 v[68:71], v[176:179], v[242:245], v[68:71]
	v_mfma_f32_16x16x32_bf16 v[64:67], v[184:187], v[242:245], v[64:67]
	s_setprio 0
	s_barrier
; #define PG8_STAGE(bufoff, gbase, voff) do { _Pragma("unroll") for (int _i = 0; _i < 2; ++_i) \
;         __builtin_amdgcn_global_load_lds((const unsigned*)((const char*)(gbase) + (voff)[_i]), (PG8_LAS unsigned*)(lds + (bufoff) + ldsw + _i * (8 * USTR)), 16, 0, 0); } while (0)
; #define PG8_LDA(dst, b, h) do { _Pragma("unroll") for (int m = 0; m < 4; ++m) _Pragma("unroll") for (int k = 0; k < 2; ++k) dst[m][k] = *(const PG8_LAS bf16x8*)(lds + PG8_SA(b, h) + aoff + m * (2 * USTR) + k * 64); } while (0)
; #define PG8_LDB(dst, b, h) do { _Pragma("unroll") for (int n = 0; n < 2; ++n) _Pragma("unroll") for (int k = 0; k < 2; ++k) dst[n][k] = *(const PG8_LAS bf16x8*)(lds + PG8_SB(b, h) + boff + n * (2 * USTR) + k * 64); } while (0)
; #define PG8_MMA(ai, bj, At, Bt) do { __builtin_amdgcn_s_setprio(1); _Pragma("unroll") for (int m = 0; m < 4; ++m) _Pragma("unroll") for (int n = 0; n < 2; ++n) _Pragma("unroll") for (int k = 0; k < 2; ++k) \
;         acc[ai][bj][m][n] = __builtin_amdgcn_mfma_f32_16x16x32_bf16(Bt[n][k], At[m][k], acc[ai][bj][m][n], 0, 0, 0); __builtin_amdgcn_s_setprio(0); } while (0)
; #define PG8_WAIT_V(n) asm volatile("s_waitcnt vmcnt(" #n ")" ::: "memory")
; #define PG8_WAIT_L(n) asm volatile("s_waitcnt lgkmcnt(" #n ")" ::: "memory")
; #define PG8_BAR __builtin_amdgcn_s_barrier()
; #define PG8_SCHED __builtin_amdgcn_sched_barrier(0)
; template <class Epi, class Sched, bool ALIGN_EPI, bool SP2>
; __device__ __forceinline__ void gemm_phase(PG8_LAS unsigned char* lds, const Gemm g, const Sched& S, const Epi& E, int wid) {
;     ...
;             PG8_LDB(B0, 0, 0); PG8_LDB(B1, 0, 1); PG8_SCHED; PG8_LDA(At, 0, 0); PG8_STAGE(PG8_SA(1, 1), a1 + hstepA, voffA);
;             PG8_WAIT_V(8); PG8_WAIT_L(0); PG8_BAR; PG8_MMA(0, 0, At, B0); PG8_MMA(0, 1, At, B1); PG8_BAR; PG8_SCHED;
;             PG8_LDA(At, 0, 1); PG8_STAGE(PG8_SB(0, 0), b2, voffB); PG8_STAGE(PG8_SB(0, 1), b2 + hstepB, voffB); PG8_STAGE(PG8_SA(0, 0), a2, voffA);
;     ...
;             PG8_LDA(At, 1, 1); PG8_STAGE(PG8_SB(1, 0), b3, voffB); PG8_STAGE(PG8_SB(1, 1), b3 + hstepB, voffB); PG8_STAGE(PG8_SA(1, 0), a3, voffA);
;             PG8_WAIT_V(8); PG8_WAIT_L(0); PG8_BAR; PG8_MMA(1, 0, At, B0); PG8_MMA(1, 1, At, B1); PG8_BAR; PG8_SCHED;
	s_add_i32 s70, s77, s33
	v_lshl_add_u64 v[94:95], v[158:159], 0, s[6:7]
	s_mov_b32 m0, s70
	ds_read_b128 v[188:191], v163 offset:52224
	ds_read_b128 v[208:211], v163 offset:52288
	ds_read_b128 v[212:215], v163 offset:54400
	ds_read_b128 v[216:219], v163 offset:54464
	ds_read_b128 v[220:223], v163 offset:56576
	ds_read_b128 v[224:227], v163 offset:56640
	ds_read_b128 v[228:231], v163 offset:58752
	ds_read_b128 v[242:245], v163 offset:58816
	global_load_lds_dwordx4 v[94:95], off
	s_add_i32 m0, s70, 0x2200
	s_add_u32 s68, s68, 0x40080
	v_lshl_add_u64 v[94:95], v[198:199], 0, s[6:7]
	s_addc_u32 s69, s69, 0
	s_add_i32 s70, s78, s33
	global_load_lds_dwordx4 v[94:95], off
	v_lshl_add_u64 v[94:95], s[68:69], 0, v[192:193]
	s_mov_b32 m0, s70
	s_nop 0
	global_load_lds_dwordx4 v[94:95], off
	v_lshl_add_u64 v[94:95], s[68:69], 0, v[144:145]
	s_add_i32 m0, s70, 0x2200
	s_nop 0
	global_load_lds_dwordx4 v[94:95], off
	v_lshl_add_u64 v[94:95], v[200:201], 0, s[6:7]
	s_mov_b32 m0, s56
	s_nop 0
	global_load_lds_dwordx4 v[94:95], off
	v_lshl_add_u64 v[94:95], v[232:233], 0, s[6:7]
	s_mov_b32 m0, s57
	s_nop 0
	global_load_lds_dwordx4 v[94:95], off
	s_add_i32 s76, s76, 2
	s_add_u32 s38, s38, 0x100
	s_addc_u32 s39, s39, 0
	s_add_u32 s74, s74, 0x100
	s_addc_u32 s75, s75, 0
	s_waitcnt vmcnt(8)
	s_waitcnt lgkmcnt(0)
	s_barrier
	s_setprio 1
	s_waitcnt lgkmcnt(0)
	v_mfma_f32_16x16x32_bf16 v[60:63], v[86:89], v[188:191], v[60:63]
	v_mfma_f32_16x16x32_bf16 v[56:59], v[164:167], v[188:191], v[56:59]
	v_mfma_f32_16x16x32_bf16 v[44:47], v[86:89], v[212:215], v[44:47]
	v_mfma_f32_16x16x32_bf16 v[40:43], v[164:167], v[212:215], v[40:43]
	v_mfma_f32_16x16x32_bf16 v[28:31], v[86:89], v[220:223], v[28:31]
	v_mfma_f32_16x16x32_bf16 v[24:27], v[164:167], v[220:223], v[24:27]
	v_mfma_f32_16x16x32_bf16 v[12:15], v[86:89], v[228:231], v[12:15]
	v_mfma_f32_16x16x32_bf16 v[8:11], v[164:167], v[228:231], v[8:11]
	v_mfma_f32_16x16x32_bf16 v[60:63], v[90:93], v[208:211], v[60:63]
	v_mfma_f32_16x16x32_bf16 v[56:59], v[168:171], v[208:211], v[56:59]
	v_mfma_f32_16x16x32_bf16 v[44:47], v[90:93], v[216:219], v[44:47]
	v_mfma_f32_16x16x32_bf16 v[40:43], v[168:171], v[216:219], v[40:43]
	v_mfma_f32_16x16x32_bf16 v[28:31], v[90:93], v[224:227], v[28:31]
	v_mfma_f32_16x16x32_bf16 v[24:27], v[168:171], v[224:227], v[24:27]
	v_mfma_f32_16x16x32_bf16 v[12:15], v[90:93], v[242:245], v[12:15]
	v_mfma_f32_16x16x32_bf16 v[8:11], v[168:171], v[242:245], v[8:11]
	s_setprio 0
	s_setprio 1
	v_mfma_f32_16x16x32_bf16 v[52:55], v[172:175], v[188:191], v[52:55]
	v_mfma_f32_16x16x32_bf16 v[48:51], v[180:183], v[188:191], v[48:51]
	v_mfma_f32_16x16x32_bf16 v[36:39], v[172:175], v[212:215], v[36:39]
	v_mfma_f32_16x16x32_bf16 v[32:35], v[180:183], v[212:215], v[32:35]
	v_mfma_f32_16x16x32_bf16 v[20:23], v[172:175], v[220:223], v[20:23]
	v_mfma_f32_16x16x32_bf16 v[16:19], v[180:183], v[220:223], v[16:19]
	v_mfma_f32_16x16x32_bf16 v[4:7], v[172:175], v[228:231], v[4:7]
	v_mfma_f32_16x16x32_bf16 v[0:3], v[180:183], v[228:231], v[0:3]
	v_mfma_f32_16x16x32_bf16 v[52:55], v[176:179], v[208:211], v[52:55]
	v_mfma_f32_16x16x32_bf16 v[48:51], v[184:187], v[208:211], v[48:51]
	v_mfma_f32_16x16x32_bf16 v[36:39], v[176:179], v[216:219], v[36:39]
	v_mfma_f32_16x16x32_bf16 v[32:35], v[184:187], v[216:219], v[32:35]
	v_mfma_f32_16x16x32_bf16 v[20:23], v[176:179], v[224:227], v[20:23]
	v_mfma_f32_16x16x32_bf16 v[16:19], v[184:187], v[224:227], v[16:19]
	v_mfma_f32_16x16x32_bf16 v[4:7], v[176:179], v[242:245], v[4:7]
	v_mfma_f32_16x16x32_bf16 v[0:3], v[184:187], v[242:245], v[0:3]
	s_setprio 0
	s_barrier
	s_cmp_gt_u32 s76, 13
	s_branch .LBB0_374
.LBB0_373:
	v_add_u32_e32 v94, 0x11000, v161
	ds_read_b128 v[86:89], v94
	ds_read_b128 v[90:93], v94 offset:64
	ds_read_b128 v[164:167], v94 offset:2176
	ds_read_b128 v[168:171], v94 offset:2240
	v_add_u32_e32 v94, 0x15400, v161
	ds_read_b128 v[172:175], v94
	ds_read_b128 v[176:179], v94 offset:64
	ds_read_b128 v[180:183], v94 offset:2176
	ds_read_b128 v[184:187], v94 offset:2240
	s_add_i32 s77, 0, 0x11000
	s_add_i32 s89, 0, 0x15400
	v_lshl_add_u64 v[94:95], s[38:39], 0, v[154:155]
	s_add_i32 m0, s0, 0xcc00
	ds_read_b128 v[188:191], v163
	ds_read_b128 v[208:211], v163 offset:64
	ds_read_b128 v[212:215], v163 offset:2176
	ds_read_b128 v[216:219], v163 offset:2240
	ds_read_b128 v[220:223], v163 offset:4352
	ds_read_b128 v[224:227], v163 offset:4416
	ds_read_b128 v[228:231], v163 offset:6528
	ds_read_b128 v[242:245], v163 offset:6592
	global_load_lds_dwordx4 v[94:95], off
	v_lshl_add_u64 v[94:95], s[38:39], 0, v[156:157]
	s_add_i32 m0, s0, 0xee00
	s_nop 0
	global_load_lds_dwordx4 v[94:95], off
	s_add_u32 s70, s38, 0xfffc0080
	s_addc_u32 s71, s39, -1
	s_and_b64 s[68:69], s[68:69], exec
	s_cselect_b32 s71, s26, s71
	s_cselect_b32 s70, s27, s70
	s_cselect_b32 s69, s41, s75
	s_cselect_b32 s68, s73, s74
	s_waitcnt vmcnt(8)
	s_waitcnt lgkmcnt(0)
	s_barrier
; #define PG8_STAGE(bufoff, gbase, voff) do { _Pragma("unroll") for (int _i = 0; _i < 2; ++_i) \
;         __builtin_amdgcn_global_load_lds((const unsigned*)((const char*)(gbase) + (voff)[_i]), (PG8_LAS unsigned*)(lds + (bufoff) + ldsw + _i * (8 * USTR)), 16, 0, 0); } while (0)
; #define PG8_LDA(dst, b, h) do { _Pragma("unroll") for (int m = 0; m < 4; ++m) _Pragma("unroll") for (int k = 0; k < 2; ++k) dst[m][k] = *(const PG8_LAS bf16x8*)(lds + PG8_SA(b, h) + aoff + m * (2 * USTR) + k * 64); } while (0)
; #define PG8_MMA(ai, bj, At, Bt) do { __builtin_amdgcn_s_setprio(1); _Pragma("unroll") for (int m = 0; m < 4; ++m) _Pragma("unroll") for (int n = 0; n < 2; ++n) _Pragma("unroll") for (int k = 0; k < 2; ++k) \
;         acc[ai][bj][m][n] = __builtin_amdgcn_mfma_f32_16x16x32_bf16(Bt[n][k], At[m][k], acc[ai][bj][m][n], 0, 0, 0); __builtin_amdgcn_s_setprio(0); } while (0)
; #define PG8_WAIT_V(n) asm volatile("s_waitcnt vmcnt(" #n ")" ::: "memory")
; #define PG8_WAIT_L(n) asm volatile("s_waitcnt lgkmcnt(" #n ")" ::: "memory")
; #define PG8_BAR __builtin_amdgcn_s_barrier()
; #define PG8_SCHED __builtin_amdgcn_sched_barrier(0)
; template <class Epi, class Sched, bool ALIGN_EPI, bool SP2>
; __device__ __forceinline__ void gemm_phase(PG8_LAS unsigned char* lds, const Gemm g, const Sched& S, const Epi& E, int wid) {
;     ...
;             PG8_WAIT_V(8); PG8_WAIT_L(0); PG8_BAR; PG8_MMA(0, 0, At, B0); PG8_MMA(0, 1, At, B1); PG8_BAR; PG8_SCHED;
;             PG8_LDA(At, 0, 1); PG8_STAGE(PG8_SB(0, 0), b2, voffB); PG8_STAGE(PG8_SB(0, 1), b2 + hstepB, voffB); PG8_STAGE(PG8_SA(0, 0), a2, voffA);
;             PG8_WAIT_V(8); PG8_WAIT_L(0); PG8_BAR; PG8_MMA(1, 0, At, B0); PG8_MMA(1, 1, At, B1); PG8_BAR; PG8_SCHED;
	s_setprio 1
	s_waitcnt lgkmcnt(0)
	v_mfma_f32_16x16x32_bf16 v[140:143], v[86:89], v[188:191], v[140:143]
	v_mfma_f32_16x16x32_bf16 v[136:139], v[164:167], v[188:191], v[136:139]
	v_mfma_f32_16x16x32_bf16 v[124:127], v[86:89], v[212:215], v[124:127]
	v_mfma_f32_16x16x32_bf16 v[120:123], v[164:167], v[212:215], v[120:123]
	v_mfma_f32_16x16x32_bf16 v[108:111], v[86:89], v[220:223], v[108:111]
	v_mfma_f32_16x16x32_bf16 v[104:107], v[164:167], v[220:223], v[104:107]
	v_mfma_f32_16x16x32_bf16 v[76:79], v[86:89], v[228:231], v[76:79]
	v_mfma_f32_16x16x32_bf16 v[72:75], v[164:167], v[228:231], v[72:75]
	v_mfma_f32_16x16x32_bf16 v[140:143], v[90:93], v[208:211], v[140:143]
	v_mfma_f32_16x16x32_bf16 v[136:139], v[168:171], v[208:211], v[136:139]
	v_mfma_f32_16x16x32_bf16 v[124:127], v[90:93], v[216:219], v[124:127]
	v_mfma_f32_16x16x32_bf16 v[120:123], v[168:171], v[216:219], v[120:123]
	v_mfma_f32_16x16x32_bf16 v[108:111], v[90:93], v[224:227], v[108:111]
	v_mfma_f32_16x16x32_bf16 v[104:107], v[168:171], v[224:227], v[104:107]
	v_mfma_f32_16x16x32_bf16 v[76:79], v[90:93], v[242:245], v[76:79]
	v_mfma_f32_16x16x32_bf16 v[72:75], v[168:171], v[242:245], v[72:75]
	s_setprio 0
	s_setprio 1
	v_mfma_f32_16x16x32_bf16 v[132:135], v[172:175], v[188:191], v[132:135]
	v_mfma_f32_16x16x32_bf16 v[128:131], v[180:183], v[188:191], v[128:131]
	v_mfma_f32_16x16x32_bf16 v[116:119], v[172:175], v[212:215], v[116:119]
	v_mfma_f32_16x16x32_bf16 v[112:115], v[180:183], v[212:215], v[112:115]
	v_mfma_f32_16x16x32_bf16 v[100:103], v[172:175], v[220:223], v[100:103]
	v_mfma_f32_16x16x32_bf16 v[94:97], v[180:183], v[220:223], v[96:99]
	v_mfma_f32_16x16x32_bf16 v[68:71], v[172:175], v[228:231], v[68:71]
	v_mfma_f32_16x16x32_bf16 v[64:67], v[180:183], v[228:231], v[64:67]
	v_mfma_f32_16x16x32_bf16 v[132:135], v[176:179], v[208:211], v[132:135]
	v_mfma_f32_16x16x32_bf16 v[128:131], v[184:187], v[208:211], v[128:131]
	v_mfma_f32_16x16x32_bf16 v[116:119], v[176:179], v[216:219], v[116:119]
	v_mfma_f32_16x16x32_bf16 v[112:115], v[184:187], v[216:219], v[112:115]
	v_mfma_f32_16x16x32_bf16 v[100:103], v[176:179], v[224:227], v[100:103]
	v_mfma_f32_16x16x32_bf16 v[94:97], v[184:187], v[224:227], v[94:97]
	v_mfma_f32_16x16x32_bf16 v[68:71], v[176:179], v[242:245], v[68:71]
	v_mfma_f32_16x16x32_bf16 v[64:67], v[184:187], v[242:245], v[64:67]
	s_setprio 0
	s_barrier
	s_add_i32 s77, s77, s33
	v_lshl_add_u64 v[158:159], s[68:69], 0, v[192:193]
	s_mov_b32 m0, s77
	ds_read_b128 v[188:191], v163 offset:17408
	ds_read_b128 v[208:211], v163 offset:17472
	ds_read_b128 v[212:215], v163 offset:19584
	ds_read_b128 v[216:219], v163 offset:19648
	ds_read_b128 v[220:223], v163 offset:21760
	ds_read_b128 v[224:227], v163 offset:21824
	ds_read_b128 v[228:231], v163 offset:23936
	ds_read_b128 v[242:245], v163 offset:24000
	global_load_lds_dwordx4 v[158:159], off
	s_add_i32 m0, s77, 0x2200
	s_add_u32 s78, s68, 0x40000
	v_lshl_add_u64 v[198:199], s[68:69], 0, v[144:145]
	s_addc_u32 s79, s69, 0
	s_add_i32 s77, s89, s33
	global_load_lds_dwordx4 v[198:199], off
	v_lshl_add_u64 v[98:99], s[78:79], 0, v[192:193]
	s_mov_b32 m0, s77
	v_lshl_add_u64 v[200:201], s[70:71], 0, v[148:149]
	global_load_lds_dwordx4 v[98:99], off
	v_lshl_add_u64 v[98:99], s[78:79], 0, v[144:145]
	s_add_i32 m0, s77, 0x2200
	v_lshl_add_u64 v[232:233], s[70:71], 0, v[146:147]
	global_load_lds_dwordx4 v[98:99], off
	s_mov_b32 m0, s0
	s_nop 0
	global_load_lds_dwordx4 v[200:201], off
	s_mov_b32 m0, s5
	s_nop 0
	global_load_lds_dwordx4 v[232:233], off
	s_waitcnt vmcnt(8)
	s_waitcnt lgkmcnt(0)
	s_barrier
	s_setprio 1
	s_waitcnt lgkmcnt(0)
	v_mfma_f32_16x16x32_bf16 v[60:63], v[86:89], v[188:191], v[60:63]
	v_mfma_f32_16x16x32_bf16 v[56:59], v[164:167], v[188:191], v[56:59]
	v_mfma_f32_16x16x32_bf16 v[44:47], v[86:89], v[212:215], v[44:47]
	v_mfma_f32_16x16x32_bf16 v[40:43], v[164:167], v[212:215], v[40:43]
	v_mfma_f32_16x16x32_bf16 v[28:31], v[86:89], v[220:223], v[28:31]
	v_mfma_f32_16x16x32_bf16 v[24:27], v[164:167], v[220:223], v[24:27]
	v_mfma_f32_16x16x32_bf16 v[12:15], v[86:89], v[228:231], v[12:15]
	v_mfma_f32_16x16x32_bf16 v[8:11], v[164:167], v[228:231], v[8:11]
	v_mfma_f32_16x16x32_bf16 v[60:63], v[90:93], v[208:211], v[60:63]
	v_mfma_f32_16x16x32_bf16 v[56:59], v[168:171], v[208:211], v[56:59]
	v_mfma_f32_16x16x32_bf16 v[44:47], v[90:93], v[216:219], v[44:47]
	v_mfma_f32_16x16x32_bf16 v[40:43], v[168:171], v[216:219], v[40:43]
	v_mfma_f32_16x16x32_bf16 v[28:31], v[90:93], v[224:227], v[28:31]
	v_mfma_f32_16x16x32_bf16 v[24:27], v[168:171], v[224:227], v[24:27]
	v_mfma_f32_16x16x32_bf16 v[12:15], v[90:93], v[242:245], v[12:15]
	v_mfma_f32_16x16x32_bf16 v[8:11], v[168:171], v[242:245], v[8:11]
	s_setprio 0
	s_setprio 1
	v_mfma_f32_16x16x32_bf16 v[52:55], v[172:175], v[188:191], v[52:55]
	v_mfma_f32_16x16x32_bf16 v[48:51], v[180:183], v[188:191], v[48:51]
	v_mfma_f32_16x16x32_bf16 v[36:39], v[172:175], v[212:215], v[36:39]
	v_mfma_f32_16x16x32_bf16 v[32:35], v[180:183], v[212:215], v[32:35]
	v_mfma_f32_16x16x32_bf16 v[20:23], v[172:175], v[220:223], v[20:23]
	v_mfma_f32_16x16x32_bf16 v[16:19], v[180:183], v[220:223], v[16:19]
	v_mfma_f32_16x16x32_bf16 v[4:7], v[172:175], v[228:231], v[4:7]
	v_mfma_f32_16x16x32_bf16 v[0:3], v[180:183], v[228:231], v[0:3]
	v_mfma_f32_16x16x32_bf16 v[52:55], v[176:179], v[208:211], v[52:55]
	v_mfma_f32_16x16x32_bf16 v[48:51], v[184:187], v[208:211], v[48:51]
	v_mfma_f32_16x16x32_bf16 v[36:39], v[176:179], v[216:219], v[36:39]
	v_mfma_f32_16x16x32_bf16 v[32:35], v[184:187], v[216:219], v[32:35]
	v_mfma_f32_16x16x32_bf16 v[20:23], v[176:179], v[224:227], v[20:23]
	v_mfma_f32_16x16x32_bf16 v[16:19], v[184:187], v[224:227], v[16:19]
	v_mfma_f32_16x16x32_bf16 v[4:7], v[176:179], v[242:245], v[4:7]
	v_mfma_f32_16x16x32_bf16 v[0:3], v[184:187], v[242:245], v[0:3]
	s_setprio 0
	s_barrier
; #define PG8_STAGE(bufoff, gbase, voff) do { _Pragma("unroll") for (int _i = 0; _i < 2; ++_i) \
;         __builtin_amdgcn_global_load_lds((const unsigned*)((const char*)(gbase) + (voff)[_i]), (PG8_LAS unsigned*)(lds + (bufoff) + ldsw + _i * (8 * USTR)), 16, 0, 0); } while (0)
; #define PG8_LDA(dst, b, h) do { _Pragma("unroll") for (int m = 0; m < 4; ++m) _Pragma("unroll") for (int k = 0; k < 2; ++k) dst[m][k] = *(const PG8_LAS bf16x8*)(lds + PG8_SA(b, h) + aoff + m * (2 * USTR) + k * 64); } while (0)
; #define PG8_LDB(dst, b, h) do { _Pragma("unroll") for (int n = 0; n < 2; ++n) _Pragma("unroll") for (int k = 0; k < 2; ++k) dst[n][k] = *(const PG8_LAS bf16x8*)(lds + PG8_SB(b, h) + boff + n * (2 * USTR) + k * 64); } while (0)
; #define PG8_MMA(ai, bj, At, Bt) do { __builtin_amdgcn_s_setprio(1); _Pragma("unroll") for (int m = 0; m < 4; ++m) _Pragma("unroll") for (int n = 0; n < 2; ++n) _Pragma("unroll") for (int k = 0; k < 2; ++k) \
;         acc[ai][bj][m][n] = __builtin_amdgcn_mfma_f32_16x16x32_bf16(Bt[n][k], At[m][k], acc[ai][bj][m][n], 0, 0, 0); __builtin_amdgcn_s_setprio(0); } while (0)
; #define PG8_WAIT_V(n) asm volatile("s_waitcnt vmcnt(" #n ")" ::: "memory")
; #define PG8_WAIT_L(n) asm volatile("s_waitcnt lgkmcnt(" #n ")" ::: "memory")
; #define PG8_BAR __builtin_amdgcn_s_barrier()
; #define PG8_SCHED __builtin_amdgcn_sched_barrier(0)
; template <class Epi, class Sched, bool ALIGN_EPI, bool SP2>
; __device__ __forceinline__ void gemm_phase(PG8_LAS unsigned char* lds, const Gemm g, const Sched& S, const Epi& E, int wid) {
;     ...
;             PG8_WAIT_V(8); PG8_WAIT_L(0); PG8_BAR; PG8_MMA(1, 0, At, B0); PG8_MMA(1, 1, At, B1); PG8_BAR; PG8_SCHED;
;             PG8_LDB(B0, 1, 0); PG8_LDB(B1, 1, 1); PG8_SCHED; PG8_LDA(At, 1, 0); PG8_STAGE(PG8_SA(0, 1), a2 + hstepA, voffA);
;             PG8_WAIT_V(8); PG8_WAIT_L(0); PG8_BAR; PG8_MMA(0, 0, At, B0); PG8_MMA(0, 1, At, B1); PG8_BAR; PG8_SCHED;
	v_add_u32_e32 v98, 0x19800, v161
	ds_read_b128 v[86:89], v98
	ds_read_b128 v[90:93], v98 offset:64
	ds_read_b128 v[164:167], v98 offset:2176
	ds_read_b128 v[168:171], v98 offset:2240
	v_add_u32_e32 v98, 0x1dc00, v161
	ds_read_b128 v[172:175], v98
	ds_read_b128 v[176:179], v98 offset:64
	ds_read_b128 v[180:183], v98 offset:2176
	ds_read_b128 v[184:187], v98 offset:2240
	s_add_i32 s77, 0, 0x19800
	s_add_i32 s78, 0, 0x1dc00
	s_add_u32 s70, s70, 0x40000
	s_addc_u32 s71, s71, 0
	s_mov_b32 m0, s10
	v_lshl_add_u64 v[98:99], s[70:71], 0, v[148:149]
	ds_read_b128 v[188:191], v163 offset:34816
	ds_read_b128 v[208:211], v163 offset:34880
	ds_read_b128 v[212:215], v163 offset:36992
	ds_read_b128 v[216:219], v163 offset:37056
	ds_read_b128 v[220:223], v163 offset:39168
	ds_read_b128 v[224:227], v163 offset:39232
	ds_read_b128 v[228:231], v163 offset:41344
	ds_read_b128 v[242:245], v163 offset:41408
	global_load_lds_dwordx4 v[98:99], off
	v_lshl_add_u64 v[98:99], s[70:71], 0, v[146:147]
	s_mov_b32 m0, s29
	s_nop 0
	global_load_lds_dwordx4 v[98:99], off
	s_waitcnt vmcnt(8)
	s_waitcnt lgkmcnt(0)
	s_barrier
	s_setprio 1
	s_waitcnt lgkmcnt(0)
	v_mfma_f32_16x16x32_bf16 v[140:143], v[86:89], v[188:191], v[140:143]
	v_mfma_f32_16x16x32_bf16 v[136:139], v[164:167], v[188:191], v[136:139]
	v_mfma_f32_16x16x32_bf16 v[124:127], v[86:89], v[212:215], v[124:127]
	v_mfma_f32_16x16x32_bf16 v[120:123], v[164:167], v[212:215], v[120:123]
	v_mfma_f32_16x16x32_bf16 v[108:111], v[86:89], v[220:223], v[108:111]
	v_mfma_f32_16x16x32_bf16 v[104:107], v[164:167], v[220:223], v[104:107]
	v_mfma_f32_16x16x32_bf16 v[76:79], v[86:89], v[228:231], v[76:79]
	v_mfma_f32_16x16x32_bf16 v[72:75], v[164:167], v[228:231], v[72:75]
	v_mfma_f32_16x16x32_bf16 v[140:143], v[90:93], v[208:211], v[140:143]
	v_mfma_f32_16x16x32_bf16 v[136:139], v[168:171], v[208:211], v[136:139]
	v_mfma_f32_16x16x32_bf16 v[124:127], v[90:93], v[216:219], v[124:127]
	v_mfma_f32_16x16x32_bf16 v[120:123], v[168:171], v[216:219], v[120:123]
	v_mfma_f32_16x16x32_bf16 v[108:111], v[90:93], v[224:227], v[108:111]
	v_mfma_f32_16x16x32_bf16 v[104:107], v[168:171], v[224:227], v[104:107]
	v_mfma_f32_16x16x32_bf16 v[76:79], v[90:93], v[242:245], v[76:79]
	v_mfma_f32_16x16x32_bf16 v[72:75], v[168:171], v[242:245], v[72:75]
	s_setprio 0
	s_setprio 1
	v_mfma_f32_16x16x32_bf16 v[132:135], v[172:175], v[188:191], v[132:135]
	v_mfma_f32_16x16x32_bf16 v[128:131], v[180:183], v[188:191], v[128:131]
	v_mfma_f32_16x16x32_bf16 v[116:119], v[172:175], v[212:215], v[116:119]
	v_mfma_f32_16x16x32_bf16 v[112:115], v[180:183], v[212:215], v[112:115]
	v_mfma_f32_16x16x32_bf16 v[98:101], v[172:175], v[220:223], v[100:103]
	v_mfma_f32_16x16x32_bf16 v[94:97], v[180:183], v[220:223], v[94:97]
	v_mfma_f32_16x16x32_bf16 v[68:71], v[172:175], v[228:231], v[68:71]
	v_mfma_f32_16x16x32_bf16 v[64:67], v[180:183], v[228:231], v[64:67]
	v_mfma_f32_16x16x32_bf16 v[132:135], v[176:179], v[208:211], v[132:135]
	v_mfma_f32_16x16x32_bf16 v[128:131], v[184:187], v[208:211], v[128:131]
	v_mfma_f32_16x16x32_bf16 v[116:119], v[176:179], v[216:219], v[116:119]
	v_mfma_f32_16x16x32_bf16 v[112:115], v[184:187], v[216:219], v[112:115]
	v_mfma_f32_16x16x32_bf16 v[100:103], v[176:179], v[224:227], v[98:101]
	v_mfma_f32_16x16x32_bf16 v[96:99], v[184:187], v[224:227], v[94:97]
	v_mfma_f32_16x16x32_bf16 v[68:71], v[176:179], v[242:245], v[68:71]
	v_mfma_f32_16x16x32_bf16 v[64:67], v[184:187], v[242:245], v[64:67]
	s_setprio 0
	s_barrier
; #define PG8_STAGE(bufoff, gbase, voff) do { _Pragma("unroll") for (int _i = 0; _i < 2; ++_i) \
;         __builtin_amdgcn_global_load_lds((const unsigned*)((const char*)(gbase) + (voff)[_i]), (PG8_LAS unsigned*)(lds + (bufoff) + ldsw + _i * (8 * USTR)), 16, 0, 0); } while (0)
; #define PG8_LDA(dst, b, h) do { _Pragma("unroll") for (int m = 0; m < 4; ++m) _Pragma("unroll") for (int k = 0; k < 2; ++k) dst[m][k] = *(const PG8_LAS bf16x8*)(lds + PG8_SA(b, h) + aoff + m * (2 * USTR) + k * 64); } while (0)
; #define PG8_MMA(ai, bj, At, Bt) do { __builtin_amdgcn_s_setprio(1); _Pragma("unroll") for (int m = 0; m < 4; ++m) _Pragma("unroll") for (int n = 0; n < 2; ++n) _Pragma("unroll") for (int k = 0; k < 2; ++k) \
;         acc[ai][bj][m][n] = __builtin_amdgcn_mfma_f32_16x16x32_bf16(Bt[n][k], At[m][k], acc[ai][bj][m][n], 0, 0, 0); __builtin_amdgcn_s_setprio(0); } while (0)
; #define PG8_WAIT_V(n) asm volatile("s_waitcnt vmcnt(" #n ")" ::: "memory")
; #define PG8_WAIT_L(n) asm volatile("s_waitcnt lgkmcnt(" #n ")" ::: "memory")
; #define PG8_BAR __builtin_amdgcn_s_barrier()
; #define PG8_SCHED __builtin_amdgcn_sched_barrier(0)
; template <class Epi, class Sched, bool ALIGN_EPI, bool SP2>
; __device__ __forceinline__ void gemm_phase(PG8_LAS unsigned char* lds, const Gemm g, const Sched& S, const Epi& E, int wid) {
;     ...
;         for (int t = 0; t < nt; t += 2) {
;     ...
;             PG8_LDA(At, 1, 1); PG8_STAGE(PG8_SB(1, 0), b3, voffB); PG8_STAGE(PG8_SB(1, 1), b3 + hstepB, voffB); PG8_STAGE(PG8_SA(1, 0), a3, voffA);
;             PG8_WAIT_V(8); PG8_WAIT_L(0); PG8_BAR; PG8_MMA(1, 0, At, B0); PG8_MMA(1, 1, At, B1); PG8_BAR; PG8_SCHED;
	s_add_i32 s70, s77, s33
	v_lshl_add_u64 v[94:95], v[158:159], 0, s[6:7]
	s_mov_b32 m0, s70
	ds_read_b128 v[188:191], v163 offset:52224
	ds_read_b128 v[208:211], v163 offset:52288
	ds_read_b128 v[212:215], v163 offset:54400
	ds_read_b128 v[216:219], v163 offset:54464
	ds_read_b128 v[220:223], v163 offset:56576
	ds_read_b128 v[224:227], v163 offset:56640
	ds_read_b128 v[228:231], v163 offset:58752
	ds_read_b128 v[242:245], v163 offset:58816
	global_load_lds_dwordx4 v[94:95], off
	s_add_i32 m0, s70, 0x2200
	s_add_u32 s68, s68, 0x40080
	v_lshl_add_u64 v[94:95], v[198:199], 0, s[6:7]
	s_addc_u32 s69, s69, 0
	s_add_i32 s70, s78, s33
	global_load_lds_dwordx4 v[94:95], off
	v_lshl_add_u64 v[94:95], s[68:69], 0, v[192:193]
	s_mov_b32 m0, s70
	s_nop 0
	global_load_lds_dwordx4 v[94:95], off
	v_lshl_add_u64 v[94:95], s[68:69], 0, v[144:145]
	s_add_i32 m0, s70, 0x2200
	s_nop 0
	global_load_lds_dwordx4 v[94:95], off
	v_lshl_add_u64 v[94:95], v[200:201], 0, s[6:7]
	s_mov_b32 m0, s56
	s_nop 0
	global_load_lds_dwordx4 v[94:95], off
	v_lshl_add_u64 v[94:95], v[232:233], 0, s[6:7]
	s_mov_b32 m0, s57
	s_nop 0
	global_load_lds_dwordx4 v[94:95], off
	s_add_i32 s76, s76, 2
	s_add_u32 s38, s38, 0x100
	s_addc_u32 s39, s39, 0
	s_add_u32 s74, s74, 0x100
	s_addc_u32 s75, s75, 0
	s_waitcnt vmcnt(8)
	s_waitcnt lgkmcnt(0)
	s_barrier
	s_setprio 1
	s_waitcnt lgkmcnt(0)
	v_mfma_f32_16x16x32_bf16 v[60:63], v[86:89], v[188:191], v[60:63]
	v_mfma_f32_16x16x32_bf16 v[56:59], v[164:167], v[188:191], v[56:59]
	v_mfma_f32_16x16x32_bf16 v[44:47], v[86:89], v[212:215], v[44:47]
	v_mfma_f32_16x16x32_bf16 v[40:43], v[164:167], v[212:215], v[40:43]
	v_mfma_f32_16x16x32_bf16 v[28:31], v[86:89], v[220:223], v[28:31]
	v_mfma_f32_16x16x32_bf16 v[24:27], v[164:167], v[220:223], v[24:27]
	v_mfma_f32_16x16x32_bf16 v[12:15], v[86:89], v[228:231], v[12:15]
	v_mfma_f32_16x16x32_bf16 v[8:11], v[164:167], v[228:231], v[8:11]
	v_mfma_f32_16x16x32_bf16 v[60:63], v[90:93], v[208:211], v[60:63]
	v_mfma_f32_16x16x32_bf16 v[56:59], v[168:171], v[208:211], v[56:59]
	v_mfma_f32_16x16x32_bf16 v[44:47], v[90:93], v[216:219], v[44:47]
	v_mfma_f32_16x16x32_bf16 v[40:43], v[168:171], v[216:219], v[40:43]
	v_mfma_f32_16x16x32_bf16 v[28:31], v[90:93], v[224:227], v[28:31]
	v_mfma_f32_16x16x32_bf16 v[24:27], v[168:171], v[224:227], v[24:27]
	v_mfma_f32_16x16x32_bf16 v[12:15], v[90:93], v[242:245], v[12:15]
	v_mfma_f32_16x16x32_bf16 v[8:11], v[168:171], v[242:245], v[8:11]
	s_setprio 0
	s_setprio 1
	v_mfma_f32_16x16x32_bf16 v[52:55], v[172:175], v[188:191], v[52:55]
	v_mfma_f32_16x16x32_bf16 v[48:51], v[180:183], v[188:191], v[48:51]
	v_mfma_f32_16x16x32_bf16 v[36:39], v[172:175], v[212:215], v[36:39]
	v_mfma_f32_16x16x32_bf16 v[32:35], v[180:183], v[212:215], v[32:35]
	v_mfma_f32_16x16x32_bf16 v[20:23], v[172:175], v[220:223], v[20:23]
	v_mfma_f32_16x16x32_bf16 v[16:19], v[180:183], v[220:223], v[16:19]
	v_mfma_f32_16x16x32_bf16 v[4:7], v[172:175], v[228:231], v[4:7]
	v_mfma_f32_16x16x32_bf16 v[0:3], v[180:183], v[228:231], v[0:3]
	v_mfma_f32_16x16x32_bf16 v[52:55], v[176:179], v[208:211], v[52:55]
	v_mfma_f32_16x16x32_bf16 v[48:51], v[184:187], v[208:211], v[48:51]
	v_mfma_f32_16x16x32_bf16 v[36:39], v[176:179], v[216:219], v[36:39]
	v_mfma_f32_16x16x32_bf16 v[32:35], v[184:187], v[216:219], v[32:35]
	v_mfma_f32_16x16x32_bf16 v[20:23], v[176:179], v[224:227], v[20:23]
	v_mfma_f32_16x16x32_bf16 v[16:19], v[184:187], v[224:227], v[16:19]
	v_mfma_f32_16x16x32_bf16 v[4:7], v[176:179], v[242:245], v[4:7]
	v_mfma_f32_16x16x32_bf16 v[0:3], v[184:187], v[242:245], v[0:3]
	s_setprio 0
	s_barrier
	s_cmp_gt_u32 s76, 13
	s_cbranch_scc1 .LBB0_377

; #define PG8_STAGE(bufoff, gbase, voff) do { _Pragma("unroll") for (int _i = 0; _i < 2; ++_i) \
;         __builtin_amdgcn_global_load_lds((const unsigned*)((const char*)(gbase) + (voff)[_i]), (PG8_LAS unsigned*)(lds + (bufoff) + ldsw + _i * (8 * USTR)), 16, 0, 0); } while (0)
; #define PG8_LDA(dst, b, h) do { _Pragma("unroll") for (int m = 0; m < 4; ++m) _Pragma("unroll") for (int k = 0; k < 2; ++k) dst[m][k] = *(const PG8_LAS bf16x8*)(lds + PG8_SA(b, h) + aoff + m * (2 * USTR) + k * 64); } while (0)
; #define PG8_LDB(dst, b, h) do { _Pragma("unroll") for (int n = 0; n < 2; ++n) _Pragma("unroll") for (int k = 0; k < 2; ++k) dst[n][k] = *(const PG8_LAS bf16x8*)(lds + PG8_SB(b, h) + boff + n * (2 * USTR) + k * 64); } while (0)
; #define PG8_MMA(ai, bj, At, Bt) do { __builtin_amdgcn_s_setprio(1); _Pragma("unroll") for (int m = 0; m < 4; ++m) _Pragma("unroll") for (int n = 0; n < 2; ++n) _Pragma("unroll") for (int k = 0; k < 2; ++k) \
;         acc[ai][bj][m][n] = __builtin_amdgcn_mfma_f32_16x16x32_bf16(Bt[n][k], At[m][k], acc[ai][bj][m][n], 0, 0, 0); __builtin_amdgcn_s_setprio(0); } while (0)
; #define PG8_WAIT_V(n) asm volatile("s_waitcnt vmcnt(" #n ")" ::: "memory")
; #define PG8_WAIT_L(n) asm volatile("s_waitcnt lgkmcnt(" #n ")" ::: "memory")
; #define PG8_BAR __builtin_amdgcn_s_barrier()
; #define PG8_SCHED __builtin_amdgcn_sched_barrier(0)
; template <class Epi, class Sched, bool ALIGN_EPI, bool SP2>
; __device__ __forceinline__ void gemm_phase(PG8_LAS unsigned char* lds, const Gemm g, const Sched& S, const Epi& E, int wid) {
;     ...
;             PG8_LDB(B0, 0, 0); PG8_LDB(B1, 0, 1); PG8_SCHED; PG8_LDA(At, 0, 0); PG8_STAGE(PG8_SA(1, 1), a1 + hstepA, voffA);
;             PG8_WAIT_V(8); PG8_WAIT_L(0); PG8_BAR; PG8_MMA(0, 0, At, B0); PG8_MMA(0, 1, At, B1); PG8_BAR; PG8_SCHED;
;             PG8_LDA(At, 0, 1); PG8_STAGE(PG8_SB(0, 0), b2, voffB); PG8_STAGE(PG8_SB(0, 1), b2 + hstepB, voffB); PG8_STAGE(PG8_SA(0, 0), a2, voffA);
;             PG8_WAIT_V(8); PG8_WAIT_L(0); PG8_BAR; PG8_MMA(1, 0, At, B0); PG8_MMA(1, 1, At, B1); PG8_BAR; PG8_SCHED;
.Lhb_mixin:
	v_add_u32_e32 v30, 0x11000, v197
	s_add_i32 s73, 0, 0x11000
	s_add_i32 vcc_lo, 0, 0x15400
	ds_read_b128 v[22:25], v30
	ds_read_b128 v[26:29], v30 offset:64
	ds_read_b128 v[158:161], v30 offset:2176
	ds_read_b128 v[162:165], v30 offset:2240
	v_add_u32_e32 v30, vcc_lo, v197
	ds_read_b128 v[166:169], v30
	ds_read_b128 v[170:173], v30 offset:64
	ds_read_b128 v[174:177], v30 offset:2176
	ds_read_b128 v[178:181], v30 offset:2240
	v_lshl_add_u64 v[30:31], s[38:39], 0, v[154:155]
	s_add_i32 m0, s95, 0xcc00
	ds_read_b128 v[182:185], v210
	ds_read_b128 v[186:189], v210 offset:64
	ds_read_b128 v[212:215], v210 offset:2176
	ds_read_b128 v[216:219], v210 offset:2240
	ds_read_b128 v[220:223], v210 offset:4352
	ds_read_b128 v[224:227], v210 offset:4416
	ds_read_b128 v[228:231], v210 offset:6528
	ds_read_b128 v[242:245], v210 offset:6592
	global_load_lds_dwordx4 v[30:31], off
	v_lshl_add_u64 v[30:31], s[38:39], 0, v[156:157]
	s_add_i32 m0, s95, 0xee00
	s_nop 0
	global_load_lds_dwordx4 v[30:31], off
	s_cmp_eq_u32 s71, 12
	s_cselect_b64 s[40:41], -1, 0
	s_add_u32 s42, s38, 0xfffc0080
	s_addc_u32 s43, s39, -1
	s_and_b64 s[40:41], s[40:41], exec
	s_cselect_b32 s43, s10, s43
	s_cselect_b32 s42, s44, s42
	s_cselect_b32 s41, s45, s70
	s_cselect_b32 s40, s69, s23
	s_waitcnt vmcnt(8)
	s_waitcnt lgkmcnt(0)
	s_barrier
	s_setprio 1
	s_waitcnt lgkmcnt(0)
	v_mfma_f32_16x16x32_bf16 v[140:143], v[22:25], v[182:185], 0
	v_mfma_f32_16x16x32_bf16 v[136:139], v[158:161], v[182:185], 0
	v_mfma_f32_16x16x32_bf16 v[124:127], v[22:25], v[212:215], 0
	v_mfma_f32_16x16x32_bf16 v[120:123], v[158:161], v[212:215], 0
	v_mfma_f32_16x16x32_bf16 v[108:111], v[22:25], v[220:223], 0
	v_mfma_f32_16x16x32_bf16 v[104:107], v[158:161], v[220:223], 0
	v_mfma_f32_16x16x32_bf16 v[92:95], v[22:25], v[228:231], 0
	v_mfma_f32_16x16x32_bf16 v[88:91], v[158:161], v[228:231], 0
	v_mfma_f32_16x16x32_bf16 v[140:143], v[26:29], v[186:189], v[140:143]
	v_mfma_f32_16x16x32_bf16 v[136:139], v[162:165], v[186:189], v[136:139]
	v_mfma_f32_16x16x32_bf16 v[124:127], v[26:29], v[216:219], v[124:127]
	v_mfma_f32_16x16x32_bf16 v[120:123], v[162:165], v[216:219], v[120:123]
	v_mfma_f32_16x16x32_bf16 v[108:111], v[26:29], v[224:227], v[108:111]
	v_mfma_f32_16x16x32_bf16 v[104:107], v[162:165], v[224:227], v[104:107]
	v_mfma_f32_16x16x32_bf16 v[92:95], v[26:29], v[242:245], v[92:95]
	v_mfma_f32_16x16x32_bf16 v[88:91], v[162:165], v[242:245], v[88:91]
	s_setprio 0
	s_setprio 1
	v_mfma_f32_16x16x32_bf16 v[132:135], v[166:169], v[182:185], 0
	v_mfma_f32_16x16x32_bf16 v[128:131], v[174:177], v[182:185], 0
	v_mfma_f32_16x16x32_bf16 v[116:119], v[166:169], v[212:215], 0
	v_mfma_f32_16x16x32_bf16 v[112:115], v[174:177], v[212:215], 0
	v_mfma_f32_16x16x32_bf16 v[100:103], v[166:169], v[220:223], 0
	v_mfma_f32_16x16x32_bf16 v[96:99], v[174:177], v[220:223], 0
	v_mfma_f32_16x16x32_bf16 v[84:87], v[166:169], v[228:231], 0
	v_mfma_f32_16x16x32_bf16 v[80:83], v[174:177], v[228:231], 0
	v_mfma_f32_16x16x32_bf16 v[132:135], v[170:173], v[186:189], v[132:135]
	v_mfma_f32_16x16x32_bf16 v[128:131], v[178:181], v[186:189], v[128:131]
	v_mfma_f32_16x16x32_bf16 v[116:119], v[170:173], v[216:219], v[116:119]
	v_mfma_f32_16x16x32_bf16 v[112:115], v[178:181], v[216:219], v[112:115]
	v_mfma_f32_16x16x32_bf16 v[100:103], v[170:173], v[224:227], v[100:103]
	v_mfma_f32_16x16x32_bf16 v[96:99], v[178:181], v[224:227], v[96:99]
	v_mfma_f32_16x16x32_bf16 v[84:87], v[170:173], v[242:245], v[84:87]
	v_mfma_f32_16x16x32_bf16 v[80:83], v[178:181], v[242:245], v[80:83]
	s_setprio 0
	s_barrier
	s_add_i32 s73, s73, s33
	v_lshl_add_u64 v[190:191], s[40:41], 0, v[192:193]
	s_mov_b32 m0, s73
	ds_read_b128 v[182:185], v210 offset:17408
	ds_read_b128 v[186:189], v210 offset:17472
	ds_read_b128 v[212:215], v210 offset:19584
	ds_read_b128 v[216:219], v210 offset:19648
	ds_read_b128 v[220:223], v210 offset:21760
	ds_read_b128 v[224:227], v210 offset:21824
	ds_read_b128 v[228:231], v210 offset:23936
	ds_read_b128 v[242:245], v210 offset:24000
	global_load_lds_dwordx4 v[190:191], off
	s_add_i32 m0, s73, 0x2200
	s_add_u32 s76, s40, 0x40000
	v_lshl_add_u64 v[198:199], s[40:41], 0, v[146:147]
	s_addc_u32 s77, s41, 0
	s_add_i32 s73, vcc_lo, s33
	global_load_lds_dwordx4 v[198:199], off
	v_lshl_add_u64 v[30:31], s[76:77], 0, v[192:193]
	s_mov_b32 m0, s73
	v_lshl_add_u64 v[200:201], s[42:43], 0, v[150:151]
	global_load_lds_dwordx4 v[30:31], off
	v_lshl_add_u64 v[30:31], s[76:77], 0, v[146:147]
	s_add_i32 m0, s73, 0x2200
	v_lshl_add_u64 v[208:209], s[42:43], 0, v[148:149]
	global_load_lds_dwordx4 v[30:31], off
	s_mov_b32 m0, s95
	s_nop 0
	global_load_lds_dwordx4 v[200:201], off
	s_mov_b32 m0, s5
	s_nop 0
	global_load_lds_dwordx4 v[208:209], off
	s_waitcnt vmcnt(8)
	s_waitcnt lgkmcnt(0)
	s_barrier
; #define PG8_STAGE(bufoff, gbase, voff) do { _Pragma("unroll") for (int _i = 0; _i < 2; ++_i) \
;         __builtin_amdgcn_global_load_lds((const unsigned*)((const char*)(gbase) + (voff)[_i]), (PG8_LAS unsigned*)(lds + (bufoff) + ldsw + _i * (8 * USTR)), 16, 0, 0); } while (0)
; #define PG8_LDA(dst, b, h) do { _Pragma("unroll") for (int m = 0; m < 4; ++m) _Pragma("unroll") for (int k = 0; k < 2; ++k) dst[m][k] = *(const PG8_LAS bf16x8*)(lds + PG8_SA(b, h) + aoff + m * (2 * USTR) + k * 64); } while (0)
; #define PG8_LDB(dst, b, h) do { _Pragma("unroll") for (int n = 0; n < 2; ++n) _Pragma("unroll") for (int k = 0; k < 2; ++k) dst[n][k] = *(const PG8_LAS bf16x8*)(lds + PG8_SB(b, h) + boff + n * (2 * USTR) + k * 64); } while (0)
; #define PG8_MMA(ai, bj, At, Bt) do { __builtin_amdgcn_s_setprio(1); _Pragma("unroll") for (int m = 0; m < 4; ++m) _Pragma("unroll") for (int n = 0; n < 2; ++n) _Pragma("unroll") for (int k = 0; k < 2; ++k) \
;         acc[ai][bj][m][n] = __builtin_amdgcn_mfma_f32_16x16x32_bf16(Bt[n][k], At[m][k], acc[ai][bj][m][n], 0, 0, 0); __builtin_amdgcn_s_setprio(0); } while (0)
; #define PG8_WAIT_V(n) asm volatile("s_waitcnt vmcnt(" #n ")" ::: "memory")
; #define PG8_WAIT_L(n) asm volatile("s_waitcnt lgkmcnt(" #n ")" ::: "memory")
; #define PG8_BAR __builtin_amdgcn_s_barrier()
; #define PG8_SCHED __builtin_amdgcn_sched_barrier(0)
; template <class Epi, class Sched, bool ALIGN_EPI, bool SP2>
; __device__ __forceinline__ void gemm_phase(PG8_LAS unsigned char* lds, const Gemm g, const Sched& S, const Epi& E, int wid) {
;     ...
;             PG8_WAIT_V(8); PG8_WAIT_L(0); PG8_BAR; PG8_MMA(1, 0, At, B0); PG8_MMA(1, 1, At, B1); PG8_BAR; PG8_SCHED;
;             PG8_LDB(B0, 1, 0); PG8_LDB(B1, 1, 1); PG8_SCHED; PG8_LDA(At, 1, 0); PG8_STAGE(PG8_SA(0, 1), a2 + hstepA, voffA);
;             PG8_WAIT_V(8); PG8_WAIT_L(0); PG8_BAR; PG8_MMA(0, 0, At, B0); PG8_MMA(0, 1, At, B1); PG8_BAR; PG8_SCHED;
	s_setprio 1
	s_waitcnt lgkmcnt(0)
	v_mfma_f32_16x16x32_bf16 v[76:79], v[22:25], v[182:185], 0
	v_mfma_f32_16x16x32_bf16 v[72:75], v[158:161], v[182:185], 0
	v_mfma_f32_16x16x32_bf16 v[60:63], v[22:25], v[212:215], 0
	v_mfma_f32_16x16x32_bf16 v[56:59], v[158:161], v[212:215], 0
	v_mfma_f32_16x16x32_bf16 v[44:47], v[22:25], v[220:223], 0
	v_mfma_f32_16x16x32_bf16 v[40:43], v[158:161], v[220:223], 0
	v_mfma_f32_16x16x32_bf16 v[12:15], v[22:25], v[228:231], 0
	v_mfma_f32_16x16x32_bf16 v[8:11], v[158:161], v[228:231], 0
	v_mfma_f32_16x16x32_bf16 v[76:79], v[26:29], v[186:189], v[76:79]
	v_mfma_f32_16x16x32_bf16 v[72:75], v[162:165], v[186:189], v[72:75]
	v_mfma_f32_16x16x32_bf16 v[60:63], v[26:29], v[216:219], v[60:63]
	v_mfma_f32_16x16x32_bf16 v[56:59], v[162:165], v[216:219], v[56:59]
	v_mfma_f32_16x16x32_bf16 v[44:47], v[26:29], v[224:227], v[44:47]
	v_mfma_f32_16x16x32_bf16 v[40:43], v[162:165], v[224:227], v[40:43]
	v_mfma_f32_16x16x32_bf16 v[12:15], v[26:29], v[242:245], v[12:15]
	v_mfma_f32_16x16x32_bf16 v[8:11], v[162:165], v[242:245], v[8:11]
	s_setprio 0
	s_setprio 1
	v_mfma_f32_16x16x32_bf16 v[52:55], v[166:169], v[212:215], 0
	v_mfma_f32_16x16x32_bf16 v[48:51], v[174:177], v[212:215], 0
	v_mfma_f32_16x16x32_bf16 v[36:39], v[166:169], v[220:223], 0
	v_mfma_f32_16x16x32_bf16 v[30:33], v[174:177], v[220:223], 0
	v_mfma_f32_16x16x32_bf16 v[4:7], v[166:169], v[228:231], 0
	v_mfma_f32_16x16x32_bf16 v[0:3], v[174:177], v[228:231], 0
	v_mfma_f32_16x16x32_bf16 v[22:25], v[166:169], v[182:185], 0
	v_mfma_f32_16x16x32_bf16 v[26:29], v[174:177], v[182:185], 0
	v_mfma_f32_16x16x32_bf16 v[52:55], v[170:173], v[216:219], v[52:55]
	v_mfma_f32_16x16x32_bf16 v[48:51], v[178:181], v[216:219], v[48:51]
	v_mfma_f32_16x16x32_bf16 v[36:39], v[170:173], v[224:227], v[36:39]
	v_mfma_f32_16x16x32_bf16 v[30:33], v[178:181], v[224:227], v[30:33]
	v_mfma_f32_16x16x32_bf16 v[4:7], v[170:173], v[242:245], v[4:7]
	v_mfma_f32_16x16x32_bf16 v[0:3], v[178:181], v[242:245], v[0:3]
	v_mfma_f32_16x16x32_bf16 v[22:25], v[170:173], v[186:189], v[22:25]
	v_mfma_f32_16x16x32_bf16 v[26:29], v[178:181], v[186:189], v[26:29]
	s_setprio 0
	s_barrier
	v_add_u32_e32 v34, 0x19800, v197
	ds_read_b128 v[64:67], v34
	ds_read_b128 v[68:71], v34 offset:64
	ds_read_b128 v[158:161], v34 offset:2176
	ds_read_b128 v[162:165], v34 offset:2240
	v_add_u32_e32 v34, 0x1dc00, v197
	ds_read_b128 v[166:169], v34
	ds_read_b128 v[170:173], v34 offset:64
	ds_read_b128 v[174:177], v34 offset:2176
	ds_read_b128 v[178:181], v34 offset:2240
	s_add_i32 s73, 0, 0x19800
	s_add_i32 s76, 0, 0x1dc00
	s_add_u32 s42, s42, 0x40000
	s_addc_u32 s43, s43, 0
	s_mov_b32 m0, s56
	v_lshl_add_u64 v[34:35], s[42:43], 0, v[150:151]
	ds_read_b128 v[182:185], v210 offset:34816
	ds_read_b128 v[186:189], v210 offset:34880
	ds_read_b128 v[212:215], v210 offset:36992
	ds_read_b128 v[216:219], v210 offset:37056
	ds_read_b128 v[220:223], v210 offset:39168
	ds_read_b128 v[224:227], v210 offset:39232
	ds_read_b128 v[228:231], v210 offset:41344
	ds_read_b128 v[242:245], v210 offset:41408
	global_load_lds_dwordx4 v[34:35], off
	v_lshl_add_u64 v[34:35], s[42:43], 0, v[148:149]
	s_mov_b32 m0, s57
	s_nop 0
	global_load_lds_dwordx4 v[34:35], off
	s_waitcnt vmcnt(8)
	s_waitcnt lgkmcnt(0)
	s_barrier
	s_setprio 1
	s_waitcnt lgkmcnt(0)
	v_mfma_f32_16x16x32_bf16 v[140:143], v[64:67], v[182:185], v[140:143]
	v_mfma_f32_16x16x32_bf16 v[136:139], v[158:161], v[182:185], v[136:139]
	v_mfma_f32_16x16x32_bf16 v[124:127], v[64:67], v[212:215], v[124:127]
	v_mfma_f32_16x16x32_bf16 v[120:123], v[158:161], v[212:215], v[120:123]
	v_mfma_f32_16x16x32_bf16 v[108:111], v[64:67], v[220:223], v[108:111]
	v_mfma_f32_16x16x32_bf16 v[104:107], v[158:161], v[220:223], v[104:107]
	v_mfma_f32_16x16x32_bf16 v[92:95], v[64:67], v[228:231], v[92:95]
	v_mfma_f32_16x16x32_bf16 v[88:91], v[158:161], v[228:231], v[88:91]
	v_mfma_f32_16x16x32_bf16 v[140:143], v[68:71], v[186:189], v[140:143]
	v_mfma_f32_16x16x32_bf16 v[136:139], v[162:165], v[186:189], v[136:139]
	v_mfma_f32_16x16x32_bf16 v[124:127], v[68:71], v[216:219], v[124:127]
	v_mfma_f32_16x16x32_bf16 v[120:123], v[162:165], v[216:219], v[120:123]
	v_mfma_f32_16x16x32_bf16 v[108:111], v[68:71], v[224:227], v[108:111]
	v_mfma_f32_16x16x32_bf16 v[104:107], v[162:165], v[224:227], v[104:107]
	v_mfma_f32_16x16x32_bf16 v[92:95], v[68:71], v[242:245], v[92:95]
	v_mfma_f32_16x16x32_bf16 v[88:91], v[162:165], v[242:245], v[88:91]
	s_setprio 0
	s_setprio 1
	v_mfma_f32_16x16x32_bf16 v[132:135], v[166:169], v[182:185], v[132:135]
	v_mfma_f32_16x16x32_bf16 v[128:131], v[174:177], v[182:185], v[128:131]
	v_mfma_f32_16x16x32_bf16 v[116:119], v[166:169], v[212:215], v[116:119]
	v_mfma_f32_16x16x32_bf16 v[112:115], v[174:177], v[212:215], v[112:115]
	v_mfma_f32_16x16x32_bf16 v[100:103], v[166:169], v[220:223], v[100:103]
	v_mfma_f32_16x16x32_bf16 v[96:99], v[174:177], v[220:223], v[96:99]
	v_mfma_f32_16x16x32_bf16 v[84:87], v[166:169], v[228:231], v[84:87]
	v_mfma_f32_16x16x32_bf16 v[80:83], v[174:177], v[228:231], v[80:83]
	v_mfma_f32_16x16x32_bf16 v[132:135], v[170:173], v[186:189], v[132:135]
	v_mfma_f32_16x16x32_bf16 v[128:131], v[178:181], v[186:189], v[128:131]
	v_mfma_f32_16x16x32_bf16 v[116:119], v[170:173], v[216:219], v[116:119]
	v_mfma_f32_16x16x32_bf16 v[112:115], v[178:181], v[216:219], v[112:115]
	v_mfma_f32_16x16x32_bf16 v[100:103], v[170:173], v[224:227], v[100:103]
	v_mfma_f32_16x16x32_bf16 v[96:99], v[178:181], v[224:227], v[96:99]
	v_mfma_f32_16x16x32_bf16 v[84:87], v[170:173], v[242:245], v[84:87]
	v_mfma_f32_16x16x32_bf16 v[80:83], v[178:181], v[242:245], v[80:83]
	s_setprio 0
	s_barrier
; #define PG8_STAGE(bufoff, gbase, voff) do { _Pragma("unroll") for (int _i = 0; _i < 2; ++_i) \
;         __builtin_amdgcn_global_load_lds((const unsigned*)((const char*)(gbase) + (voff)[_i]), (PG8_LAS unsigned*)(lds + (bufoff) + ldsw + _i * (8 * USTR)), 16, 0, 0); } while (0)
; #define PG8_LDA(dst, b, h) do { _Pragma("unroll") for (int m = 0; m < 4; ++m) _Pragma("unroll") for (int k = 0; k < 2; ++k) dst[m][k] = *(const PG8_LAS bf16x8*)(lds + PG8_SA(b, h) + aoff + m * (2 * USTR) + k * 64); } while (0)
; #define PG8_LDB(dst, b, h) do { _Pragma("unroll") for (int n = 0; n < 2; ++n) _Pragma("unroll") for (int k = 0; k < 2; ++k) dst[n][k] = *(const PG8_LAS bf16x8*)(lds + PG8_SB(b, h) + boff + n * (2 * USTR) + k * 64); } while (0)
; #define PG8_MMA(ai, bj, At, Bt) do { __builtin_amdgcn_s_setprio(1); _Pragma("unroll") for (int m = 0; m < 4; ++m) _Pragma("unroll") for (int n = 0; n < 2; ++n) _Pragma("unroll") for (int k = 0; k < 2; ++k) \
;         acc[ai][bj][m][n] = __builtin_amdgcn_mfma_f32_16x16x32_bf16(Bt[n][k], At[m][k], acc[ai][bj][m][n], 0, 0, 0); __builtin_amdgcn_s_setprio(0); } while (0)
; #define PG8_WAIT_V(n) asm volatile("s_waitcnt vmcnt(" #n ")" ::: "memory")
; #define PG8_WAIT_L(n) asm volatile("s_waitcnt lgkmcnt(" #n ")" ::: "memory")
; #define PG8_BAR __builtin_amdgcn_s_barrier()
; #define PG8_SCHED __builtin_amdgcn_sched_barrier(0)
; template <class Epi, class Sched, bool ALIGN_EPI, bool SP2>
; __device__ __forceinline__ void gemm_phase(PG8_LAS unsigned char* lds, const Gemm g, const Sched& S, const Epi& E, int wid) {
;     ...
;             PG8_LDB(B0, 0, 0); PG8_LDB(B1, 0, 1); PG8_SCHED; PG8_LDA(At, 0, 0); PG8_STAGE(PG8_SA(1, 1), a1 + hstepA, voffA);
;             PG8_WAIT_V(8); PG8_WAIT_L(0); PG8_BAR; PG8_MMA(0, 0, At, B0); PG8_MMA(0, 1, At, B1); PG8_BAR; PG8_SCHED;
;             PG8_LDA(At, 0, 1); PG8_STAGE(PG8_SB(0, 0), b2, voffB); PG8_STAGE(PG8_SB(0, 1), b2 + hstepB, voffB); PG8_STAGE(PG8_SA(0, 0), a2, voffA);
;     ...
;             PG8_LDA(At, 1, 1); PG8_STAGE(PG8_SB(1, 0), b3, voffB); PG8_STAGE(PG8_SB(1, 1), b3 + hstepB, voffB); PG8_STAGE(PG8_SA(1, 0), a3, voffA);
;             PG8_WAIT_V(8); PG8_WAIT_L(0); PG8_BAR; PG8_MMA(1, 0, At, B0); PG8_MMA(1, 1, At, B1); PG8_BAR; PG8_SCHED;
	s_add_i32 s42, s73, s33
	v_lshl_add_u64 v[34:35], v[190:191], 0, s[6:7]
	s_mov_b32 m0, s42
	ds_read_b128 v[182:185], v210 offset:52224
	ds_read_b128 v[186:189], v210 offset:52288
	ds_read_b128 v[212:215], v210 offset:54400
	ds_read_b128 v[216:219], v210 offset:54464
	ds_read_b128 v[220:223], v210 offset:56576
	ds_read_b128 v[224:227], v210 offset:56640
	ds_read_b128 v[228:231], v210 offset:58752
	ds_read_b128 v[242:245], v210 offset:58816
	global_load_lds_dwordx4 v[34:35], off
	s_add_i32 m0, s42, 0x2200
	s_add_u32 s40, s40, 0x40080
	v_lshl_add_u64 v[34:35], v[198:199], 0, s[6:7]
	s_addc_u32 s41, s41, 0
	s_add_i32 s42, s76, s33
	global_load_lds_dwordx4 v[34:35], off
	v_lshl_add_u64 v[34:35], s[40:41], 0, v[192:193]
	s_mov_b32 m0, s42
	s_nop 0
	global_load_lds_dwordx4 v[34:35], off
	v_lshl_add_u64 v[34:35], s[40:41], 0, v[146:147]
	s_add_i32 m0, s42, 0x2200
	s_nop 0
	global_load_lds_dwordx4 v[34:35], off
	v_lshl_add_u64 v[34:35], v[200:201], 0, s[6:7]
	s_mov_b32 m0, s29
	s_nop 0
	global_load_lds_dwordx4 v[34:35], off
	v_lshl_add_u64 v[34:35], v[208:209], 0, s[6:7]
	s_mov_b32 m0, s0
	s_nop 0
	global_load_lds_dwordx4 v[34:35], off
	s_add_i32 s71, s71, 2
	s_add_u32 s38, s38, 0x100
	s_addc_u32 s39, s39, 0
	s_add_u32 s23, s23, 0x100
	s_addc_u32 s70, s70, 0
	s_waitcnt vmcnt(8)
	s_waitcnt lgkmcnt(0)
	s_barrier
	s_setprio 1
	s_waitcnt lgkmcnt(0)
	v_mfma_f32_16x16x32_bf16 v[76:79], v[64:67], v[182:185], v[76:79]
	v_mfma_f32_16x16x32_bf16 v[72:75], v[158:161], v[182:185], v[72:75]
	v_mfma_f32_16x16x32_bf16 v[60:63], v[64:67], v[212:215], v[60:63]
	v_mfma_f32_16x16x32_bf16 v[56:59], v[158:161], v[212:215], v[56:59]
	v_mfma_f32_16x16x32_bf16 v[44:47], v[64:67], v[220:223], v[44:47]
	v_mfma_f32_16x16x32_bf16 v[40:43], v[158:161], v[220:223], v[40:43]
	v_mfma_f32_16x16x32_bf16 v[12:15], v[64:67], v[228:231], v[12:15]
	v_mfma_f32_16x16x32_bf16 v[8:11], v[158:161], v[228:231], v[8:11]
	v_mfma_f32_16x16x32_bf16 v[76:79], v[68:71], v[186:189], v[76:79]
	v_mfma_f32_16x16x32_bf16 v[72:75], v[162:165], v[186:189], v[72:75]
	v_mfma_f32_16x16x32_bf16 v[60:63], v[68:71], v[216:219], v[60:63]
	v_mfma_f32_16x16x32_bf16 v[56:59], v[162:165], v[216:219], v[56:59]
	v_mfma_f32_16x16x32_bf16 v[44:47], v[68:71], v[224:227], v[44:47]
	v_mfma_f32_16x16x32_bf16 v[40:43], v[162:165], v[224:227], v[40:43]
	v_mfma_f32_16x16x32_bf16 v[12:15], v[68:71], v[242:245], v[12:15]
	v_mfma_f32_16x16x32_bf16 v[8:11], v[162:165], v[242:245], v[8:11]
	s_setprio 0
	s_setprio 1
	v_mfma_f32_16x16x32_bf16 v[22:25], v[166:169], v[182:185], v[22:25]
	v_mfma_f32_16x16x32_bf16 v[68:71], v[170:173], v[186:189], v[22:25]
	v_mfma_f32_16x16x32_bf16 v[22:25], v[174:177], v[182:185], v[26:29]
	v_mfma_f32_16x16x32_bf16 v[64:67], v[178:181], v[186:189], v[22:25]
	v_mfma_f32_16x16x32_bf16 v[22:25], v[166:169], v[212:215], v[52:55]
	v_mfma_f32_16x16x32_bf16 v[52:55], v[170:173], v[216:219], v[22:25]
	v_mfma_f32_16x16x32_bf16 v[22:25], v[174:177], v[212:215], v[48:51]
	v_mfma_f32_16x16x32_bf16 v[48:51], v[178:181], v[216:219], v[22:25]
	v_mfma_f32_16x16x32_bf16 v[22:25], v[166:169], v[220:223], v[36:39]
	v_mfma_f32_16x16x32_bf16 v[36:39], v[170:173], v[224:227], v[22:25]
	v_mfma_f32_16x16x32_bf16 v[22:25], v[174:177], v[220:223], v[30:33]
	v_mfma_f32_16x16x32_bf16 v[4:7], v[166:169], v[228:231], v[4:7]
	v_mfma_f32_16x16x32_bf16 v[0:3], v[174:177], v[228:231], v[0:3]
	v_mfma_f32_16x16x32_bf16 v[32:35], v[178:181], v[224:227], v[22:25]
	v_mfma_f32_16x16x32_bf16 v[4:7], v[170:173], v[242:245], v[4:7]
	v_mfma_f32_16x16x32_bf16 v[0:3], v[178:181], v[242:245], v[0:3]
	s_setprio 0
	s_barrier
	s_cmp_gt_u32 s71, 13
	s_branch .LBB0_394
.LBB0_393:
	v_add_u32_e32 v30, 0x11000, v197
	s_add_i32 s73, 0, 0x11000
	s_add_i32 vcc_lo, 0, 0x15400
	ds_read_b128 v[22:25], v30
	ds_read_b128 v[26:29], v30 offset:64
	ds_read_b128 v[158:161], v30 offset:2176
	ds_read_b128 v[162:165], v30 offset:2240
	v_add_u32_e32 v30, vcc_lo, v197
	ds_read_b128 v[166:169], v30
	ds_read_b128 v[170:173], v30 offset:64
	ds_read_b128 v[174:177], v30 offset:2176
	ds_read_b128 v[178:181], v30 offset:2240
	v_lshl_add_u64 v[30:31], s[38:39], 0, v[154:155]
	s_add_i32 m0, s95, 0xcc00
	ds_read_b128 v[182:185], v210
	ds_read_b128 v[186:189], v210 offset:64
	ds_read_b128 v[212:215], v210 offset:2176
	ds_read_b128 v[216:219], v210 offset:2240
	ds_read_b128 v[220:223], v210 offset:4352
	ds_read_b128 v[224:227], v210 offset:4416
	ds_read_b128 v[228:231], v210 offset:6528
	ds_read_b128 v[242:245], v210 offset:6592
	global_load_lds_dwordx4 v[30:31], off
	v_lshl_add_u64 v[30:31], s[38:39], 0, v[156:157]
	s_add_i32 m0, s95, 0xee00
	s_nop 0
	global_load_lds_dwordx4 v[30:31], off
	s_add_u32 s42, s38, 0xfffc0080
	s_addc_u32 s43, s39, -1
	s_and_b64 s[40:41], s[40:41], exec
	s_cselect_b32 s43, s10, s43
	s_cselect_b32 s42, s44, s42
	s_cselect_b32 s41, s45, s70
	s_cselect_b32 s40, s69, s23
	s_waitcnt vmcnt(8)
	s_waitcnt lgkmcnt(0)
	s_barrier
; #define PG8_STAGE(bufoff, gbase, voff) do { _Pragma("unroll") for (int _i = 0; _i < 2; ++_i) \
;         __builtin_amdgcn_global_load_lds((const unsigned*)((const char*)(gbase) + (voff)[_i]), (PG8_LAS unsigned*)(lds + (bufoff) + ldsw + _i * (8 * USTR)), 16, 0, 0); } while (0)
; #define PG8_LDA(dst, b, h) do { _Pragma("unroll") for (int m = 0; m < 4; ++m) _Pragma("unroll") for (int k = 0; k < 2; ++k) dst[m][k] = *(const PG8_LAS bf16x8*)(lds + PG8_SA(b, h) + aoff + m * (2 * USTR) + k * 64); } while (0)
; #define PG8_MMA(ai, bj, At, Bt) do { __builtin_amdgcn_s_setprio(1); _Pragma("unroll") for (int m = 0; m < 4; ++m) _Pragma("unroll") for (int n = 0; n < 2; ++n) _Pragma("unroll") for (int k = 0; k < 2; ++k) \
;         acc[ai][bj][m][n] = __builtin_amdgcn_mfma_f32_16x16x32_bf16(Bt[n][k], At[m][k], acc[ai][bj][m][n], 0, 0, 0); __builtin_amdgcn_s_setprio(0); } while (0)
; #define PG8_WAIT_V(n) asm volatile("s_waitcnt vmcnt(" #n ")" ::: "memory")
; #define PG8_WAIT_L(n) asm volatile("s_waitcnt lgkmcnt(" #n ")" ::: "memory")
; #define PG8_BAR __builtin_amdgcn_s_barrier()
; #define PG8_SCHED __builtin_amdgcn_sched_barrier(0)
; template <class Epi, class Sched, bool ALIGN_EPI, bool SP2>
; __device__ __forceinline__ void gemm_phase(PG8_LAS unsigned char* lds, const Gemm g, const Sched& S, const Epi& E, int wid) {
;     ...
;             PG8_WAIT_V(8); PG8_WAIT_L(0); PG8_BAR; PG8_MMA(0, 0, At, B0); PG8_MMA(0, 1, At, B1); PG8_BAR; PG8_SCHED;
;             PG8_LDA(At, 0, 1); PG8_STAGE(PG8_SB(0, 0), b2, voffB); PG8_STAGE(PG8_SB(0, 1), b2 + hstepB, voffB); PG8_STAGE(PG8_SA(0, 0), a2, voffA);
;             PG8_WAIT_V(8); PG8_WAIT_L(0); PG8_BAR; PG8_MMA(1, 0, At, B0); PG8_MMA(1, 1, At, B1); PG8_BAR; PG8_SCHED;
	s_setprio 1
	s_waitcnt lgkmcnt(0)
	v_mfma_f32_16x16x32_bf16 v[140:143], v[22:25], v[182:185], v[140:143]
	v_mfma_f32_16x16x32_bf16 v[136:139], v[158:161], v[182:185], v[136:139]
	v_mfma_f32_16x16x32_bf16 v[124:127], v[22:25], v[212:215], v[124:127]
	v_mfma_f32_16x16x32_bf16 v[120:123], v[158:161], v[212:215], v[120:123]
	v_mfma_f32_16x16x32_bf16 v[108:111], v[22:25], v[220:223], v[108:111]
	v_mfma_f32_16x16x32_bf16 v[104:107], v[158:161], v[220:223], v[104:107]
	v_mfma_f32_16x16x32_bf16 v[92:95], v[22:25], v[228:231], v[92:95]
	v_mfma_f32_16x16x32_bf16 v[88:91], v[158:161], v[228:231], v[88:91]
	v_mfma_f32_16x16x32_bf16 v[140:143], v[26:29], v[186:189], v[140:143]
	v_mfma_f32_16x16x32_bf16 v[136:139], v[162:165], v[186:189], v[136:139]
	v_mfma_f32_16x16x32_bf16 v[124:127], v[26:29], v[216:219], v[124:127]
	v_mfma_f32_16x16x32_bf16 v[120:123], v[162:165], v[216:219], v[120:123]
	v_mfma_f32_16x16x32_bf16 v[108:111], v[26:29], v[224:227], v[108:111]
	v_mfma_f32_16x16x32_bf16 v[104:107], v[162:165], v[224:227], v[104:107]
	v_mfma_f32_16x16x32_bf16 v[92:95], v[26:29], v[242:245], v[92:95]
	v_mfma_f32_16x16x32_bf16 v[88:91], v[162:165], v[242:245], v[88:91]
	s_setprio 0
	s_setprio 1
	v_mfma_f32_16x16x32_bf16 v[132:135], v[166:169], v[182:185], v[132:135]
	v_mfma_f32_16x16x32_bf16 v[128:131], v[174:177], v[182:185], v[128:131]
	v_mfma_f32_16x16x32_bf16 v[116:119], v[166:169], v[212:215], v[116:119]
	v_mfma_f32_16x16x32_bf16 v[112:115], v[174:177], v[212:215], v[112:115]
	v_mfma_f32_16x16x32_bf16 v[100:103], v[166:169], v[220:223], v[100:103]
	v_mfma_f32_16x16x32_bf16 v[96:99], v[174:177], v[220:223], v[96:99]
	v_mfma_f32_16x16x32_bf16 v[84:87], v[166:169], v[228:231], v[84:87]
	v_mfma_f32_16x16x32_bf16 v[80:83], v[174:177], v[228:231], v[80:83]
	v_mfma_f32_16x16x32_bf16 v[132:135], v[170:173], v[186:189], v[132:135]
	v_mfma_f32_16x16x32_bf16 v[128:131], v[178:181], v[186:189], v[128:131]
	v_mfma_f32_16x16x32_bf16 v[116:119], v[170:173], v[216:219], v[116:119]
	v_mfma_f32_16x16x32_bf16 v[112:115], v[178:181], v[216:219], v[112:115]
	v_mfma_f32_16x16x32_bf16 v[100:103], v[170:173], v[224:227], v[100:103]
	v_mfma_f32_16x16x32_bf16 v[96:99], v[178:181], v[224:227], v[96:99]
	v_mfma_f32_16x16x32_bf16 v[84:87], v[170:173], v[242:245], v[84:87]
	v_mfma_f32_16x16x32_bf16 v[80:83], v[178:181], v[242:245], v[80:83]
	s_setprio 0
	s_barrier
	s_add_i32 s73, s73, s33
	v_lshl_add_u64 v[190:191], s[40:41], 0, v[192:193]
	s_mov_b32 m0, s73
	ds_read_b128 v[182:185], v210 offset:17408
	ds_read_b128 v[186:189], v210 offset:17472
	ds_read_b128 v[212:215], v210 offset:19584
	ds_read_b128 v[216:219], v210 offset:19648
	ds_read_b128 v[220:223], v210 offset:21760
	ds_read_b128 v[224:227], v210 offset:21824
	ds_read_b128 v[228:231], v210 offset:23936
	ds_read_b128 v[242:245], v210 offset:24000
	global_load_lds_dwordx4 v[190:191], off
	s_add_i32 m0, s73, 0x2200
	s_add_u32 s76, s40, 0x40000
	v_lshl_add_u64 v[198:199], s[40:41], 0, v[146:147]
	s_addc_u32 s77, s41, 0
	s_add_i32 s73, vcc_lo, s33
	global_load_lds_dwordx4 v[198:199], off
	v_lshl_add_u64 v[30:31], s[76:77], 0, v[192:193]
	s_mov_b32 m0, s73
	v_lshl_add_u64 v[200:201], s[42:43], 0, v[150:151]
	global_load_lds_dwordx4 v[30:31], off
	v_lshl_add_u64 v[30:31], s[76:77], 0, v[146:147]
	s_add_i32 m0, s73, 0x2200
	v_lshl_add_u64 v[208:209], s[42:43], 0, v[148:149]
	global_load_lds_dwordx4 v[30:31], off
	s_mov_b32 m0, s95
	s_nop 0
	global_load_lds_dwordx4 v[200:201], off
	s_mov_b32 m0, s5
	s_nop 0
	global_load_lds_dwordx4 v[208:209], off
	s_waitcnt vmcnt(8)
	s_waitcnt lgkmcnt(0)
	s_barrier
	s_setprio 1
	s_waitcnt lgkmcnt(0)
	v_mfma_f32_16x16x32_bf16 v[76:79], v[22:25], v[182:185], v[76:79]
	v_mfma_f32_16x16x32_bf16 v[72:75], v[158:161], v[182:185], v[72:75]
	v_mfma_f32_16x16x32_bf16 v[60:63], v[22:25], v[212:215], v[60:63]
	v_mfma_f32_16x16x32_bf16 v[56:59], v[158:161], v[212:215], v[56:59]
	v_mfma_f32_16x16x32_bf16 v[44:47], v[22:25], v[220:223], v[44:47]
	v_mfma_f32_16x16x32_bf16 v[40:43], v[158:161], v[220:223], v[40:43]
	v_mfma_f32_16x16x32_bf16 v[12:15], v[22:25], v[228:231], v[12:15]
	v_mfma_f32_16x16x32_bf16 v[8:11], v[158:161], v[228:231], v[8:11]
	v_mfma_f32_16x16x32_bf16 v[76:79], v[26:29], v[186:189], v[76:79]
	v_mfma_f32_16x16x32_bf16 v[72:75], v[162:165], v[186:189], v[72:75]
	v_mfma_f32_16x16x32_bf16 v[60:63], v[26:29], v[216:219], v[60:63]
	v_mfma_f32_16x16x32_bf16 v[56:59], v[162:165], v[216:219], v[56:59]
	v_mfma_f32_16x16x32_bf16 v[44:47], v[26:29], v[224:227], v[44:47]
	v_mfma_f32_16x16x32_bf16 v[40:43], v[162:165], v[224:227], v[40:43]
	v_mfma_f32_16x16x32_bf16 v[12:15], v[26:29], v[242:245], v[12:15]
	v_mfma_f32_16x16x32_bf16 v[8:11], v[162:165], v[242:245], v[8:11]
	s_setprio 0
	s_setprio 1
	v_mfma_f32_16x16x32_bf16 v[52:55], v[166:169], v[212:215], v[52:55]
	v_mfma_f32_16x16x32_bf16 v[48:51], v[174:177], v[212:215], v[48:51]
	v_mfma_f32_16x16x32_bf16 v[36:39], v[166:169], v[220:223], v[36:39]
	v_mfma_f32_16x16x32_bf16 v[30:33], v[174:177], v[220:223], v[32:35]
	v_mfma_f32_16x16x32_bf16 v[4:7], v[166:169], v[228:231], v[4:7]
	v_mfma_f32_16x16x32_bf16 v[0:3], v[174:177], v[228:231], v[0:3]
	v_mfma_f32_16x16x32_bf16 v[22:25], v[166:169], v[182:185], v[68:71]
	v_mfma_f32_16x16x32_bf16 v[26:29], v[174:177], v[182:185], v[64:67]
	v_mfma_f32_16x16x32_bf16 v[52:55], v[170:173], v[216:219], v[52:55]
	v_mfma_f32_16x16x32_bf16 v[48:51], v[178:181], v[216:219], v[48:51]
	v_mfma_f32_16x16x32_bf16 v[36:39], v[170:173], v[224:227], v[36:39]
	v_mfma_f32_16x16x32_bf16 v[30:33], v[178:181], v[224:227], v[30:33]
	v_mfma_f32_16x16x32_bf16 v[4:7], v[170:173], v[242:245], v[4:7]
	v_mfma_f32_16x16x32_bf16 v[0:3], v[178:181], v[242:245], v[0:3]
	v_mfma_f32_16x16x32_bf16 v[22:25], v[170:173], v[186:189], v[22:25]
	v_mfma_f32_16x16x32_bf16 v[26:29], v[178:181], v[186:189], v[26:29]
	s_setprio 0
	s_barrier
; #define PG8_STAGE(bufoff, gbase, voff) do { _Pragma("unroll") for (int _i = 0; _i < 2; ++_i) \
;         __builtin_amdgcn_global_load_lds((const unsigned*)((const char*)(gbase) + (voff)[_i]), (PG8_LAS unsigned*)(lds + (bufoff) + ldsw + _i * (8 * USTR)), 16, 0, 0); } while (0)
; #define PG8_LDA(dst, b, h) do { _Pragma("unroll") for (int m = 0; m < 4; ++m) _Pragma("unroll") for (int k = 0; k < 2; ++k) dst[m][k] = *(const PG8_LAS bf16x8*)(lds + PG8_SA(b, h) + aoff + m * (2 * USTR) + k * 64); } while (0)
; #define PG8_LDB(dst, b, h) do { _Pragma("unroll") for (int n = 0; n < 2; ++n) _Pragma("unroll") for (int k = 0; k < 2; ++k) dst[n][k] = *(const PG8_LAS bf16x8*)(lds + PG8_SB(b, h) + boff + n * (2 * USTR) + k * 64); } while (0)
; #define PG8_MMA(ai, bj, At, Bt) do { __builtin_amdgcn_s_setprio(1); _Pragma("unroll") for (int m = 0; m < 4; ++m) _Pragma("unroll") for (int n = 0; n < 2; ++n) _Pragma("unroll") for (int k = 0; k < 2; ++k) \
;         acc[ai][bj][m][n] = __builtin_amdgcn_mfma_f32_16x16x32_bf16(Bt[n][k], At[m][k], acc[ai][bj][m][n], 0, 0, 0); __builtin_amdgcn_s_setprio(0); } while (0)
; #define PG8_WAIT_V(n) asm volatile("s_waitcnt vmcnt(" #n ")" ::: "memory")
; #define PG8_WAIT_L(n) asm volatile("s_waitcnt lgkmcnt(" #n ")" ::: "memory")
; #define PG8_BAR __builtin_amdgcn_s_barrier()
; #define PG8_SCHED __builtin_amdgcn_sched_barrier(0)
; template <class Epi, class Sched, bool ALIGN_EPI, bool SP2>
; __device__ __forceinline__ void gemm_phase(PG8_LAS unsigned char* lds, const Gemm g, const Sched& S, const Epi& E, int wid) {
;     ...
;             PG8_WAIT_V(8); PG8_WAIT_L(0); PG8_BAR; PG8_MMA(1, 0, At, B0); PG8_MMA(1, 1, At, B1); PG8_BAR; PG8_SCHED;
;             PG8_LDB(B0, 1, 0); PG8_LDB(B1, 1, 1); PG8_SCHED; PG8_LDA(At, 1, 0); PG8_STAGE(PG8_SA(0, 1), a2 + hstepA, voffA);
;             PG8_WAIT_V(8); PG8_WAIT_L(0); PG8_BAR; PG8_MMA(0, 0, At, B0); PG8_MMA(0, 1, At, B1); PG8_BAR; PG8_SCHED;
	v_add_u32_e32 v34, 0x19800, v197
	ds_read_b128 v[64:67], v34
	ds_read_b128 v[68:71], v34 offset:64
	ds_read_b128 v[158:161], v34 offset:2176
	ds_read_b128 v[162:165], v34 offset:2240
	v_add_u32_e32 v34, 0x1dc00, v197
	ds_read_b128 v[166:169], v34
	ds_read_b128 v[170:173], v34 offset:64
	ds_read_b128 v[174:177], v34 offset:2176
	ds_read_b128 v[178:181], v34 offset:2240
	s_add_i32 s73, 0, 0x19800
	s_add_i32 s76, 0, 0x1dc00
	s_add_u32 s42, s42, 0x40000
	s_addc_u32 s43, s43, 0
	s_mov_b32 m0, s56
	v_lshl_add_u64 v[34:35], s[42:43], 0, v[150:151]
	ds_read_b128 v[182:185], v210 offset:34816
	ds_read_b128 v[186:189], v210 offset:34880
	ds_read_b128 v[212:215], v210 offset:36992
	ds_read_b128 v[216:219], v210 offset:37056
	ds_read_b128 v[220:223], v210 offset:39168
	ds_read_b128 v[224:227], v210 offset:39232
	ds_read_b128 v[228:231], v210 offset:41344
	ds_read_b128 v[242:245], v210 offset:41408
	global_load_lds_dwordx4 v[34:35], off
	v_lshl_add_u64 v[34:35], s[42:43], 0, v[148:149]
	s_mov_b32 m0, s57
	s_nop 0
	global_load_lds_dwordx4 v[34:35], off
	s_waitcnt vmcnt(8)
	s_waitcnt lgkmcnt(0)
	s_barrier
	s_setprio 1
	s_waitcnt lgkmcnt(0)
	v_mfma_f32_16x16x32_bf16 v[140:143], v[64:67], v[182:185], v[140:143]
	v_mfma_f32_16x16x32_bf16 v[136:139], v[158:161], v[182:185], v[136:139]
	v_mfma_f32_16x16x32_bf16 v[124:127], v[64:67], v[212:215], v[124:127]
	v_mfma_f32_16x16x32_bf16 v[120:123], v[158:161], v[212:215], v[120:123]
	v_mfma_f32_16x16x32_bf16 v[108:111], v[64:67], v[220:223], v[108:111]
	v_mfma_f32_16x16x32_bf16 v[104:107], v[158:161], v[220:223], v[104:107]
	v_mfma_f32_16x16x32_bf16 v[92:95], v[64:67], v[228:231], v[92:95]
	v_mfma_f32_16x16x32_bf16 v[88:91], v[158:161], v[228:231], v[88:91]
	v_mfma_f32_16x16x32_bf16 v[140:143], v[68:71], v[186:189], v[140:143]
	v_mfma_f32_16x16x32_bf16 v[136:139], v[162:165], v[186:189], v[136:139]
	v_mfma_f32_16x16x32_bf16 v[124:127], v[68:71], v[216:219], v[124:127]
	v_mfma_f32_16x16x32_bf16 v[120:123], v[162:165], v[216:219], v[120:123]
	v_mfma_f32_16x16x32_bf16 v[108:111], v[68:71], v[224:227], v[108:111]
	v_mfma_f32_16x16x32_bf16 v[104:107], v[162:165], v[224:227], v[104:107]
	v_mfma_f32_16x16x32_bf16 v[92:95], v[68:71], v[242:245], v[92:95]
	v_mfma_f32_16x16x32_bf16 v[88:91], v[162:165], v[242:245], v[88:91]
	s_setprio 0
	s_setprio 1
	v_mfma_f32_16x16x32_bf16 v[132:135], v[166:169], v[182:185], v[132:135]
	v_mfma_f32_16x16x32_bf16 v[128:131], v[174:177], v[182:185], v[128:131]
	v_mfma_f32_16x16x32_bf16 v[116:119], v[166:169], v[212:215], v[116:119]
	v_mfma_f32_16x16x32_bf16 v[112:115], v[174:177], v[212:215], v[112:115]
	v_mfma_f32_16x16x32_bf16 v[100:103], v[166:169], v[220:223], v[100:103]
	v_mfma_f32_16x16x32_bf16 v[96:99], v[174:177], v[220:223], v[96:99]
	v_mfma_f32_16x16x32_bf16 v[84:87], v[166:169], v[228:231], v[84:87]
	v_mfma_f32_16x16x32_bf16 v[80:83], v[174:177], v[228:231], v[80:83]
	v_mfma_f32_16x16x32_bf16 v[132:135], v[170:173], v[186:189], v[132:135]
	v_mfma_f32_16x16x32_bf16 v[128:131], v[178:181], v[186:189], v[128:131]
	v_mfma_f32_16x16x32_bf16 v[116:119], v[170:173], v[216:219], v[116:119]
	v_mfma_f32_16x16x32_bf16 v[112:115], v[178:181], v[216:219], v[112:115]
	v_mfma_f32_16x16x32_bf16 v[100:103], v[170:173], v[224:227], v[100:103]
	v_mfma_f32_16x16x32_bf16 v[96:99], v[178:181], v[224:227], v[96:99]
	v_mfma_f32_16x16x32_bf16 v[84:87], v[170:173], v[242:245], v[84:87]
	v_mfma_f32_16x16x32_bf16 v[80:83], v[178:181], v[242:245], v[80:83]
	s_setprio 0
	s_barrier
; #define PG8_STAGE(bufoff, gbase, voff) do { _Pragma("unroll") for (int _i = 0; _i < 2; ++_i) \
;         __builtin_amdgcn_global_load_lds((const unsigned*)((const char*)(gbase) + (voff)[_i]), (PG8_LAS unsigned*)(lds + (bufoff) + ldsw + _i * (8 * USTR)), 16, 0, 0); } while (0)
; #define PG8_LDA(dst, b, h) do { _Pragma("unroll") for (int m = 0; m < 4; ++m) _Pragma("unroll") for (int k = 0; k < 2; ++k) dst[m][k] = *(const PG8_LAS bf16x8*)(lds + PG8_SA(b, h) + aoff + m * (2 * USTR) + k * 64); } while (0)
; #define PG8_MMA(ai, bj, At, Bt) do { __builtin_amdgcn_s_setprio(1); _Pragma("unroll") for (int m = 0; m < 4; ++m) _Pragma("unroll") for (int n = 0; n < 2; ++n) _Pragma("unroll") for (int k = 0; k < 2; ++k) \
;         acc[ai][bj][m][n] = __builtin_amdgcn_mfma_f32_16x16x32_bf16(Bt[n][k], At[m][k], acc[ai][bj][m][n], 0, 0, 0); __builtin_amdgcn_s_setprio(0); } while (0)
; #define PG8_WAIT_V(n) asm volatile("s_waitcnt vmcnt(" #n ")" ::: "memory")
; #define PG8_WAIT_L(n) asm volatile("s_waitcnt lgkmcnt(" #n ")" ::: "memory")
; #define PG8_BAR __builtin_amdgcn_s_barrier()
; #define PG8_SCHED __builtin_amdgcn_sched_barrier(0)
; template <class Epi, class Sched, bool ALIGN_EPI, bool SP2>
; __device__ __forceinline__ void gemm_phase(PG8_LAS unsigned char* lds, const Gemm g, const Sched& S, const Epi& E, int wid) {
;     ...
;         for (int t = 0; t < nt; t += 2) {
;     ...
;             PG8_LDA(At, 1, 1); PG8_STAGE(PG8_SB(1, 0), b3, voffB); PG8_STAGE(PG8_SB(1, 1), b3 + hstepB, voffB); PG8_STAGE(PG8_SA(1, 0), a3, voffA);
;             PG8_WAIT_V(8); PG8_WAIT_L(0); PG8_BAR; PG8_MMA(1, 0, At, B0); PG8_MMA(1, 1, At, B1); PG8_BAR; PG8_SCHED;
	s_add_i32 s42, s73, s33
	v_lshl_add_u64 v[34:35], v[190:191], 0, s[6:7]
	s_mov_b32 m0, s42
	ds_read_b128 v[182:185], v210 offset:52224
	ds_read_b128 v[186:189], v210 offset:52288
	ds_read_b128 v[212:215], v210 offset:54400
	ds_read_b128 v[216:219], v210 offset:54464
	ds_read_b128 v[220:223], v210 offset:56576
	ds_read_b128 v[224:227], v210 offset:56640
	ds_read_b128 v[228:231], v210 offset:58752
	ds_read_b128 v[242:245], v210 offset:58816
	global_load_lds_dwordx4 v[34:35], off
	s_add_i32 m0, s42, 0x2200
	s_add_u32 s40, s40, 0x40080
	v_lshl_add_u64 v[34:35], v[198:199], 0, s[6:7]
	s_addc_u32 s41, s41, 0
	s_add_i32 s42, s76, s33
	global_load_lds_dwordx4 v[34:35], off
	v_lshl_add_u64 v[34:35], s[40:41], 0, v[192:193]
	s_mov_b32 m0, s42
	s_nop 0
	global_load_lds_dwordx4 v[34:35], off
	v_lshl_add_u64 v[34:35], s[40:41], 0, v[146:147]
	s_add_i32 m0, s42, 0x2200
	s_nop 0
	global_load_lds_dwordx4 v[34:35], off
	v_lshl_add_u64 v[34:35], v[200:201], 0, s[6:7]
	s_mov_b32 m0, s29
	s_nop 0
	global_load_lds_dwordx4 v[34:35], off
	v_lshl_add_u64 v[34:35], v[208:209], 0, s[6:7]
	s_mov_b32 m0, s0
	s_nop 0
	global_load_lds_dwordx4 v[34:35], off
	s_add_i32 s71, s71, 2
	s_add_u32 s38, s38, 0x100
	s_addc_u32 s39, s39, 0
	s_add_u32 s23, s23, 0x100
	s_addc_u32 s70, s70, 0
	s_waitcnt vmcnt(8)
	s_waitcnt lgkmcnt(0)
	s_barrier
	s_setprio 1
	s_waitcnt lgkmcnt(0)
	v_mfma_f32_16x16x32_bf16 v[76:79], v[64:67], v[182:185], v[76:79]
	v_mfma_f32_16x16x32_bf16 v[72:75], v[158:161], v[182:185], v[72:75]
	v_mfma_f32_16x16x32_bf16 v[60:63], v[64:67], v[212:215], v[60:63]
	v_mfma_f32_16x16x32_bf16 v[56:59], v[158:161], v[212:215], v[56:59]
	v_mfma_f32_16x16x32_bf16 v[44:47], v[64:67], v[220:223], v[44:47]
	v_mfma_f32_16x16x32_bf16 v[40:43], v[158:161], v[220:223], v[40:43]
	v_mfma_f32_16x16x32_bf16 v[12:15], v[64:67], v[228:231], v[12:15]
	v_mfma_f32_16x16x32_bf16 v[8:11], v[158:161], v[228:231], v[8:11]
	v_mfma_f32_16x16x32_bf16 v[76:79], v[68:71], v[186:189], v[76:79]
	v_mfma_f32_16x16x32_bf16 v[72:75], v[162:165], v[186:189], v[72:75]
	v_mfma_f32_16x16x32_bf16 v[60:63], v[68:71], v[216:219], v[60:63]
	v_mfma_f32_16x16x32_bf16 v[56:59], v[162:165], v[216:219], v[56:59]
	v_mfma_f32_16x16x32_bf16 v[44:47], v[68:71], v[224:227], v[44:47]
	v_mfma_f32_16x16x32_bf16 v[40:43], v[162:165], v[224:227], v[40:43]
	v_mfma_f32_16x16x32_bf16 v[12:15], v[68:71], v[242:245], v[12:15]
	v_mfma_f32_16x16x32_bf16 v[8:11], v[162:165], v[242:245], v[8:11]
	s_setprio 0
	s_setprio 1
	v_mfma_f32_16x16x32_bf16 v[22:25], v[166:169], v[182:185], v[22:25]
	v_mfma_f32_16x16x32_bf16 v[68:71], v[170:173], v[186:189], v[22:25]
	v_mfma_f32_16x16x32_bf16 v[22:25], v[174:177], v[182:185], v[26:29]
	v_mfma_f32_16x16x32_bf16 v[64:67], v[178:181], v[186:189], v[22:25]
	v_mfma_f32_16x16x32_bf16 v[22:25], v[166:169], v[212:215], v[52:55]
	v_mfma_f32_16x16x32_bf16 v[52:55], v[170:173], v[216:219], v[22:25]
	v_mfma_f32_16x16x32_bf16 v[22:25], v[174:177], v[212:215], v[48:51]
	v_mfma_f32_16x16x32_bf16 v[48:51], v[178:181], v[216:219], v[22:25]
	v_mfma_f32_16x16x32_bf16 v[22:25], v[166:169], v[220:223], v[36:39]
	v_mfma_f32_16x16x32_bf16 v[36:39], v[170:173], v[224:227], v[22:25]
	v_mfma_f32_16x16x32_bf16 v[22:25], v[174:177], v[220:223], v[30:33]
	v_mfma_f32_16x16x32_bf16 v[4:7], v[166:169], v[228:231], v[4:7]
	v_mfma_f32_16x16x32_bf16 v[0:3], v[174:177], v[228:231], v[0:3]
	v_mfma_f32_16x16x32_bf16 v[32:35], v[178:181], v[224:227], v[22:25]
	v_mfma_f32_16x16x32_bf16 v[4:7], v[170:173], v[242:245], v[4:7]
	v_mfma_f32_16x16x32_bf16 v[0:3], v[178:181], v[242:245], v[0:3]
	s_setprio 0
	s_barrier
	s_cmp_gt_u32 s71, 13
	s_cbranch_scc1 .LBB0_397
